# adds: residual stream X (fp16) stored in 16-row x 32-col contiguous blocks so every OUT/DOWN epilogue load/store instruction is one 1 KiB access; FINAL reads remapped
# speedup vs baseline: 1.0142x; 1.0105x over previous
;     template <bool INF32, int M0, int M1> __device__ __forceinline__ void half(f32x4 (&acc)[2][2][4][2], int ai, int b, int row0, int col, int pn, int wc, int fr, int fq) const {
;     ...
;             for (int m = M0; m < M1; ++m)
; #pragma unroll
;                 for (int bj = 0; bj < 2; ++bj) hh[m][bj] = *(const f16x8_t*)((const bf16_t*)xin + (size_t)(row0 + ai * 128 + m * 16) * D + col + bj * 128);
; #pragma unroll
;             for (int m = M0; m < M1; ++m)
; #pragma unroll
;                 for (int bj = 0; bj < 2; ++bj) { const f32x8_t ff = __builtin_convertvector(hh[m][bj], f32x8_t); xv[m][bj][0] = (f32x4){ff[0], ff[1], ff[2], ff[3]}; xv[m][bj][1] = (f32x4){ff[4], ff[5], ff[6], ff[7]}; }
;         }
;         f32x4 gt[2][2], gs[2][2];
; #pragma unroll
;         for (int bj = 0; bj < 2; ++bj)
; #pragma unroll
;             for (int n = 0; n < 2; ++n) { gt[bj][n] = *(const f32x4*)(gate + (size_t)b * 6 * D + col + bj * 128 + n * 4); gs[bj][n] = XS ? *(const f32x4*)(GS + (size_t)b * D + col + bj * 128 + n * 4) : (f32x4){0.f, 0.f, 0.f, 0.f}; }
;         __builtin_amdgcn_sched_barrier(0);
; #pragma unroll
;         for (int m = M0; m < M1; ++m) { const int row = row0 + ai * 128 + m * 16; float ss = 0.f;
; #pragma unroll
;             for (int bj = 0; bj < 2; ++bj) { const size_t o = (size_t)row * D + col + bj * 128;
;                 const f32x4 x0 = xv[m][bj][0] + gt[bj][0] * acc[ai][bj][m][0], x1 = xv[m][bj][1] + gt[bj][1] * acc[ai][bj][m][1];
;                 if (out_f32) { *(f32x4*)((float*)xout + o) = x0; *(f32x4*)((float*)xout + o + 4) = x1; }
;                 else { const f32x8_t ff = {x0.x, x0.y, x0.z, x0.w, x1.x, x1.y, x1.z, x1.w}; *(f16x8_t*)((bf16_t*)xout + o) = __builtin_convertvector(ff, f16x8_t); }
;                 ss += ((x0.x * x0.x + x0.y * x0.y) + (x0.z * x0.z + x0.w * x0.w)) + ((x1.x * x1.x + x1.y * x1.y) + (x1.z * x1.z + x1.w * x1.w));
;                 if (XS) *(u32x4*)(XS + xs_off(row0, col) + (ai * 128 + m * 16) * 64 + bj * (2 * 256 * 64)) = pack8(x0 * gs[bj][0], x1 * gs[bj][1]); }
;             { const int ln = fr + 16 * fq; ss += bperm(ss, ln ^ 16); ss += bperm(ss, ln ^ 32); }
;             if (fq == 0) RSS[(size_t)row * 32 + pn * 4 + wc] = ss; }
;     }
;     __device__ __forceinline__ void operator()(f32x4 (&acc)[2][2][4][2], const pg8::Unit& u, int ui, int wr, int wc, int fr, int fq) const {
.LBB0_1131:
	s_mul_i32 s100, s30, 0x1e00
	s_mul_i32 s101, s81, 62
	s_add_u32 s100, s100, s101
	s_mov_b32 s101, 0
	v_mbcnt_lo_u32_b32 v247, -1, 0
	v_mbcnt_hi_u32_b32 v247, -1, v247
	s_lshl_b32 s31, s28, 8
	v_ashrrev_i32_e32 v130, 4, v247
	v_and_b32_e32 v0, 15, v247
	s_add_i32 s31, s31, s80
	v_lshl_add_u32 v131, v130, 3, s81
	v_or_b32_e32 v200, s31, v0
	v_lshl_add_u32 v198, s30, 8, v131
	s_ashr_i32 s36, s28, 4
	v_ashrrev_i32_e32 v199, 31, v198
	v_or_b32_e32 v206, 16, v200
	v_or_b32_e32 v204, 32, v200
	v_or_b32_e32 v202, 48, v200
	v_lshlrev_b32_e32 v132, 6, v200
	v_and_b32_e32 v131, 56, v131
	v_lshlrev_b32_e32 v130, 6, v130
	v_lshlrev_b32_e32 v0, 2, v0
	s_movk_i32 s12, 0x33c0
	s_and_b64 vcc, exec, s[94:95]
	v_ashrrev_i32_e32 v201, 31, v200
	s_mul_hi_i32 s65, s36, 0xc000
	s_mul_i32 s66, s36, 0xc000
	v_lshlrev_b64 v[146:147], 2, v[198:199]
	v_cmp_gt_u32_e64 s[28:29], 16, v247
	v_ashrrev_i32_e32 v207, 31, v206
	v_ashrrev_i32_e32 v205, 31, v204
	v_ashrrev_i32_e32 v203, 31, v202
	v_ashrrev_i32_e32 v208, 6, v198
	v_and_or_b32 v246, v132, s12, v131
	v_bitop3_b32 v245, v130, 64, v0 bitop3:0x36
	v_bitop3_b32 v244, v130, s84, v0 bitop3:0x36
	s_cbranch_vccz .LBB0_1149
	v_lshlrev_b64 v[212:213], 1, v[198:199]
	v_lshl_add_u64 v[212:213], v[212:213], 0, s[100:101]
	v_lshl_add_u64 v[220:221], s[10:11], 0, v[212:213]
	v_lshlrev_b64 v[214:215], 12, v[200:201]
	v_bfe_u32 v215, v214, 12, 4
	v_lshl_add_u32 v214, v215, 6, v214
	v_lshlrev_b32_e32 v215, 12, v215
	v_sub_u32_e32 v214, v214, v215
	v_mov_b32_e32 v215, 0
	v_lshl_add_u64 v[134:135], v[220:221], 0, v[214:215]
	global_load_dwordx4 v[130:133], v[134:135], off
	s_nop 0
	global_load_dwordx4 v[134:137], v[134:135], off offset:1024
	s_ashr_i32 s37, s36, 31
	s_add_u32 s34, s63, s66
	v_lshlrev_b64 v[228:229], 12, v[206:207]
	v_bfe_u32 v229, v228, 12, 4
	v_lshl_add_u32 v228, v229, 6, v228
	v_lshlrev_b32_e32 v229, 12, v229
	v_sub_u32_e32 v228, v228, v229
	v_mov_b32_e32 v229, 0
	s_addc_u32 s35, s67, s65
	v_lshl_add_u64 v[138:139], v[220:221], 0, v[228:229]
	v_lshlrev_b64 v[226:227], 12, v[204:205]
	v_bfe_u32 v227, v226, 12, 4
	v_lshl_add_u32 v226, v227, 6, v226
	v_lshlrev_b32_e32 v227, 12, v227
	v_sub_u32_e32 v226, v226, v227
	v_mov_b32_e32 v227, 0
	v_lshl_add_u64 v[222:223], s[34:35], 0, v[146:147]
	s_lshl_b64 s[34:35], s[36:37], 13
	global_load_dwordx4 v[182:185], v[138:139], off
	global_load_dwordx4 v[178:181], v[138:139], off offset:1024
	v_lshl_add_u64 v[138:139], v[220:221], 0, v[226:227]
	v_lshlrev_b64 v[218:219], 12, v[202:203]
	v_bfe_u32 v219, v218, 12, 4
	v_lshl_add_u32 v218, v219, 6, v218
	v_lshlrev_b32_e32 v219, 12, v219
	v_sub_u32_e32 v218, v218, v219
	v_mov_b32_e32 v219, 0
	s_add_u32 s34, s68, s34
	global_load_dwordx4 v[174:177], v[138:139], off
	global_load_dwordx4 v[170:173], v[138:139], off offset:1024
	v_lshl_add_u64 v[138:139], v[220:221], 0, v[218:219]
	s_addc_u32 s35, s70, s35
	global_load_dwordx4 v[142:145], v[138:139], off
	s_nop 0
	global_load_dwordx4 v[138:141], v[138:139], off offset:1024
	v_lshl_add_u64 v[224:225], s[34:35], 0, v[146:147]
	s_waitcnt vmcnt(0)
	v_cvt_f32_f16_e32 v216, v132
	v_cvt_f32_f16_sdwa v217, v132 dst_sel:DWORD dst_unused:UNUSED_PAD src0_sel:WORD_1
	v_cvt_f32_f16_e32 v234, v133
	v_cvt_f32_f16_sdwa v235, v133 dst_sel:DWORD dst_unused:UNUSED_PAD src0_sel:WORD_1
	v_cvt_f32_f16_e32 v236, v130
	v_cvt_f32_f16_sdwa v237, v130 dst_sel:DWORD dst_unused:UNUSED_PAD src0_sel:WORD_1
	v_cvt_f32_f16_e32 v248, v131
	v_cvt_f32_f16_sdwa v249, v131 dst_sel:DWORD dst_unused:UNUSED_PAD src0_sel:WORD_1
	v_cvt_f32_f16_e32 v230, v136
	v_cvt_f32_f16_sdwa v231, v136 dst_sel:DWORD dst_unused:UNUSED_PAD src0_sel:WORD_1
	v_cvt_f32_f16_e32 v232, v137
	v_cvt_f32_f16_sdwa v233, v137 dst_sel:DWORD dst_unused:UNUSED_PAD src0_sel:WORD_1
	v_cvt_f32_f16_e32 v250, v134
	v_cvt_f32_f16_sdwa v251, v134 dst_sel:DWORD dst_unused:UNUSED_PAD src0_sel:WORD_1
	v_cvt_f32_f16_e32 v252, v135
	v_cvt_f32_f16_sdwa v253, v135 dst_sel:DWORD dst_unused:UNUSED_PAD src0_sel:WORD_1
	global_load_dwordx4 v[162:165], v[222:223], off offset:16
	global_load_dwordx4 v[166:169], v[222:223], off
	global_load_dwordx4 v[154:157], v[224:225], off offset:16
	global_load_dwordx4 v[158:161], v[224:225], off
	global_load_dwordx4 v[146:149], v[222:223], off offset:528
	global_load_dwordx4 v[150:153], v[222:223], off offset:512
	global_load_dwordx4 v[130:133], v[224:225], off offset:528
	global_load_dwordx4 v[134:137], v[224:225], off offset:512
	v_ashrrev_i32_e32 v209, 31, v208
	s_waitcnt vmcnt(6)
	v_pk_fma_f32 v[248:249], v[128:129], v[168:169], v[248:249]
	v_pk_fma_f32 v[240:241], v[126:127], v[166:167], v[236:237]
	v_lshlrev_b64 v[238:239], 15, v[208:209]
	v_mul_f32_e32 v0, v241, v241
	v_mul_f32_e32 v209, v249, v249
	v_pk_fma_f32 v[210:211], v[124:125], v[164:165], v[234:235]
	v_pk_fma_f32 v[216:217], v[122:123], v[162:163], v[216:217]
	v_lshl_add_u64 v[214:215], s[10:11], 0, v[214:215]
	v_fmac_f32_e32 v0, v240, v240
	v_fmac_f32_e32 v209, v248, v248
	s_ashr_i32 s34, s31, 8
	v_cvt_pk_f16_f32 v237, v210, v211
	v_cvt_pk_f16_f32 v235, v248, v249
	v_cvt_pk_f16_f32 v236, v216, v217
	v_cvt_pk_f16_f32 v234, v240, v241
	v_lshl_add_u64 v[212:213], v[214:215], 0, v[212:213]
	v_add_f32_e32 v0, v0, v209
	v_mul_f32_e32 v209, v217, v217
	v_mul_f32_e32 v214, v211, v211
	s_ashr_i32 s35, s34, 31
	global_store_dwordx4 v[212:213], v[234:237], off
	v_fmac_f32_e32 v209, v216, v216
	v_fmac_f32_e32 v214, v210, v210
	s_waitcnt vmcnt(5)
; __device__ __forceinline__ float bperm(float v, int src_lane) { return __int_as_float(__builtin_amdgcn_ds_bpermute(src_lane << 2, __float_as_int(v))); }
; __device__ __forceinline__ u32x4 pack8(const f32x4 a, const f32x4 b) { u32x4 w; w.x = cvt_pk_bf16(a.x, a.y); w.y = cvt_pk_bf16(a.z, a.w); w.z = cvt_pk_bf16(b.x, b.y); w.w = cvt_pk_bf16(b.z, b.w); return w; }
; __host__ __device__ __forceinline__ size_t xs_off(int row, int col) { return (size_t)(row >> 8) * (256 * D) + (size_t)(col >> 6) * (256 * 64) + (size_t)((row & 255) * 64 + (col & 63)); }
;     template <bool INF32, int M0, int M1> __device__ __forceinline__ void half(f32x4 (&acc)[2][2][4][2], int ai, int b, int row0, int col, int pn, int wc, int fr, int fq) const {
;     ...
;         for (int m = M0; m < M1; ++m) { const int row = row0 + ai * 128 + m * 16; float ss = 0.f;
; #pragma unroll
;             for (int bj = 0; bj < 2; ++bj) { const size_t o = (size_t)row * D + col + bj * 128;
;                 const f32x4 x0 = xv[m][bj][0] + gt[bj][0] * acc[ai][bj][m][0], x1 = xv[m][bj][1] + gt[bj][1] * acc[ai][bj][m][1];
;                 if (out_f32) { *(f32x4*)((float*)xout + o) = x0; *(f32x4*)((float*)xout + o + 4) = x1; }
;                 else { const f32x8_t ff = {x0.x, x0.y, x0.z, x0.w, x1.x, x1.y, x1.z, x1.w}; *(f16x8_t*)((bf16_t*)xout + o) = __builtin_convertvector(ff, f16x8_t); }
;                 ss += ((x0.x * x0.x + x0.y * x0.y) + (x0.z * x0.z + x0.w * x0.w)) + ((x1.x * x1.x + x1.y * x1.y) + (x1.z * x1.z + x1.w * x1.w));
;                 if (XS) *(u32x4*)(XS + xs_off(row0, col) + (ai * 128 + m * 16) * 64 + bj * (2 * 256 * 64)) = pack8(x0 * gs[bj][0], x1 * gs[bj][1]); }
;             { const int ln = fr + 16 * fq; ss += bperm(ss, ln ^ 16); ss += bperm(ss, ln ^ 32); }
;             if (fq == 0) RSS[(size_t)row * 32 + pn * 4 + wc] = ss; }
	v_pk_mul_f32 v[234:235], v[158:159], v[240:241]
	v_pk_mul_f32 v[210:211], v[156:157], v[210:211]
	s_lshl_b64 s[46:47], s[34:35], 20
	v_add_f32_e32 v209, v209, v214
	v_pk_mul_f32 v[214:215], v[160:161], v[248:249]
	v_pk_mul_f32 v[216:217], v[154:155], v[216:217]
	v_cvt_pk_bf16_f32 v234, v234, v235
	v_cvt_pk_bf16_f32 v235, v214, v215
	v_add_f32_e32 v209, v0, v209
	v_cvt_pk_bf16_f32 v236, v216, v217
	v_cvt_pk_bf16_f32 v237, v210, v211
	v_lshl_add_u64 v[210:211], s[74:75], 0, v[238:239]
	v_lshl_add_u64 v[210:211], v[210:211], 0, s[46:47]
	v_lshlrev_b32_e32 v0, 1, v246
	v_lshl_add_u64 v[216:217], v[210:211], 0, v[0:1]
	global_store_dwordx4 v[216:217], v[234:237], off
	s_waitcnt vmcnt(4)
	v_pk_fma_f32 v[210:211], v[120:121], v[152:153], v[252:253]
	v_pk_fma_f32 v[214:215], v[118:119], v[150:151], v[250:251]
	v_pk_fma_f32 v[234:235], v[116:117], v[148:149], v[232:233]
	v_pk_fma_f32 v[236:237], v[114:115], v[146:147], v[230:231]
	v_cvt_pk_f16_f32 v233, v234, v235
	v_cvt_pk_f16_f32 v231, v210, v211
	v_cvt_pk_f16_f32 v232, v236, v237
	v_cvt_pk_f16_f32 v230, v214, v215
	global_store_dwordx4 v[212:213], v[230:233], off offset:1024
	v_mul_f32_e32 v0, v215, v215
	v_mul_f32_e32 v212, v211, v211
	v_fmac_f32_e32 v0, v214, v214
	v_fmac_f32_e32 v212, v210, v210
	v_add_f32_e32 v0, v0, v212
	v_mul_f32_e32 v212, v237, v237
	v_mul_f32_e32 v213, v235, v235
	v_fmac_f32_e32 v212, v236, v236
	v_fmac_f32_e32 v213, v234, v234
	v_add_f32_e32 v212, v212, v213
	v_add_f32_e32 v0, v0, v212
	v_add_f32_e32 v0, v209, v0
	ds_bpermute_b32 v209, v245, v0
	s_waitcnt vmcnt(3)
	v_pk_mul_f32 v[210:211], v[136:137], v[210:211]
	s_lshl_b32 s34, s30, 2
	v_pk_mul_f32 v[212:213], v[134:135], v[214:215]
	s_ashr_i32 s35, s34, 31
	s_waitcnt lgkmcnt(0)
	v_add_f32_e32 v0, v0, v209
	ds_bpermute_b32 v209, v244, v0
	v_cvt_pk_bf16_f32 v230, v212, v213
	v_cvt_pk_bf16_f32 v231, v210, v211
	v_add_co_u32_e32 v210, vcc, 0x10000, v216
	v_pk_mul_f32 v[232:233], v[130:131], v[236:237]
	s_nop 0
	v_addc_co_u32_e32 v211, vcc, 0, v217, vcc
	v_pk_mul_f32 v[214:215], v[132:133], v[234:235]
	v_cvt_pk_bf16_f32 v232, v232, v233
	s_nop 0
	v_cvt_pk_bf16_f32 v233, v214, v215
	global_store_dwordx4 v[210:211], v[230:233], off
	s_and_saveexec_b64 s[46:47], s[28:29]
	s_cbranch_execz .LBB0_1134
	v_lshlrev_b64 v[210:211], 7, v[200:201]
	v_lshl_add_u64 v[210:211], s[42:43], 0, v[210:211]
	v_lshl_add_u64 v[210:211], s[34:35], 2, v[210:211]
	s_lshl_b32 s44, s71, 2
	v_lshl_add_u64 v[210:211], v[210:211], 0, s[44:45]
	s_waitcnt lgkmcnt(0)
	v_add_f32_e32 v0, v0, v209
	global_store_dword v[210:211], v0, off
.LBB0_1134:
	s_or_b64 exec, exec, s[46:47]
	v_cvt_f32_f16_sdwa v211, v184 dst_sel:DWORD dst_unused:UNUSED_PAD src0_sel:WORD_1
	v_cvt_f32_f16_sdwa v213, v185 dst_sel:DWORD dst_unused:UNUSED_PAD src0_sel:WORD_1
	v_cvt_f32_f16_sdwa v215, v182 dst_sel:DWORD dst_unused:UNUSED_PAD src0_sel:WORD_1
	v_cvt_f32_f16_sdwa v231, v183 dst_sel:DWORD dst_unused:UNUSED_PAD src0_sel:WORD_1
	v_cvt_f32_f16_e32 v210, v184
	v_cvt_f32_f16_e32 v212, v185
	v_cvt_f32_f16_e32 v214, v182
	v_cvt_f32_f16_e32 v230, v183
	v_pk_fma_f32 v[210:211], v[106:107], v[162:163], v[210:211]
	v_pk_fma_f32 v[212:213], v[108:109], v[164:165], v[212:213]
	v_pk_fma_f32 v[214:215], v[110:111], v[166:167], v[214:215]
	v_pk_fma_f32 v[230:231], v[112:113], v[168:169], v[230:231]
	v_lshl_add_u64 v[228:229], s[10:11], 0, v[228:229]
	v_cvt_f32_f16_sdwa v183, v180 dst_sel:DWORD dst_unused:UNUSED_PAD src0_sel:WORD_1
	v_cvt_f32_f16_sdwa v185, v181 dst_sel:DWORD dst_unused:UNUSED_PAD src0_sel:WORD_1
	v_cvt_f32_f16_sdwa v233, v178 dst_sel:DWORD dst_unused:UNUSED_PAD src0_sel:WORD_1
	v_cvt_f32_f16_sdwa v235, v179 dst_sel:DWORD dst_unused:UNUSED_PAD src0_sel:WORD_1
	v_cvt_f32_f16_e32 v182, v180
	v_cvt_f32_f16_e32 v184, v181
	v_cvt_f32_f16_e32 v232, v178
	v_cvt_f32_f16_e32 v234, v179
	v_cvt_pk_f16_f32 v181, v212, v213
	v_cvt_pk_f16_f32 v179, v230, v231
	v_cvt_pk_f16_f32 v180, v210, v211
	v_cvt_pk_f16_f32 v178, v214, v215
	v_lshl_add_u64 v[228:229], v[198:199], 1, v[228:229]
	v_lshl_add_u64 v[228:229], v[228:229], 0, s[100:101]
	global_store_dwordx4 v[228:229], v[178:181], off
	v_mul_f32_e32 v0, v215, v215
	v_fmac_f32_e32 v0, v214, v214
	v_mul_f32_e32 v178, v231, v231
	v_fmac_f32_e32 v178, v230, v230
	v_add_f32_e32 v0, v0, v178
	v_mul_f32_e32 v178, v211, v211
	v_mul_f32_e32 v179, v213, v213
	v_fmac_f32_e32 v178, v210, v210
	v_fmac_f32_e32 v179, v212, v212
	v_add_f32_e32 v178, v178, v179
	v_add_f32_e32 v0, v0, v178
	v_pk_mul_f32 v[180:181], v[160:161], v[230:231]
	v_pk_mul_f32 v[178:179], v[158:159], v[214:215]
	v_pk_mul_f32 v[212:213], v[156:157], v[212:213]
	v_pk_mul_f32 v[210:211], v[154:155], v[210:211]
	v_cvt_pk_bf16_f32 v178, v178, v179
	v_cvt_pk_bf16_f32 v179, v180, v181
	v_pk_fma_f32 v[184:185], v[100:101], v[148:149], v[184:185]
	v_cvt_pk_bf16_f32 v180, v210, v211
	v_cvt_pk_bf16_f32 v181, v212, v213
	v_pk_fma_f32 v[210:211], v[104:105], v[152:153], v[234:235]
	v_pk_fma_f32 v[212:213], v[102:103], v[150:151], v[232:233]
	v_pk_fma_f32 v[182:183], v[98:99], v[146:147], v[182:183]
	global_store_dwordx4 v[216:217], v[178:181], off offset:2048
	s_nop 1
	v_cvt_pk_f16_f32 v181, v184, v185
	v_cvt_pk_f16_f32 v179, v210, v211
	v_cvt_pk_f16_f32 v180, v182, v183
	v_cvt_pk_f16_f32 v178, v212, v213
	global_store_dwordx4 v[228:229], v[178:181], off offset:1024
	s_nop 1
	v_mul_f32_e32 v178, v213, v213
	v_mul_f32_e32 v179, v211, v211
	v_fmac_f32_e32 v178, v212, v212
	v_fmac_f32_e32 v179, v210, v210
	v_add_f32_e32 v178, v178, v179
	v_mul_f32_e32 v179, v183, v183
	v_mul_f32_e32 v180, v185, v185
	v_fmac_f32_e32 v179, v182, v182
	v_fmac_f32_e32 v180, v184, v184
	v_add_f32_e32 v179, v179, v180
	v_add_f32_e32 v178, v178, v179
	v_add_f32_e32 v0, v0, v178
	v_pk_mul_f32 v[178:179], v[136:137], v[210:211]
	v_pk_mul_f32 v[180:181], v[134:135], v[212:213]
	v_pk_mul_f32 v[184:185], v[132:133], v[184:185]
	v_cvt_pk_bf16_f32 v180, v180, v181
	v_cvt_pk_bf16_f32 v181, v178, v179
	ds_bpermute_b32 v178, v245, v0
	v_pk_mul_f32 v[182:183], v[130:131], v[182:183]
	s_waitcnt lgkmcnt(0)
	v_add_f32_e32 v0, v0, v178
	ds_bpermute_b32 v178, v244, v0
	v_cvt_pk_bf16_f32 v182, v182, v183
	v_cvt_pk_bf16_f32 v183, v184, v185
	v_add_co_u32_e32 v184, vcc, 0x10000, v216
	s_nop 1
	v_addc_co_u32_e32 v185, vcc, 0, v217, vcc
	global_store_dwordx4 v[184:185], v[180:183], off offset:2048
	s_and_saveexec_b64 s[46:47], s[28:29]
	s_cbranch_execz .LBB0_1136
	v_lshlrev_b64 v[180:181], 7, v[206:207]
	v_lshl_add_u64 v[180:181], s[42:43], 0, v[180:181]
	v_lshl_add_u64 v[180:181], s[34:35], 2, v[180:181]
	s_lshl_b32 s44, s71, 2
	v_lshl_add_u64 v[180:181], v[180:181], 0, s[44:45]
	s_waitcnt lgkmcnt(0)
	v_add_f32_e32 v0, v0, v178
	global_store_dword v[180:181], v0, off
; __device__ __forceinline__ float bperm(float v, int src_lane) { return __int_as_float(__builtin_amdgcn_ds_bpermute(src_lane << 2, __float_as_int(v))); }
; __device__ __forceinline__ u32x4 pack8(const f32x4 a, const f32x4 b) { u32x4 w; w.x = cvt_pk_bf16(a.x, a.y); w.y = cvt_pk_bf16(a.z, a.w); w.z = cvt_pk_bf16(b.x, b.y); w.w = cvt_pk_bf16(b.z, b.w); return w; }
; __host__ __device__ __forceinline__ size_t xs_off(int row, int col) { return (size_t)(row >> 8) * (256 * D) + (size_t)(col >> 6) * (256 * 64) + (size_t)((row & 255) * 64 + (col & 63)); }
;     template <bool INF32, int M0, int M1> __device__ __forceinline__ void half(f32x4 (&acc)[2][2][4][2], int ai, int b, int row0, int col, int pn, int wc, int fr, int fq) const {
;     ...
;         for (int m = M0; m < M1; ++m) { const int row = row0 + ai * 128 + m * 16; float ss = 0.f;
; #pragma unroll
;             for (int bj = 0; bj < 2; ++bj) { const size_t o = (size_t)row * D + col + bj * 128;
;                 const f32x4 x0 = xv[m][bj][0] + gt[bj][0] * acc[ai][bj][m][0], x1 = xv[m][bj][1] + gt[bj][1] * acc[ai][bj][m][1];
;                 if (out_f32) { *(f32x4*)((float*)xout + o) = x0; *(f32x4*)((float*)xout + o + 4) = x1; }
;                 else { const f32x8_t ff = {x0.x, x0.y, x0.z, x0.w, x1.x, x1.y, x1.z, x1.w}; *(f16x8_t*)((bf16_t*)xout + o) = __builtin_convertvector(ff, f16x8_t); }
;                 ss += ((x0.x * x0.x + x0.y * x0.y) + (x0.z * x0.z + x0.w * x0.w)) + ((x1.x * x1.x + x1.y * x1.y) + (x1.z * x1.z + x1.w * x1.w));
;                 if (XS) *(u32x4*)(XS + xs_off(row0, col) + (ai * 128 + m * 16) * 64 + bj * (2 * 256 * 64)) = pack8(x0 * gs[bj][0], x1 * gs[bj][1]); }
;             { const int ln = fr + 16 * fq; ss += bperm(ss, ln ^ 16); ss += bperm(ss, ln ^ 32); }
;             if (fq == 0) RSS[(size_t)row * 32 + pn * 4 + wc] = ss; }
.LBB0_1136:
	s_or_b64 exec, exec, s[46:47]
	v_cvt_f32_f16_sdwa v179, v176 dst_sel:DWORD dst_unused:UNUSED_PAD src0_sel:WORD_1
	v_cvt_f32_f16_sdwa v181, v177 dst_sel:DWORD dst_unused:UNUSED_PAD src0_sel:WORD_1
	v_cvt_f32_f16_sdwa v183, v174 dst_sel:DWORD dst_unused:UNUSED_PAD src0_sel:WORD_1
	v_cvt_f32_f16_sdwa v185, v175 dst_sel:DWORD dst_unused:UNUSED_PAD src0_sel:WORD_1
	s_waitcnt lgkmcnt(0)
	v_cvt_f32_f16_e32 v178, v176
	v_cvt_f32_f16_e32 v180, v177
	v_cvt_f32_f16_e32 v182, v174
	v_cvt_f32_f16_e32 v184, v175
	v_pk_fma_f32 v[178:179], v[90:91], v[162:163], v[178:179]
	v_pk_fma_f32 v[180:181], v[92:93], v[164:165], v[180:181]
	v_pk_fma_f32 v[182:183], v[94:95], v[166:167], v[182:183]
	v_pk_fma_f32 v[174:175], v[96:97], v[168:169], v[184:185]
	v_lshl_add_u64 v[184:185], s[10:11], 0, v[226:227]
	v_cvt_f32_f16_sdwa v177, v172 dst_sel:DWORD dst_unused:UNUSED_PAD src0_sel:WORD_1
	v_cvt_f32_f16_sdwa v211, v173 dst_sel:DWORD dst_unused:UNUSED_PAD src0_sel:WORD_1
	v_cvt_f32_f16_sdwa v213, v170 dst_sel:DWORD dst_unused:UNUSED_PAD src0_sel:WORD_1
	v_cvt_f32_f16_sdwa v215, v171 dst_sel:DWORD dst_unused:UNUSED_PAD src0_sel:WORD_1
	v_cvt_f32_f16_e32 v176, v172
	v_cvt_f32_f16_e32 v210, v173
	v_cvt_f32_f16_e32 v212, v170
	v_cvt_f32_f16_e32 v214, v171
	v_cvt_pk_f16_f32 v173, v180, v181
	v_cvt_pk_f16_f32 v171, v174, v175
	v_cvt_pk_f16_f32 v172, v178, v179
	v_cvt_pk_f16_f32 v170, v182, v183
	v_lshl_add_u64 v[184:185], v[198:199], 1, v[184:185]
	v_lshl_add_u64 v[184:185], v[184:185], 0, s[100:101]
	global_store_dwordx4 v[184:185], v[170:173], off
	v_mul_f32_e32 v0, v183, v183
	v_fmac_f32_e32 v0, v182, v182
	v_mul_f32_e32 v170, v175, v175
	v_fmac_f32_e32 v170, v174, v174
	v_add_f32_e32 v0, v0, v170
	v_mul_f32_e32 v170, v179, v179
	v_mul_f32_e32 v171, v181, v181
	v_fmac_f32_e32 v170, v178, v178
	v_fmac_f32_e32 v171, v180, v180
	v_add_f32_e32 v170, v170, v171
	v_add_f32_e32 v0, v0, v170
	v_pk_mul_f32 v[170:171], v[160:161], v[174:175]
	v_pk_mul_f32 v[172:173], v[158:159], v[182:183]
	s_movk_i32 s12, 0x1000
	v_pk_mul_f32 v[180:181], v[156:157], v[180:181]
	v_pk_mul_f32 v[174:175], v[154:155], v[178:179]
	v_cvt_pk_bf16_f32 v172, v172, v173
	v_cvt_pk_bf16_f32 v173, v170, v171
	v_add_co_u32_e32 v170, vcc, s12, v216
	v_cvt_pk_bf16_f32 v174, v174, v175
	v_cvt_pk_bf16_f32 v175, v180, v181
	v_pk_fma_f32 v[178:179], v[88:89], v[152:153], v[214:215]
	s_nop 0
	v_addc_co_u32_e32 v171, vcc, 0, v217, vcc
	v_pk_fma_f32 v[180:181], v[86:87], v[150:151], v[212:213]
	v_pk_fma_f32 v[182:183], v[84:85], v[148:149], v[210:211]
	v_pk_fma_f32 v[176:177], v[82:83], v[146:147], v[176:177]
	global_store_dwordx4 v[170:171], v[172:175], off
	s_nop 1
	v_cvt_pk_f16_f32 v175, v182, v183
	v_cvt_pk_f16_f32 v173, v178, v179
	v_cvt_pk_f16_f32 v174, v176, v177
	v_cvt_pk_f16_f32 v172, v180, v181
	global_store_dwordx4 v[184:185], v[172:175], off offset:1024
	s_nop 1
	v_mul_f32_e32 v172, v181, v181
	v_mul_f32_e32 v173, v179, v179
	v_fmac_f32_e32 v172, v180, v180
	v_fmac_f32_e32 v173, v178, v178
	v_add_f32_e32 v172, v172, v173
	v_mul_f32_e32 v173, v177, v177
	v_mul_f32_e32 v174, v183, v183
	v_fmac_f32_e32 v173, v176, v176
	v_fmac_f32_e32 v174, v182, v182
	v_add_f32_e32 v173, v173, v174
	v_add_f32_e32 v172, v172, v173
	v_add_f32_e32 v0, v0, v172
	v_pk_mul_f32 v[172:173], v[136:137], v[178:179]
	v_pk_mul_f32 v[174:175], v[134:135], v[180:181]
	v_pk_mul_f32 v[178:179], v[132:133], v[182:183]
	v_cvt_pk_bf16_f32 v174, v174, v175
	v_cvt_pk_bf16_f32 v175, v172, v173
	ds_bpermute_b32 v172, v245, v0
	v_pk_mul_f32 v[176:177], v[130:131], v[176:177]
	s_waitcnt lgkmcnt(0)
	v_add_f32_e32 v0, v0, v172
	ds_bpermute_b32 v172, v244, v0
	v_cvt_pk_bf16_f32 v176, v176, v177
	v_cvt_pk_bf16_f32 v177, v178, v179
	v_add_co_u32_e32 v178, vcc, 0x11000, v216
	s_nop 1
	v_addc_co_u32_e32 v179, vcc, 0, v217, vcc
	global_store_dwordx4 v[178:179], v[174:177], off
	s_and_saveexec_b64 s[46:47], s[28:29]
	s_cbranch_execz .LBB0_1138
	v_lshlrev_b64 v[174:175], 7, v[204:205]
	v_lshl_add_u64 v[174:175], s[42:43], 0, v[174:175]
	v_lshl_add_u64 v[174:175], s[34:35], 2, v[174:175]
	s_lshl_b32 s44, s71, 2
	v_lshl_add_u64 v[174:175], v[174:175], 0, s[44:45]
	s_waitcnt lgkmcnt(0)
	v_add_f32_e32 v0, v0, v172
	global_store_dword v[174:175], v0, off
.LBB0_1138:
	s_or_b64 exec, exec, s[46:47]
	v_cvt_f32_f16_sdwa v173, v144 dst_sel:DWORD dst_unused:UNUSED_PAD src0_sel:WORD_1
	v_cvt_f32_f16_sdwa v175, v145 dst_sel:DWORD dst_unused:UNUSED_PAD src0_sel:WORD_1
	v_cvt_f32_f16_sdwa v177, v142 dst_sel:DWORD dst_unused:UNUSED_PAD src0_sel:WORD_1
	v_cvt_f32_f16_sdwa v179, v143 dst_sel:DWORD dst_unused:UNUSED_PAD src0_sel:WORD_1
	s_waitcnt lgkmcnt(0)
; __device__ __forceinline__ float bperm(float v, int src_lane) { return __int_as_float(__builtin_amdgcn_ds_bpermute(src_lane << 2, __float_as_int(v))); }
;     template <bool INF32, int M0, int M1> __device__ __forceinline__ void half(f32x4 (&acc)[2][2][4][2], int ai, int b, int row0, int col, int pn, int wc, int fr, int fq) const {
;     ...
;             for (int m = M0; m < M1; ++m)
; #pragma unroll
;                 for (int bj = 0; bj < 2; ++bj) hh[m][bj] = *(const f16x8_t*)((const bf16_t*)xin + (size_t)(row0 + ai * 128 + m * 16) * D + col + bj * 128);
; #pragma unroll
;             for (int m = M0; m < M1; ++m)
; #pragma unroll
;                 for (int bj = 0; bj < 2; ++bj) { const f32x8_t ff = __builtin_convertvector(hh[m][bj], f32x8_t); xv[m][bj][0] = (f32x4){ff[0], ff[1], ff[2], ff[3]}; xv[m][bj][1] = (f32x4){ff[4], ff[5], ff[6], ff[7]}; }
;         }
;         f32x4 gt[2][2], gs[2][2];
; #pragma unroll
;         for (int bj = 0; bj < 2; ++bj)
; #pragma unroll
;             for (int n = 0; n < 2; ++n) { gt[bj][n] = *(const f32x4*)(gate + (size_t)b * 6 * D + col + bj * 128 + n * 4); gs[bj][n] = XS ? *(const f32x4*)(GS + (size_t)b * D + col + bj * 128 + n * 4) : (f32x4){0.f, 0.f, 0.f, 0.f}; }
;         __builtin_amdgcn_sched_barrier(0);
; #pragma unroll
;         for (int m = M0; m < M1; ++m) { const int row = row0 + ai * 128 + m * 16; float ss = 0.f;
; #pragma unroll
;             for (int bj = 0; bj < 2; ++bj) { const size_t o = (size_t)row * D + col + bj * 128;
;                 const f32x4 x0 = xv[m][bj][0] + gt[bj][0] * acc[ai][bj][m][0], x1 = xv[m][bj][1] + gt[bj][1] * acc[ai][bj][m][1];
;                 if (out_f32) { *(f32x4*)((float*)xout + o) = x0; *(f32x4*)((float*)xout + o + 4) = x1; }
;                 else { const f32x8_t ff = {x0.x, x0.y, x0.z, x0.w, x1.x, x1.y, x1.z, x1.w}; *(f16x8_t*)((bf16_t*)xout + o) = __builtin_convertvector(ff, f16x8_t); }
;                 ss += ((x0.x * x0.x + x0.y * x0.y) + (x0.z * x0.z + x0.w * x0.w)) + ((x1.x * x1.x + x1.y * x1.y) + (x1.z * x1.z + x1.w * x1.w));
;                 if (XS) *(u32x4*)(XS + xs_off(row0, col) + (ai * 128 + m * 16) * 64 + bj * (2 * 256 * 64)) = pack8(x0 * gs[bj][0], x1 * gs[bj][1]); }
;             { const int ln = fr + 16 * fq; ss += bperm(ss, ln ^ 16); ss += bperm(ss, ln ^ 32); }
;             if (fq == 0) RSS[(size_t)row * 32 + pn * 4 + wc] = ss; }
	v_cvt_f32_f16_e32 v172, v144
	v_cvt_f32_f16_e32 v174, v145
	v_cvt_f32_f16_e32 v176, v142
	v_cvt_f32_f16_e32 v178, v143
	v_pk_fma_f32 v[162:163], v[74:75], v[162:163], v[172:173]
	v_pk_fma_f32 v[164:165], v[76:77], v[164:165], v[174:175]
	v_pk_fma_f32 v[166:167], v[78:79], v[166:167], v[176:177]
	v_pk_fma_f32 v[168:169], v[80:81], v[168:169], v[178:179]
	v_lshl_add_u64 v[172:173], s[10:11], 0, v[218:219]
	v_cvt_f32_f16_sdwa v143, v140 dst_sel:DWORD dst_unused:UNUSED_PAD src0_sel:WORD_1
	v_cvt_f32_f16_sdwa v145, v141 dst_sel:DWORD dst_unused:UNUSED_PAD src0_sel:WORD_1
	v_cvt_f32_f16_sdwa v181, v138 dst_sel:DWORD dst_unused:UNUSED_PAD src0_sel:WORD_1
	v_cvt_f32_f16_sdwa v183, v139 dst_sel:DWORD dst_unused:UNUSED_PAD src0_sel:WORD_1
	v_cvt_f32_f16_e32 v142, v140
	v_cvt_f32_f16_e32 v144, v141
	v_cvt_f32_f16_e32 v180, v138
	v_cvt_f32_f16_e32 v182, v139
	v_cvt_pk_f16_f32 v141, v164, v165
	v_cvt_pk_f16_f32 v139, v168, v169
	v_cvt_pk_f16_f32 v140, v162, v163
	v_cvt_pk_f16_f32 v138, v166, v167
	v_lshl_add_u64 v[172:173], v[198:199], 1, v[172:173]
	v_lshl_add_u64 v[172:173], v[172:173], 0, s[100:101]
	global_store_dwordx4 v[172:173], v[138:141], off
	v_mul_f32_e32 v0, v167, v167
	v_fmac_f32_e32 v0, v166, v166
	v_mul_f32_e32 v138, v169, v169
	v_fmac_f32_e32 v138, v168, v168
	v_add_f32_e32 v0, v0, v138
	v_mul_f32_e32 v138, v163, v163
	v_mul_f32_e32 v139, v165, v165
	v_fmac_f32_e32 v138, v162, v162
	v_fmac_f32_e32 v139, v164, v164
	v_add_f32_e32 v138, v138, v139
	v_add_f32_e32 v0, v0, v138
	v_pk_mul_f32 v[140:141], v[160:161], v[168:169]
	v_pk_mul_f32 v[138:139], v[158:159], v[166:167]
	v_pk_mul_f32 v[156:157], v[156:157], v[164:165]
	v_pk_mul_f32 v[154:155], v[154:155], v[162:163]
	v_cvt_pk_bf16_f32 v138, v138, v139
	v_cvt_pk_bf16_f32 v139, v140, v141
	v_pk_fma_f32 v[152:153], v[72:73], v[152:153], v[182:183]
	v_cvt_pk_bf16_f32 v140, v154, v155
	v_cvt_pk_bf16_f32 v141, v156, v157
	v_pk_fma_f32 v[150:151], v[70:71], v[150:151], v[180:181]
	v_pk_fma_f32 v[144:145], v[68:69], v[148:149], v[144:145]
	v_pk_fma_f32 v[142:143], v[66:67], v[146:147], v[142:143]
	global_store_dwordx4 v[170:171], v[138:141], off offset:2048
	v_pk_mul_f32 v[136:137], v[136:137], v[152:153]
	v_pk_mul_f32 v[134:135], v[134:135], v[150:151]
	v_cvt_pk_f16_f32 v141, v144, v145
	v_cvt_pk_f16_f32 v139, v152, v153
	v_cvt_pk_f16_f32 v140, v142, v143
	v_cvt_pk_f16_f32 v138, v150, v151
	global_store_dwordx4 v[172:173], v[138:141], off offset:1024
	v_pk_mul_f32 v[130:131], v[130:131], v[142:143]
	s_nop 0
	v_mul_f32_e32 v138, v151, v151
	v_mul_f32_e32 v139, v153, v153
	v_fmac_f32_e32 v138, v150, v150
	v_fmac_f32_e32 v139, v152, v152
	v_add_f32_e32 v138, v138, v139
	v_mul_f32_e32 v139, v143, v143
	v_mul_f32_e32 v140, v145, v145
	v_fmac_f32_e32 v139, v142, v142
	v_fmac_f32_e32 v140, v144, v144
	v_add_f32_e32 v139, v139, v140
	v_add_f32_e32 v138, v138, v139
	v_add_f32_e32 v0, v0, v138
	v_pk_mul_f32 v[138:139], v[132:133], v[144:145]
	v_cvt_pk_bf16_f32 v132, v134, v135
	v_cvt_pk_bf16_f32 v133, v136, v137
	ds_bpermute_b32 v137, v245, v0
	v_cvt_pk_bf16_f32 v134, v130, v131
	v_add_co_u32_e32 v136, vcc, 0x11000, v216
	v_cvt_pk_bf16_f32 v135, v138, v139
	s_waitcnt lgkmcnt(0)
	v_add_f32_e32 v0, v0, v137
	ds_bpermute_b32 v130, v244, v0
	v_addc_co_u32_e32 v137, vcc, 0, v217, vcc
	global_store_dwordx4 v[136:137], v[132:135], off offset:2048
	s_and_saveexec_b64 s[46:47], s[28:29]
	s_cbranch_execz .LBB0_1140
	v_lshlrev_b64 v[132:133], 7, v[202:203]
	v_lshl_add_u64 v[132:133], s[42:43], 0, v[132:133]
	v_lshl_add_u64 v[132:133], s[34:35], 2, v[132:133]
	s_lshl_b32 s44, s71, 2
	v_lshl_add_u64 v[132:133], v[132:133], 0, s[44:45]
	s_waitcnt lgkmcnt(0)
	v_add_f32_e32 v0, v0, v130
	global_store_dword v[132:133], v0, off
.LBB0_1140:
	s_or_b64 exec, exec, s[46:47]
	v_add_u32_e32 v236, 0x80, v200
	v_ashrrev_i32_e32 v237, 31, v236
	v_add_u32_e32 v232, 0x90, v200
	v_lshlrev_b64 v[210:211], 12, v[236:237]
	v_bfe_u32 v211, v210, 12, 4
	v_lshl_add_u32 v210, v211, 6, v210
	v_lshlrev_b32_e32 v211, 12, v211
	v_sub_u32_e32 v210, v210, v211
	v_mov_b32_e32 v211, 0
	v_ashrrev_i32_e32 v233, 31, v232
	v_add_u32_e32 v228, 0xa0, v200
	v_add_u32_e32 v218, 0xb0, v200
	s_waitcnt lgkmcnt(0)
	v_lshl_add_u64 v[130:131], v[220:221], 0, v[210:211]
	v_lshlrev_b64 v[234:235], 12, v[232:233]
	v_bfe_u32 v235, v234, 12, 4
	v_lshl_add_u32 v234, v235, 6, v234
	v_lshlrev_b32_e32 v235, 12, v235
	v_sub_u32_e32 v234, v234, v235
	v_mov_b32_e32 v235, 0
	v_ashrrev_i32_e32 v229, 31, v228
	v_ashrrev_i32_e32 v219, 31, v218
	global_load_dwordx4 v[248:251], v[130:131], off
	global_load_dwordx4 v[212:215], v[130:131], off offset:1024
	v_lshl_add_u64 v[130:131], v[220:221], 0, v[234:235]
	v_lshlrev_b64 v[230:231], 12, v[228:229]
	v_bfe_u32 v231, v230, 12, 4
	v_lshl_add_u32 v230, v231, 6, v230
	v_lshlrev_b32_e32 v231, 12, v231
	v_sub_u32_e32 v230, v230, v231
	v_mov_b32_e32 v231, 0
	v_lshlrev_b64 v[226:227], 12, v[218:219]
	v_bfe_u32 v227, v226, 12, 4
	v_lshl_add_u32 v226, v227, 6, v226
	v_lshlrev_b32_e32 v227, 12, v227
	v_sub_u32_e32 v226, v226, v227
	v_mov_b32_e32 v227, 0
	global_load_dwordx4 v[182:185], v[130:131], off
	global_load_dwordx4 v[178:181], v[130:131], off offset:1024
	v_lshl_add_u64 v[130:131], v[220:221], 0, v[230:231]
	v_lshl_add_u64 v[162:163], v[220:221], 0, v[226:227]
	global_load_dwordx4 v[174:177], v[130:131], off
	global_load_dwordx4 v[170:173], v[130:131], off offset:1024
	global_load_dwordx4 v[154:157], v[222:223], off offset:16
	global_load_dwordx4 v[158:161], v[222:223], off
	global_load_dwordx4 v[146:149], v[224:225], off offset:16
	global_load_dwordx4 v[150:153], v[224:225], off
	global_load_dwordx4 v[138:141], v[222:223], off offset:528
	global_load_dwordx4 v[142:145], v[222:223], off offset:512
	global_load_dwordx4 v[130:133], v[224:225], off offset:528
	global_load_dwordx4 v[134:137], v[224:225], off offset:512
	global_load_dwordx4 v[166:169], v[162:163], off
	s_nop 0
	global_load_dwordx4 v[162:165], v[162:163], off offset:1024
	s_waitcnt vmcnt(15)
; __device__ __forceinline__ float bperm(float v, int src_lane) { return __int_as_float(__builtin_amdgcn_ds_bpermute(src_lane << 2, __float_as_int(v))); }
; __device__ __forceinline__ u32x4 pack8(const f32x4 a, const f32x4 b) { u32x4 w; w.x = cvt_pk_bf16(a.x, a.y); w.y = cvt_pk_bf16(a.z, a.w); w.z = cvt_pk_bf16(b.x, b.y); w.w = cvt_pk_bf16(b.z, b.w); return w; }
; __host__ __device__ __forceinline__ size_t xs_off(int row, int col) { return (size_t)(row >> 8) * (256 * D) + (size_t)(col >> 6) * (256 * 64) + (size_t)((row & 255) * 64 + (col & 63)); }
;     template <bool INF32, int M0, int M1> __device__ __forceinline__ void half(f32x4 (&acc)[2][2][4][2], int ai, int b, int row0, int col, int pn, int wc, int fr, int fq) const {
;     ...
;         for (int m = M0; m < M1; ++m) { const int row = row0 + ai * 128 + m * 16; float ss = 0.f;
; #pragma unroll
;             for (int bj = 0; bj < 2; ++bj) { const size_t o = (size_t)row * D + col + bj * 128;
;                 const f32x4 x0 = xv[m][bj][0] + gt[bj][0] * acc[ai][bj][m][0], x1 = xv[m][bj][1] + gt[bj][1] * acc[ai][bj][m][1];
;                 if (out_f32) { *(f32x4*)((float*)xout + o) = x0; *(f32x4*)((float*)xout + o + 4) = x1; }
;                 else { const f32x8_t ff = {x0.x, x0.y, x0.z, x0.w, x1.x, x1.y, x1.z, x1.w}; *(f16x8_t*)((bf16_t*)xout + o) = __builtin_convertvector(ff, f16x8_t); }
;                 ss += ((x0.x * x0.x + x0.y * x0.y) + (x0.z * x0.z + x0.w * x0.w)) + ((x1.x * x1.x + x1.y * x1.y) + (x1.z * x1.z + x1.w * x1.w));
;                 if (XS) *(u32x4*)(XS + xs_off(row0, col) + (ai * 128 + m * 16) * 64 + bj * (2 * 256 * 64)) = pack8(x0 * gs[bj][0], x1 * gs[bj][1]); }
;             { const int ln = fr + 16 * fq; ss += bperm(ss, ln ^ 16); ss += bperm(ss, ln ^ 32); }
;             if (fq == 0) RSS[(size_t)row * 32 + pn * 4 + wc] = ss; }
	v_cvt_f32_f16_e32 v220, v251
	v_cvt_f32_f16_sdwa v221, v251 dst_sel:DWORD dst_unused:UNUSED_PAD src0_sel:WORD_1
	v_cvt_f32_f16_e32 v222, v250
	v_cvt_f32_f16_sdwa v223, v250 dst_sel:DWORD dst_unused:UNUSED_PAD src0_sel:WORD_1
	v_cvt_f32_f16_e32 v224, v249
	v_cvt_f32_f16_sdwa v225, v249 dst_sel:DWORD dst_unused:UNUSED_PAD src0_sel:WORD_1
	v_cvt_f32_f16_e32 v238, v248
	v_cvt_f32_f16_sdwa v239, v248 dst_sel:DWORD dst_unused:UNUSED_PAD src0_sel:WORD_1
	s_waitcnt vmcnt(14)
	v_cvt_f32_f16_e32 v240, v215
	v_cvt_f32_f16_sdwa v241, v215 dst_sel:DWORD dst_unused:UNUSED_PAD src0_sel:WORD_1
	v_cvt_f32_f16_e32 v248, v214
	v_cvt_f32_f16_sdwa v249, v214 dst_sel:DWORD dst_unused:UNUSED_PAD src0_sel:WORD_1
	v_cvt_f32_f16_e32 v250, v213
	v_cvt_f32_f16_sdwa v251, v213 dst_sel:DWORD dst_unused:UNUSED_PAD src0_sel:WORD_1
	v_cvt_f32_f16_e32 v252, v212
	v_cvt_f32_f16_sdwa v253, v212 dst_sel:DWORD dst_unused:UNUSED_PAD src0_sel:WORD_1
	s_waitcnt vmcnt(8)
	v_pk_fma_f32 v[238:239], v[62:63], v[158:159], v[238:239]
	v_pk_fma_f32 v[224:225], v[64:65], v[160:161], v[224:225]
	v_pk_fma_f32 v[222:223], v[58:59], v[154:155], v[222:223]
	v_pk_fma_f32 v[220:221], v[60:61], v[156:157], v[220:221]
	v_lshl_add_u64 v[210:211], s[10:11], 0, v[210:211]
	v_mul_f32_e32 v0, v239, v239
	v_mul_f32_e32 v209, v225, v225
	v_cvt_pk_f16_f32 v215, v220, v221
	v_cvt_pk_f16_f32 v214, v222, v223
	v_cvt_pk_f16_f32 v213, v224, v225
	v_cvt_pk_f16_f32 v212, v238, v239
	v_lshl_add_u64 v[210:211], v[198:199], 1, v[210:211]
	v_lshl_add_u64 v[210:211], v[210:211], 0, s[100:101]
	v_fmac_f32_e32 v0, v238, v238
	v_fmac_f32_e32 v209, v224, v224
	global_store_dwordx4 v[210:211], v[212:215], off
	v_add_f32_e32 v0, v0, v209
	v_mul_f32_e32 v209, v223, v223
	v_mul_f32_e32 v212, v221, v221
	v_fmac_f32_e32 v209, v222, v222
	v_fmac_f32_e32 v212, v220, v220
	v_add_f32_e32 v209, v209, v212
	s_waitcnt vmcnt(7)
	v_pk_mul_f32 v[214:215], v[152:153], v[224:225]
	v_pk_mul_f32 v[212:213], v[150:151], v[238:239]
	v_pk_mul_f32 v[220:221], v[148:149], v[220:221]
	v_pk_mul_f32 v[222:223], v[146:147], v[222:223]
	v_cvt_pk_bf16_f32 v212, v212, v213
	v_cvt_pk_bf16_f32 v213, v214, v215
	s_waitcnt vmcnt(5)
	v_pk_fma_f32 v[224:225], v[56:57], v[144:145], v[250:251]
	v_cvt_pk_bf16_f32 v214, v222, v223
	v_cvt_pk_bf16_f32 v215, v220, v221
	v_add_co_u32_e32 v220, vcc, s60, v216
	v_pk_fma_f32 v[222:223], v[54:55], v[142:143], v[252:253]
	s_nop 0
	v_addc_co_u32_e32 v221, vcc, 0, v217, vcc
	v_pk_fma_f32 v[238:239], v[50:51], v[138:139], v[248:249]
	v_pk_fma_f32 v[240:241], v[52:53], v[140:141], v[240:241]
	global_store_dwordx4 v[220:221], v[212:215], off
	v_add_f32_e32 v0, v0, v209
	v_mul_f32_e32 v209, v223, v223
	v_cvt_pk_f16_f32 v215, v240, v241
	v_cvt_pk_f16_f32 v214, v238, v239
	v_cvt_pk_f16_f32 v213, v224, v225
	v_cvt_pk_f16_f32 v212, v222, v223
	global_store_dwordx4 v[210:211], v[212:215], off offset:1024
	v_mul_f32_e32 v210, v225, v225
	v_fmac_f32_e32 v209, v222, v222
	v_fmac_f32_e32 v210, v224, v224
	v_add_f32_e32 v209, v209, v210
	v_mul_f32_e32 v210, v239, v239
	v_mul_f32_e32 v211, v241, v241
	v_fmac_f32_e32 v210, v238, v238
	v_fmac_f32_e32 v211, v240, v240
	v_add_f32_e32 v210, v210, v211
	v_add_f32_e32 v209, v209, v210
	v_add_f32_e32 v0, v0, v209
	ds_bpermute_b32 v209, v245, v0
	s_waitcnt vmcnt(5)
	v_pk_mul_f32 v[210:211], v[136:137], v[224:225]
	v_pk_mul_f32 v[212:213], v[134:135], v[222:223]
	v_pk_mul_f32 v[214:215], v[130:131], v[238:239]
	v_cvt_pk_bf16_f32 v212, v212, v213
	s_waitcnt lgkmcnt(0)
	v_add_f32_e32 v0, v0, v209
	ds_bpermute_b32 v209, v244, v0
	v_cvt_pk_bf16_f32 v213, v210, v211
	v_add_co_u32_e32 v210, vcc, 0x14000, v216
	v_pk_mul_f32 v[222:223], v[132:133], v[240:241]
	s_nop 0
	v_addc_co_u32_e32 v211, vcc, 0, v217, vcc
	v_cvt_pk_bf16_f32 v214, v214, v215
	v_cvt_pk_bf16_f32 v215, v222, v223
	global_store_dwordx4 v[210:211], v[212:215], off
	s_and_saveexec_b64 s[46:47], s[28:29]
	s_cbranch_execz .LBB0_1142
	v_lshlrev_b64 v[210:211], 7, v[236:237]
	v_lshl_add_u64 v[210:211], s[42:43], 0, v[210:211]
	v_lshl_add_u64 v[210:211], s[34:35], 2, v[210:211]
	s_lshl_b32 s44, s71, 2
	v_lshl_add_u64 v[210:211], v[210:211], 0, s[44:45]
	s_waitcnt lgkmcnt(0)
	v_add_f32_e32 v0, v0, v209
	global_store_dword v[210:211], v0, off
.LBB0_1142:
	s_or_b64 exec, exec, s[46:47]
	v_cvt_f32_f16_sdwa v211, v184 dst_sel:DWORD dst_unused:UNUSED_PAD src0_sel:WORD_1
	v_cvt_f32_f16_sdwa v213, v185 dst_sel:DWORD dst_unused:UNUSED_PAD src0_sel:WORD_1
	v_cvt_f32_f16_sdwa v215, v182 dst_sel:DWORD dst_unused:UNUSED_PAD src0_sel:WORD_1
	v_cvt_f32_f16_sdwa v223, v183 dst_sel:DWORD dst_unused:UNUSED_PAD src0_sel:WORD_1
	v_cvt_f32_f16_e32 v210, v184
	v_cvt_f32_f16_e32 v212, v185
	v_cvt_f32_f16_e32 v214, v182
	v_cvt_f32_f16_e32 v222, v183
	v_pk_fma_f32 v[210:211], v[42:43], v[154:155], v[210:211]
	v_pk_fma_f32 v[212:213], v[44:45], v[156:157], v[212:213]
	v_pk_fma_f32 v[214:215], v[46:47], v[158:159], v[214:215]
	v_pk_fma_f32 v[222:223], v[48:49], v[160:161], v[222:223]
	v_lshl_add_u64 v[234:235], s[10:11], 0, v[234:235]
	v_cvt_f32_f16_sdwa v183, v180 dst_sel:DWORD dst_unused:UNUSED_PAD src0_sel:WORD_1
	v_cvt_f32_f16_sdwa v185, v181 dst_sel:DWORD dst_unused:UNUSED_PAD src0_sel:WORD_1
	v_cvt_f32_f16_sdwa v225, v178 dst_sel:DWORD dst_unused:UNUSED_PAD src0_sel:WORD_1
	v_cvt_f32_f16_sdwa v237, v179 dst_sel:DWORD dst_unused:UNUSED_PAD src0_sel:WORD_1
	v_cvt_f32_f16_e32 v182, v180
	v_cvt_f32_f16_e32 v184, v181
	v_cvt_f32_f16_e32 v224, v178
	v_cvt_f32_f16_e32 v236, v179
	v_cvt_pk_f16_f32 v181, v212, v213
	v_cvt_pk_f16_f32 v179, v222, v223
	v_cvt_pk_f16_f32 v180, v210, v211
	v_cvt_pk_f16_f32 v178, v214, v215
	v_lshl_add_u64 v[234:235], v[198:199], 1, v[234:235]
; __device__ __forceinline__ float bperm(float v, int src_lane) { return __int_as_float(__builtin_amdgcn_ds_bpermute(src_lane << 2, __float_as_int(v))); }
; __device__ __forceinline__ u32x4 pack8(const f32x4 a, const f32x4 b) { u32x4 w; w.x = cvt_pk_bf16(a.x, a.y); w.y = cvt_pk_bf16(a.z, a.w); w.z = cvt_pk_bf16(b.x, b.y); w.w = cvt_pk_bf16(b.z, b.w); return w; }
; __host__ __device__ __forceinline__ size_t xs_off(int row, int col) { return (size_t)(row >> 8) * (256 * D) + (size_t)(col >> 6) * (256 * 64) + (size_t)((row & 255) * 64 + (col & 63)); }
;     template <bool INF32, int M0, int M1> __device__ __forceinline__ void half(f32x4 (&acc)[2][2][4][2], int ai, int b, int row0, int col, int pn, int wc, int fr, int fq) const {
;     ...
;         for (int m = M0; m < M1; ++m) { const int row = row0 + ai * 128 + m * 16; float ss = 0.f;
; #pragma unroll
;             for (int bj = 0; bj < 2; ++bj) { const size_t o = (size_t)row * D + col + bj * 128;
;                 const f32x4 x0 = xv[m][bj][0] + gt[bj][0] * acc[ai][bj][m][0], x1 = xv[m][bj][1] + gt[bj][1] * acc[ai][bj][m][1];
;                 if (out_f32) { *(f32x4*)((float*)xout + o) = x0; *(f32x4*)((float*)xout + o + 4) = x1; }
;                 else { const f32x8_t ff = {x0.x, x0.y, x0.z, x0.w, x1.x, x1.y, x1.z, x1.w}; *(f16x8_t*)((bf16_t*)xout + o) = __builtin_convertvector(ff, f16x8_t); }
;                 ss += ((x0.x * x0.x + x0.y * x0.y) + (x0.z * x0.z + x0.w * x0.w)) + ((x1.x * x1.x + x1.y * x1.y) + (x1.z * x1.z + x1.w * x1.w));
;                 if (XS) *(u32x4*)(XS + xs_off(row0, col) + (ai * 128 + m * 16) * 64 + bj * (2 * 256 * 64)) = pack8(x0 * gs[bj][0], x1 * gs[bj][1]); }
;             { const int ln = fr + 16 * fq; ss += bperm(ss, ln ^ 16); ss += bperm(ss, ln ^ 32); }
;             if (fq == 0) RSS[(size_t)row * 32 + pn * 4 + wc] = ss; }
	v_lshl_add_u64 v[234:235], v[234:235], 0, s[100:101]
	global_store_dwordx4 v[234:235], v[178:181], off
	v_mul_f32_e32 v0, v215, v215
	v_fmac_f32_e32 v0, v214, v214
	v_mul_f32_e32 v178, v223, v223
	v_fmac_f32_e32 v178, v222, v222
	v_add_f32_e32 v0, v0, v178
	v_mul_f32_e32 v178, v211, v211
	v_mul_f32_e32 v179, v213, v213
	v_fmac_f32_e32 v178, v210, v210
	v_fmac_f32_e32 v179, v212, v212
	v_add_f32_e32 v178, v178, v179
	v_add_f32_e32 v0, v0, v178
	v_pk_mul_f32 v[180:181], v[152:153], v[222:223]
	v_pk_mul_f32 v[178:179], v[150:151], v[214:215]
	v_pk_mul_f32 v[212:213], v[148:149], v[212:213]
	v_pk_mul_f32 v[210:211], v[146:147], v[210:211]
	v_cvt_pk_bf16_f32 v178, v178, v179
	v_cvt_pk_bf16_f32 v179, v180, v181
	v_pk_fma_f32 v[184:185], v[36:37], v[140:141], v[184:185]
	v_cvt_pk_bf16_f32 v180, v210, v211
	v_cvt_pk_bf16_f32 v181, v212, v213
	v_pk_fma_f32 v[210:211], v[40:41], v[144:145], v[236:237]
	v_pk_fma_f32 v[212:213], v[38:39], v[142:143], v[224:225]
	v_pk_fma_f32 v[182:183], v[34:35], v[138:139], v[182:183]
	global_store_dwordx4 v[220:221], v[178:181], off offset:2048
	s_nop 1
	v_cvt_pk_f16_f32 v181, v184, v185
	v_cvt_pk_f16_f32 v179, v210, v211
	v_cvt_pk_f16_f32 v180, v182, v183
	v_cvt_pk_f16_f32 v178, v212, v213
	global_store_dwordx4 v[234:235], v[178:181], off offset:1024
	s_nop 1
	v_mul_f32_e32 v178, v213, v213
	v_mul_f32_e32 v179, v211, v211
	v_fmac_f32_e32 v178, v212, v212
	v_fmac_f32_e32 v179, v210, v210
	v_add_f32_e32 v178, v178, v179
	v_mul_f32_e32 v179, v183, v183
	v_mul_f32_e32 v180, v185, v185
	v_fmac_f32_e32 v179, v182, v182
	v_fmac_f32_e32 v180, v184, v184
	v_add_f32_e32 v179, v179, v180
	v_add_f32_e32 v178, v178, v179
	v_add_f32_e32 v0, v0, v178
	v_pk_mul_f32 v[178:179], v[136:137], v[210:211]
	v_pk_mul_f32 v[180:181], v[134:135], v[212:213]
	v_pk_mul_f32 v[184:185], v[132:133], v[184:185]
	v_cvt_pk_bf16_f32 v180, v180, v181
	v_cvt_pk_bf16_f32 v181, v178, v179
	ds_bpermute_b32 v178, v245, v0
	v_pk_mul_f32 v[182:183], v[130:131], v[182:183]
	s_waitcnt lgkmcnt(0)
	v_add_f32_e32 v0, v0, v178
	ds_bpermute_b32 v178, v244, v0
	v_cvt_pk_bf16_f32 v182, v182, v183
	v_cvt_pk_bf16_f32 v183, v184, v185
	v_add_co_u32_e32 v184, vcc, 0x14000, v216
	s_nop 1
	v_addc_co_u32_e32 v185, vcc, 0, v217, vcc
	global_store_dwordx4 v[184:185], v[180:183], off offset:2048
	s_and_saveexec_b64 s[46:47], s[28:29]
	s_cbranch_execz .LBB0_1144
	v_lshlrev_b64 v[180:181], 7, v[232:233]
	v_lshl_add_u64 v[180:181], s[42:43], 0, v[180:181]
	v_lshl_add_u64 v[180:181], s[34:35], 2, v[180:181]
	s_lshl_b32 s44, s71, 2
	v_lshl_add_u64 v[180:181], v[180:181], 0, s[44:45]
	s_waitcnt lgkmcnt(0)
	v_add_f32_e32 v0, v0, v178
	global_store_dword v[180:181], v0, off
.LBB0_1144:
	s_or_b64 exec, exec, s[46:47]
	v_cvt_f32_f16_sdwa v179, v176 dst_sel:DWORD dst_unused:UNUSED_PAD src0_sel:WORD_1
	v_cvt_f32_f16_sdwa v181, v177 dst_sel:DWORD dst_unused:UNUSED_PAD src0_sel:WORD_1
	v_cvt_f32_f16_sdwa v183, v174 dst_sel:DWORD dst_unused:UNUSED_PAD src0_sel:WORD_1
	v_cvt_f32_f16_sdwa v185, v175 dst_sel:DWORD dst_unused:UNUSED_PAD src0_sel:WORD_1
	s_waitcnt lgkmcnt(0)
	v_cvt_f32_f16_e32 v178, v176
	v_cvt_f32_f16_e32 v180, v177
	v_cvt_f32_f16_e32 v182, v174
	v_cvt_f32_f16_e32 v184, v175
	v_pk_fma_f32 v[178:179], v[26:27], v[154:155], v[178:179]
	v_pk_fma_f32 v[180:181], v[28:29], v[156:157], v[180:181]
	v_pk_fma_f32 v[182:183], v[30:31], v[158:159], v[182:183]
	v_pk_fma_f32 v[174:175], v[32:33], v[160:161], v[184:185]
	v_lshl_add_u64 v[184:185], s[10:11], 0, v[230:231]
	v_cvt_f32_f16_sdwa v177, v172 dst_sel:DWORD dst_unused:UNUSED_PAD src0_sel:WORD_1
	v_cvt_f32_f16_sdwa v211, v173 dst_sel:DWORD dst_unused:UNUSED_PAD src0_sel:WORD_1
	v_cvt_f32_f16_sdwa v213, v170 dst_sel:DWORD dst_unused:UNUSED_PAD src0_sel:WORD_1
	v_cvt_f32_f16_sdwa v215, v171 dst_sel:DWORD dst_unused:UNUSED_PAD src0_sel:WORD_1
	v_cvt_f32_f16_e32 v176, v172
	v_cvt_f32_f16_e32 v210, v173
	v_cvt_f32_f16_e32 v212, v170
	v_cvt_f32_f16_e32 v214, v171
	v_cvt_pk_f16_f32 v173, v180, v181
	v_cvt_pk_f16_f32 v171, v174, v175
	v_cvt_pk_f16_f32 v172, v178, v179
	v_cvt_pk_f16_f32 v170, v182, v183
	v_lshl_add_u64 v[184:185], v[198:199], 1, v[184:185]
	v_lshl_add_u64 v[184:185], v[184:185], 0, s[100:101]
	global_store_dwordx4 v[184:185], v[170:173], off
	v_mul_f32_e32 v0, v183, v183
	v_fmac_f32_e32 v0, v182, v182
	v_mul_f32_e32 v170, v175, v175
	v_fmac_f32_e32 v170, v174, v174
	v_add_f32_e32 v0, v0, v170
	v_mul_f32_e32 v170, v179, v179
	v_mul_f32_e32 v171, v181, v181
	v_fmac_f32_e32 v170, v178, v178
	v_fmac_f32_e32 v171, v180, v180
	v_add_f32_e32 v170, v170, v171
	v_add_f32_e32 v0, v0, v170
	v_pk_mul_f32 v[170:171], v[152:153], v[174:175]
	v_pk_mul_f32 v[172:173], v[150:151], v[182:183]
	v_pk_mul_f32 v[180:181], v[148:149], v[180:181]
	v_pk_mul_f32 v[174:175], v[146:147], v[178:179]
	v_cvt_pk_bf16_f32 v172, v172, v173
	v_cvt_pk_bf16_f32 v173, v170, v171
	v_add_co_u32_e32 v170, vcc, s82, v216
	v_cvt_pk_bf16_f32 v174, v174, v175
	v_cvt_pk_bf16_f32 v175, v180, v181
	v_pk_fma_f32 v[178:179], v[24:25], v[144:145], v[214:215]
	s_nop 0
	v_addc_co_u32_e32 v171, vcc, 0, v217, vcc
	v_pk_fma_f32 v[180:181], v[22:23], v[142:143], v[212:213]
	v_pk_fma_f32 v[182:183], v[20:21], v[140:141], v[210:211]
	v_pk_fma_f32 v[176:177], v[18:19], v[138:139], v[176:177]
	global_store_dwordx4 v[170:171], v[172:175], off
	s_nop 1
	v_cvt_pk_f16_f32 v175, v182, v183
	v_cvt_pk_f16_f32 v173, v178, v179
	v_cvt_pk_f16_f32 v174, v176, v177
	v_cvt_pk_f16_f32 v172, v180, v181
	global_store_dwordx4 v[184:185], v[172:175], off offset:1024
	s_nop 1
	v_mul_f32_e32 v172, v181, v181
	v_mul_f32_e32 v173, v179, v179
	v_fmac_f32_e32 v172, v180, v180
	v_fmac_f32_e32 v173, v178, v178
	v_add_f32_e32 v172, v172, v173
	v_mul_f32_e32 v173, v177, v177
	v_mul_f32_e32 v174, v183, v183
	v_fmac_f32_e32 v173, v176, v176
	v_fmac_f32_e32 v174, v182, v182
	v_add_f32_e32 v173, v173, v174
	v_add_f32_e32 v172, v172, v173
	v_add_f32_e32 v0, v0, v172
	v_pk_mul_f32 v[172:173], v[136:137], v[178:179]
	v_pk_mul_f32 v[174:175], v[134:135], v[180:181]
	v_pk_mul_f32 v[178:179], v[132:133], v[182:183]
	v_cvt_pk_bf16_f32 v174, v174, v175
	v_cvt_pk_bf16_f32 v175, v172, v173
	ds_bpermute_b32 v172, v245, v0
	v_pk_mul_f32 v[176:177], v[130:131], v[176:177]
	s_waitcnt lgkmcnt(0)
	v_add_f32_e32 v0, v0, v172
	ds_bpermute_b32 v172, v244, v0
	v_cvt_pk_bf16_f32 v176, v176, v177
	v_cvt_pk_bf16_f32 v177, v178, v179
	v_add_co_u32_e32 v178, vcc, 0x15000, v216
	s_nop 1
	v_addc_co_u32_e32 v179, vcc, 0, v217, vcc
	global_store_dwordx4 v[178:179], v[174:177], off
	s_and_saveexec_b64 s[46:47], s[28:29]
	s_cbranch_execz .LBB0_1146
	v_lshlrev_b64 v[174:175], 7, v[228:229]
	v_lshl_add_u64 v[174:175], s[42:43], 0, v[174:175]
	v_lshl_add_u64 v[174:175], s[34:35], 2, v[174:175]
	s_lshl_b32 s44, s71, 2
	v_lshl_add_u64 v[174:175], v[174:175], 0, s[44:45]
	s_waitcnt lgkmcnt(0)
	v_add_f32_e32 v0, v0, v172
	global_store_dword v[174:175], v0, off
; __device__ __forceinline__ float bperm(float v, int src_lane) { return __int_as_float(__builtin_amdgcn_ds_bpermute(src_lane << 2, __float_as_int(v))); }
; __device__ __forceinline__ u32x4 pack8(const f32x4 a, const f32x4 b) { u32x4 w; w.x = cvt_pk_bf16(a.x, a.y); w.y = cvt_pk_bf16(a.z, a.w); w.z = cvt_pk_bf16(b.x, b.y); w.w = cvt_pk_bf16(b.z, b.w); return w; }
; __host__ __device__ __forceinline__ size_t xs_off(int row, int col) { return (size_t)(row >> 8) * (256 * D) + (size_t)(col >> 6) * (256 * 64) + (size_t)((row & 255) * 64 + (col & 63)); }
;     template <bool INF32, int M0, int M1> __device__ __forceinline__ void half(f32x4 (&acc)[2][2][4][2], int ai, int b, int row0, int col, int pn, int wc, int fr, int fq) const {
;     ...
;         for (int m = M0; m < M1; ++m) { const int row = row0 + ai * 128 + m * 16; float ss = 0.f;
; #pragma unroll
;             for (int bj = 0; bj < 2; ++bj) { const size_t o = (size_t)row * D + col + bj * 128;
;                 const f32x4 x0 = xv[m][bj][0] + gt[bj][0] * acc[ai][bj][m][0], x1 = xv[m][bj][1] + gt[bj][1] * acc[ai][bj][m][1];
;                 if (out_f32) { *(f32x4*)((float*)xout + o) = x0; *(f32x4*)((float*)xout + o + 4) = x1; }
;                 else { const f32x8_t ff = {x0.x, x0.y, x0.z, x0.w, x1.x, x1.y, x1.z, x1.w}; *(f16x8_t*)((bf16_t*)xout + o) = __builtin_convertvector(ff, f16x8_t); }
;                 ss += ((x0.x * x0.x + x0.y * x0.y) + (x0.z * x0.z + x0.w * x0.w)) + ((x1.x * x1.x + x1.y * x1.y) + (x1.z * x1.z + x1.w * x1.w));
;                 if (XS) *(u32x4*)(XS + xs_off(row0, col) + (ai * 128 + m * 16) * 64 + bj * (2 * 256 * 64)) = pack8(x0 * gs[bj][0], x1 * gs[bj][1]); }
;             { const int ln = fr + 16 * fq; ss += bperm(ss, ln ^ 16); ss += bperm(ss, ln ^ 32); }
;             if (fq == 0) RSS[(size_t)row * 32 + pn * 4 + wc] = ss; }
.LBB0_1146:
	s_or_b64 exec, exec, s[46:47]
	s_waitcnt vmcnt(13)
	v_cvt_f32_f16_sdwa v173, v168 dst_sel:DWORD dst_unused:UNUSED_PAD src0_sel:WORD_1
	v_cvt_f32_f16_sdwa v175, v169 dst_sel:DWORD dst_unused:UNUSED_PAD src0_sel:WORD_1
	v_cvt_f32_f16_sdwa v177, v166 dst_sel:DWORD dst_unused:UNUSED_PAD src0_sel:WORD_1
	v_cvt_f32_f16_sdwa v179, v167 dst_sel:DWORD dst_unused:UNUSED_PAD src0_sel:WORD_1
	s_waitcnt lgkmcnt(0)
	v_cvt_f32_f16_e32 v172, v168
	v_cvt_f32_f16_e32 v174, v169
	v_cvt_f32_f16_e32 v176, v166
	v_cvt_f32_f16_e32 v178, v167
	s_waitcnt vmcnt(12)
	v_cvt_f32_f16_sdwa v167, v164 dst_sel:DWORD dst_unused:UNUSED_PAD src0_sel:WORD_1
	v_cvt_f32_f16_sdwa v169, v165 dst_sel:DWORD dst_unused:UNUSED_PAD src0_sel:WORD_1
	v_cvt_f32_f16_sdwa v181, v162 dst_sel:DWORD dst_unused:UNUSED_PAD src0_sel:WORD_1
	v_cvt_f32_f16_sdwa v183, v163 dst_sel:DWORD dst_unused:UNUSED_PAD src0_sel:WORD_1
	v_cvt_f32_f16_e32 v166, v164
	v_cvt_f32_f16_e32 v168, v165
	v_cvt_f32_f16_e32 v180, v162
	v_cvt_f32_f16_e32 v182, v163
	v_pk_fma_f32 v[160:161], v[16:17], v[160:161], v[178:179]
	v_pk_fma_f32 v[158:159], v[14:15], v[158:159], v[176:177]
	v_pk_fma_f32 v[162:163], v[12:13], v[156:157], v[174:175]
	v_pk_fma_f32 v[164:165], v[10:11], v[154:155], v[172:173]
	v_lshl_add_u64 v[172:173], s[10:11], 0, v[226:227]
	v_cvt_pk_f16_f32 v157, v162, v163
	v_cvt_pk_f16_f32 v155, v160, v161
	v_cvt_pk_f16_f32 v156, v164, v165
	v_cvt_pk_f16_f32 v154, v158, v159
	v_lshl_add_u64 v[172:173], v[198:199], 1, v[172:173]
	v_lshl_add_u64 v[172:173], v[172:173], 0, s[100:101]
	global_store_dwordx4 v[172:173], v[154:157], off
	v_pk_mul_f32 v[152:153], v[152:153], v[160:161]
	v_pk_mul_f32 v[150:151], v[150:151], v[158:159]
	v_pk_mul_f32 v[154:155], v[148:149], v[162:163]
	v_pk_mul_f32 v[148:149], v[146:147], v[164:165]
	v_cvt_pk_bf16_f32 v146, v150, v151
	v_cvt_pk_bf16_f32 v147, v152, v153
	v_pk_fma_f32 v[144:145], v[8:9], v[144:145], v[182:183]
	v_cvt_pk_bf16_f32 v148, v148, v149
	v_cvt_pk_bf16_f32 v149, v154, v155
	global_store_dwordx4 v[170:171], v[146:149], off offset:2048
	v_pk_fma_f32 v[142:143], v[6:7], v[142:143], v[180:181]
	v_mov_b32_e32 v150, v161
	v_pk_fma_f32 v[146:147], v[4:5], v[140:141], v[168:169]
	v_pk_fma_f32 v[148:149], v[2:3], v[138:139], v[166:167]
	v_cvt_pk_f16_f32 v141, v146, v147
	v_cvt_pk_f16_f32 v139, v144, v145
	v_cvt_pk_f16_f32 v140, v148, v149
	v_cvt_pk_f16_f32 v138, v142, v143
	global_store_dwordx4 v[172:173], v[138:141], off offset:1024
	v_mov_b32_e32 v151, v145
	v_pk_mul_f32 v[150:151], v[150:151], v[150:151]
	v_mov_b32_e32 v140, v159
	v_mov_b32_e32 v141, v143
	v_mov_b32_e32 v138, v158
	v_mov_b32_e32 v139, v142
	v_pk_mul_f32 v[140:141], v[140:141], v[140:141]
	v_mov_b32_e32 v152, v163
	v_pk_fma_f32 v[138:139], v[138:139], v[138:139], v[140:141]
	v_mov_b32_e32 v140, v160
	v_mov_b32_e32 v141, v144
	v_pk_fma_f32 v[140:141], v[140:141], v[140:141], v[150:151]
	v_mov_b32_e32 v150, v165
	v_mov_b32_e32 v151, v149
	v_pk_add_f32 v[138:139], v[138:139], v[140:141]
	v_mov_b32_e32 v140, v164
	v_mov_b32_e32 v141, v148
	v_pk_mul_f32 v[150:151], v[150:151], v[150:151]
	v_mov_b32_e32 v153, v147
	v_pk_fma_f32 v[140:141], v[140:141], v[140:141], v[150:151]
	v_mov_b32_e32 v150, v162
	v_mov_b32_e32 v151, v146
	v_pk_mul_f32 v[152:153], v[152:153], v[152:153]
	v_pk_mul_f32 v[136:137], v[136:137], v[144:145]
	v_pk_fma_f32 v[150:151], v[150:151], v[150:151], v[152:153]
	v_pk_mul_f32 v[134:135], v[134:135], v[142:143]
	v_pk_add_f32 v[140:141], v[140:141], v[150:151]
	v_pk_mul_f32 v[130:131], v[130:131], v[148:149]
	v_pk_add_f32 v[138:139], v[138:139], v[140:141]
	s_nop 0
	v_add_f32_e32 v0, v138, v139
	v_pk_mul_f32 v[138:139], v[132:133], v[146:147]
	v_cvt_pk_bf16_f32 v132, v134, v135
	v_cvt_pk_bf16_f32 v133, v136, v137
	ds_bpermute_b32 v137, v245, v0
	v_add_co_u32_e32 v136, vcc, 0x15000, v216
	v_cvt_pk_bf16_f32 v134, v130, v131
	v_cvt_pk_bf16_f32 v135, v138, v139
	s_waitcnt lgkmcnt(0)
	v_add_f32_e32 v0, v0, v137
	v_addc_co_u32_e32 v137, vcc, 0, v217, vcc
	ds_bpermute_b32 v130, v244, v0
	global_store_dwordx4 v[136:137], v[132:135], off offset:2048

;     template <bool INF32, int M0, int M1> __device__ __forceinline__ void half(f32x4 (&acc)[2][2][4][2], int ai, int b, int row0, int col, int pn, int wc, int fr, int fq) const {
;     ...
;         if (INF32) {
; #pragma unroll
;             for (int m = M0; m < M1; ++m)
; #pragma unroll
;                 for (int bj = 0; bj < 2; ++bj) { const float* p = (const float*)xin + (size_t)(row0 + ai * 128 + m * 16) * D + col + bj * 128; xv[m][bj][0] = *(const f32x4*)p; xv[m][bj][1] = *(const f32x4*)(p + 4); }
;         } else {
;             f16x8_t hh[4][2];
; #pragma unroll
;             for (int m = M0; m < M1; ++m)
; #pragma unroll
;                 for (int bj = 0; bj < 2; ++bj) hh[m][bj] = *(const f16x8_t*)((const bf16_t*)xin + (size_t)(row0 + ai * 128 + m * 16) * D + col + bj * 128);
; #pragma unroll
;             for (int m = M0; m < M1; ++m)
; #pragma unroll
;                 for (int bj = 0; bj < 2; ++bj) { const f32x8_t ff = __builtin_convertvector(hh[m][bj], f32x8_t); xv[m][bj][0] = (f32x4){ff[0], ff[1], ff[2], ff[3]}; xv[m][bj][1] = (f32x4){ff[4], ff[5], ff[6], ff[7]}; }
;         }
;         f32x4 gt[2][2], gs[2][2];
; #pragma unroll
;         for (int bj = 0; bj < 2; ++bj)
; #pragma unroll
;             for (int n = 0; n < 2; ++n) { gt[bj][n] = *(const f32x4*)(gate + (size_t)b * 6 * D + col + bj * 128 + n * 4); gs[bj][n] = XS ? *(const f32x4*)(GS + (size_t)b * D + col + bj * 128 + n * 4) : (f32x4){0.f, 0.f, 0.f, 0.f}; }
;         __builtin_amdgcn_sched_barrier(0);
; #pragma unroll
;         for (int m = M0; m < M1; ++m) { const int row = row0 + ai * 128 + m * 16; float ss = 0.f;
; #pragma unroll
;             for (int bj = 0; bj < 2; ++bj) { const size_t o = (size_t)row * D + col + bj * 128;
;                 const f32x4 x0 = xv[m][bj][0] + gt[bj][0] * acc[ai][bj][m][0], x1 = xv[m][bj][1] + gt[bj][1] * acc[ai][bj][m][1];
;                 if (out_f32) { *(f32x4*)((float*)xout + o) = x0; *(f32x4*)((float*)xout + o + 4) = x1; }
;                 else { const f32x8_t ff = {x0.x, x0.y, x0.z, x0.w, x1.x, x1.y, x1.z, x1.w}; *(f16x8_t*)((bf16_t*)xout + o) = __builtin_convertvector(ff, f16x8_t); }
;                 ss += ((x0.x * x0.x + x0.y * x0.y) + (x0.z * x0.z + x0.w * x0.w)) + ((x1.x * x1.x + x1.y * x1.y) + (x1.z * x1.z + x1.w * x1.w));
.LBB0_1149:
	s_mov_b64 s[28:29], 0
	s_cbranch_execz .LBB0_1147
	s_ashr_i32 s34, s31, 8
	s_ashr_i32 s37, s36, 31
	s_ashr_i32 s35, s34, 31
	v_readlane_b32 s12, v254, 30
	s_lshl_b64 s[28:29], s[36:37], 13
	s_lshl_b64 s[36:37], s[34:35], 20
	v_readlane_b32 s13, v254, 31
	v_lshlrev_b64 v[132:133], 2, v[198:199]
	s_waitcnt lgkmcnt(0)
	v_lshlrev_b64 v[130:131], 13, v[200:201]
	v_lshl_add_u64 v[180:181], s[12:13], 0, v[132:133]
	s_add_u32 s34, s63, s66
	v_lshl_add_u64 v[130:131], v[180:181], 0, v[130:131]
	s_addc_u32 s35, s67, s65
	global_load_dwordx4 v[216:219], v[130:131], off offset:16
	global_load_dwordx4 v[220:223], v[130:131], off
	global_load_dwordx4 v[224:227], v[130:131], off offset:528
	global_load_dwordx4 v[228:231], v[130:131], off offset:512
	v_lshlrev_b64 v[130:131], 13, v[206:207]
	s_add_u32 s28, s68, s28
	v_lshl_add_u64 v[130:131], v[180:181], 0, v[130:131]
	v_lshl_add_u64 v[182:183], s[34:35], 0, v[132:133]
	s_addc_u32 s29, s70, s29
	global_load_dwordx4 v[162:165], v[130:131], off offset:16
	global_load_dwordx4 v[166:169], v[130:131], off
	global_load_dwordx4 v[138:141], v[130:131], off offset:528
	global_load_dwordx4 v[142:145], v[130:131], off offset:512
	v_lshl_add_u64 v[184:185], s[28:29], 0, v[132:133]
	global_load_dwordx4 v[170:173], v[182:183], off offset:16
	global_load_dwordx4 v[174:177], v[182:183], off
	global_load_dwordx4 v[154:157], v[184:185], off offset:16
	global_load_dwordx4 v[158:161], v[184:185], off
	global_load_dwordx4 v[146:149], v[182:183], off offset:528
	global_load_dwordx4 v[150:153], v[182:183], off offset:512
	global_load_dwordx4 v[130:133], v[184:185], off offset:528
	global_load_dwordx4 v[134:137], v[184:185], off offset:512
	v_ashrrev_i32_e32 v209, 31, v208
	v_lshlrev_b64 v[178:179], 15, v[208:209]
	v_cmp_gt_u32_e64 s[28:29], 16, v247
	v_readlane_b32 s14, v254, 32
	v_readlane_b32 s15, v254, 33
	v_readlane_b32 s16, v254, 34
	v_readlane_b32 s17, v254, 35
	v_readlane_b32 s18, v254, 36
	v_readlane_b32 s19, v254, 37
	v_readlane_b32 s20, v254, 38
	v_readlane_b32 s21, v254, 39
	v_readlane_b32 s22, v254, 40
	v_readlane_b32 s23, v254, 41
	v_readlane_b32 s24, v254, 42
	v_readlane_b32 s25, v254, 43
	v_readlane_b32 s26, v254, 44
	v_readlane_b32 s27, v254, 45
	v_lshlrev_b64 v[212:213], 12, v[200:201]
	v_bfe_u32 v213, v212, 12, 4
	v_lshl_add_u32 v212, v213, 6, v212
	v_lshlrev_b32_e32 v213, 12, v213
	v_sub_u32_e32 v212, v212, v213
	v_mov_b32_e32 v213, 0
	s_waitcnt vmcnt(0)
	v_pk_fma_f32 v[128:129], v[128:129], v[176:177], v[222:223]
	v_pk_fma_f32 v[126:127], v[126:127], v[174:175], v[220:221]
	v_pk_fma_f32 v[208:209], v[124:125], v[172:173], v[218:219]
	v_pk_fma_f32 v[210:211], v[122:123], v[170:171], v[216:217]
	v_lshl_add_u64 v[212:213], s[10:11], 0, v[212:213]
	v_cvt_pk_f16_f32 v125, v208, v209
	v_cvt_pk_f16_f32 v123, v128, v129
	v_cvt_pk_f16_f32 v124, v210, v211
	v_cvt_pk_f16_f32 v122, v126, v127
	v_lshl_add_u64 v[212:213], v[198:199], 1, v[212:213]
	v_lshl_add_u64 v[212:213], v[212:213], 0, s[100:101]
	global_store_dwordx4 v[212:213], v[122:125], off
	v_mul_f32_e32 v0, v127, v127
	v_fmac_f32_e32 v0, v126, v126
	v_mul_f32_e32 v122, v129, v129
	v_fmac_f32_e32 v122, v128, v128
	v_add_f32_e32 v0, v0, v122
	v_mul_f32_e32 v122, v211, v211
	v_mul_f32_e32 v123, v209, v209
	v_fmac_f32_e32 v122, v210, v210
	v_fmac_f32_e32 v123, v208, v208
	v_add_f32_e32 v122, v122, v123
	v_add_f32_e32 v214, v0, v122
	v_pk_mul_f32 v[124:125], v[160:161], v[128:129]
	v_pk_mul_f32 v[122:123], v[158:159], v[126:127]
	v_pk_mul_f32 v[126:127], v[156:157], v[208:209]
	v_pk_mul_f32 v[128:129], v[154:155], v[210:211]
	v_cvt_pk_bf16_f32 v122, v122, v123
	v_cvt_pk_bf16_f32 v123, v124, v125
	v_lshlrev_b32_e32 v0, 1, v246
	v_cvt_pk_bf16_f32 v124, v128, v129
	v_cvt_pk_bf16_f32 v125, v126, v127
	v_lshl_add_u64 v[126:127], s[74:75], 0, v[178:179]
	v_lshl_add_u64 v[126:127], v[126:127], 0, s[36:37]
	v_lshl_add_u64 v[178:179], v[126:127], 0, v[0:1]
	global_store_dwordx4 v[178:179], v[122:125], off
	v_pk_fma_f32 v[120:121], v[120:121], v[152:153], v[230:231]
	v_pk_fma_f32 v[118:119], v[118:119], v[150:151], v[228:229]
	v_pk_fma_f32 v[122:123], v[116:117], v[148:149], v[226:227]
	v_pk_fma_f32 v[124:125], v[114:115], v[146:147], v[224:225]
	v_cvt_pk_f16_f32 v117, v122, v123
	v_cvt_pk_f16_f32 v115, v120, v121
	v_cvt_pk_f16_f32 v116, v124, v125
	v_cvt_pk_f16_f32 v114, v118, v119
	global_store_dwordx4 v[212:213], v[114:117], off offset:1024
	v_mul_f32_e32 v0, v119, v119
	v_fmac_f32_e32 v0, v118, v118
	v_mul_f32_e32 v114, v121, v121
	v_fmac_f32_e32 v114, v120, v120
	v_add_f32_e32 v0, v0, v114
	v_mul_f32_e32 v114, v125, v125
	v_mul_f32_e32 v115, v123, v123
	v_fmac_f32_e32 v114, v124, v124
	v_fmac_f32_e32 v115, v122, v122
	v_add_f32_e32 v114, v114, v115
	v_add_f32_e32 v0, v0, v114
	v_add_f32_e32 v0, v214, v0
	v_pk_mul_f32 v[114:115], v[136:137], v[120:121]
	v_pk_mul_f32 v[116:117], v[134:135], v[118:119]
	v_pk_mul_f32 v[120:121], v[132:133], v[122:123]
	v_cvt_pk_bf16_f32 v116, v116, v117
	v_cvt_pk_bf16_f32 v117, v114, v115
	ds_bpermute_b32 v114, v245, v0
	v_pk_mul_f32 v[118:119], v[130:131], v[124:125]
	s_lshl_b32 s34, s30, 2
	v_cvt_pk_bf16_f32 v118, v118, v119
	v_cvt_pk_bf16_f32 v119, v120, v121
	s_waitcnt lgkmcnt(0)
	v_add_f32_e32 v0, v0, v114
	ds_bpermute_b32 v114, v244, v0
	v_add_co_u32_e32 v120, vcc, 0x10000, v178
	s_ashr_i32 s35, s34, 31
	s_nop 0
	v_addc_co_u32_e32 v121, vcc, 0, v179, vcc
	global_store_dwordx4 v[120:121], v[116:119], off
	s_and_saveexec_b64 s[30:31], s[28:29]
	s_cbranch_execz .LBB0_1152
	v_lshlrev_b64 v[116:117], 7, v[200:201]
	v_lshl_add_u64 v[116:117], s[42:43], 0, v[116:117]
	v_lshl_add_u64 v[116:117], s[34:35], 2, v[116:117]
	s_lshl_b32 s44, s71, 2
	v_lshl_add_u64 v[116:117], v[116:117], 0, s[44:45]
	s_waitcnt lgkmcnt(0)
	v_add_f32_e32 v0, v0, v114
	global_store_dword v[116:117], v0, off
;     template <bool INF32, int M0, int M1> __device__ __forceinline__ void half(f32x4 (&acc)[2][2][4][2], int ai, int b, int row0, int col, int pn, int wc, int fr, int fq) const {
;     ...
;         if (INF32) {
; #pragma unroll
;             for (int m = M0; m < M1; ++m)
; #pragma unroll
;                 for (int bj = 0; bj < 2; ++bj) { const float* p = (const float*)xin + (size_t)(row0 + ai * 128 + m * 16) * D + col + bj * 128; xv[m][bj][0] = *(const f32x4*)p; xv[m][bj][1] = *(const f32x4*)(p + 4); }
;         } else {
;             f16x8_t hh[4][2];
; #pragma unroll
;             for (int m = M0; m < M1; ++m)
; #pragma unroll
;                 for (int bj = 0; bj < 2; ++bj) hh[m][bj] = *(const f16x8_t*)((const bf16_t*)xin + (size_t)(row0 + ai * 128 + m * 16) * D + col + bj * 128);
; #pragma unroll
;             for (int m = M0; m < M1; ++m)
; #pragma unroll
;                 for (int bj = 0; bj < 2; ++bj) { const f32x8_t ff = __builtin_convertvector(hh[m][bj], f32x8_t); xv[m][bj][0] = (f32x4){ff[0], ff[1], ff[2], ff[3]}; xv[m][bj][1] = (f32x4){ff[4], ff[5], ff[6], ff[7]}; }
;         }
;         f32x4 gt[2][2], gs[2][2];
; #pragma unroll
;         for (int bj = 0; bj < 2; ++bj)
; #pragma unroll
;             for (int n = 0; n < 2; ++n) { gt[bj][n] = *(const f32x4*)(gate + (size_t)b * 6 * D + col + bj * 128 + n * 4); gs[bj][n] = XS ? *(const f32x4*)(GS + (size_t)b * D + col + bj * 128 + n * 4) : (f32x4){0.f, 0.f, 0.f, 0.f}; }
;         __builtin_amdgcn_sched_barrier(0);
; #pragma unroll
;         for (int m = M0; m < M1; ++m) { const int row = row0 + ai * 128 + m * 16; float ss = 0.f;
; #pragma unroll
;             for (int bj = 0; bj < 2; ++bj) { const size_t o = (size_t)row * D + col + bj * 128;
;                 const f32x4 x0 = xv[m][bj][0] + gt[bj][0] * acc[ai][bj][m][0], x1 = xv[m][bj][1] + gt[bj][1] * acc[ai][bj][m][1];
;                 if (out_f32) { *(f32x4*)((float*)xout + o) = x0; *(f32x4*)((float*)xout + o + 4) = x1; }
;                 else { const f32x8_t ff = {x0.x, x0.y, x0.z, x0.w, x1.x, x1.y, x1.z, x1.w}; *(f16x8_t*)((bf16_t*)xout + o) = __builtin_convertvector(ff, f16x8_t); }
;                 ss += ((x0.x * x0.x + x0.y * x0.y) + (x0.z * x0.z + x0.w * x0.w)) + ((x1.x * x1.x + x1.y * x1.y) + (x1.z * x1.z + x1.w * x1.w));
.LBB0_1152:
	s_or_b64 exec, exec, s[30:31]
	v_lshlrev_b64 v[118:119], 12, v[206:207]
	v_bfe_u32 v119, v118, 12, 4
	v_lshl_add_u32 v118, v119, 6, v118
	v_lshlrev_b32_e32 v119, 12, v119
	v_sub_u32_e32 v118, v118, v119
	v_mov_b32_e32 v119, 0
	v_pk_fma_f32 v[112:113], v[112:113], v[176:177], v[168:169]
	v_pk_fma_f32 v[110:111], v[110:111], v[174:175], v[166:167]
	s_waitcnt lgkmcnt(0)
	v_pk_fma_f32 v[114:115], v[108:109], v[172:173], v[164:165]
	v_pk_fma_f32 v[116:117], v[106:107], v[170:171], v[162:163]
	v_lshl_add_u64 v[118:119], s[10:11], 0, v[118:119]
	v_cvt_pk_f16_f32 v109, v114, v115
	v_cvt_pk_f16_f32 v107, v112, v113
	v_cvt_pk_f16_f32 v106, v110, v111
	v_cvt_pk_f16_f32 v108, v116, v117
	v_lshl_add_u64 v[118:119], v[198:199], 1, v[118:119]
	v_lshl_add_u64 v[118:119], v[118:119], 0, s[100:101]
	global_store_dwordx4 v[118:119], v[106:109], off
	v_mul_f32_e32 v0, v111, v111
	v_fmac_f32_e32 v0, v110, v110
	v_mul_f32_e32 v106, v113, v113
	v_fmac_f32_e32 v106, v112, v112
	v_add_f32_e32 v0, v0, v106
	v_mul_f32_e32 v106, v117, v117
	v_mul_f32_e32 v107, v115, v115
	v_fmac_f32_e32 v106, v116, v116
	v_fmac_f32_e32 v107, v114, v114
	v_add_f32_e32 v106, v106, v107
	v_add_f32_e32 v0, v0, v106
	v_pk_mul_f32 v[108:109], v[160:161], v[112:113]
	v_pk_mul_f32 v[106:107], v[158:159], v[110:111]
	v_pk_mul_f32 v[110:111], v[156:157], v[114:115]
	v_pk_mul_f32 v[112:113], v[154:155], v[116:117]
	v_cvt_pk_bf16_f32 v106, v106, v107
	v_cvt_pk_bf16_f32 v107, v108, v109
	v_pk_fma_f32 v[104:105], v[104:105], v[152:153], v[144:145]
	v_cvt_pk_bf16_f32 v108, v112, v113
	v_cvt_pk_bf16_f32 v109, v110, v111
	global_store_dwordx4 v[178:179], v[106:109], off offset:2048
	v_pk_fma_f32 v[102:103], v[102:103], v[150:151], v[142:143]
	s_nop 0
	v_pk_fma_f32 v[106:107], v[100:101], v[148:149], v[140:141]
	v_pk_fma_f32 v[108:109], v[98:99], v[146:147], v[138:139]
	v_cvt_pk_f16_f32 v101, v106, v107
	v_cvt_pk_f16_f32 v99, v104, v105
	v_cvt_pk_f16_f32 v98, v102, v103
	v_cvt_pk_f16_f32 v100, v108, v109
	global_store_dwordx4 v[118:119], v[98:101], off offset:1024
	s_nop 1
	v_mul_f32_e32 v98, v103, v103
	v_mul_f32_e32 v99, v105, v105
	v_fmac_f32_e32 v98, v102, v102
	v_fmac_f32_e32 v99, v104, v104
	v_add_f32_e32 v98, v98, v99
	v_mul_f32_e32 v99, v109, v109
	v_mul_f32_e32 v100, v107, v107
	v_fmac_f32_e32 v99, v108, v108
	v_fmac_f32_e32 v100, v106, v106
	v_add_f32_e32 v99, v99, v100
	v_add_f32_e32 v98, v98, v99
	v_add_f32_e32 v0, v0, v98
	v_pk_mul_f32 v[98:99], v[136:137], v[104:105]
	v_pk_mul_f32 v[100:101], v[134:135], v[102:103]
	v_pk_mul_f32 v[104:105], v[132:133], v[106:107]
	v_cvt_pk_bf16_f32 v100, v100, v101
	v_cvt_pk_bf16_f32 v101, v98, v99
	ds_bpermute_b32 v98, v245, v0
	v_pk_mul_f32 v[102:103], v[130:131], v[108:109]
	s_waitcnt lgkmcnt(0)
	v_add_f32_e32 v0, v0, v98
	ds_bpermute_b32 v98, v244, v0
	v_cvt_pk_bf16_f32 v102, v102, v103
	v_cvt_pk_bf16_f32 v103, v104, v105
	v_add_co_u32_e32 v104, vcc, 0x10000, v178
	s_nop 1
	v_addc_co_u32_e32 v105, vcc, 0, v179, vcc
	global_store_dwordx4 v[104:105], v[100:103], off offset:2048
	s_and_saveexec_b64 s[30:31], s[28:29]
	s_cbranch_execz .LBB0_1154
	v_lshlrev_b64 v[100:101], 7, v[206:207]
	v_lshl_add_u64 v[100:101], s[42:43], 0, v[100:101]
	v_lshl_add_u64 v[100:101], s[34:35], 2, v[100:101]
	s_lshl_b32 s44, s71, 2
	v_lshl_add_u64 v[100:101], v[100:101], 0, s[44:45]
	s_waitcnt lgkmcnt(0)
	v_add_f32_e32 v0, v0, v98
	global_store_dword v[100:101], v0, off
.LBB0_1154:
	s_or_b64 exec, exec, s[30:31]
	s_waitcnt lgkmcnt(0)
	v_lshlrev_b64 v[98:99], 13, v[204:205]
	v_lshl_add_u64 v[98:99], v[180:181], 0, v[98:99]
	global_load_dwordx4 v[146:149], v[98:99], off offset:16
	global_load_dwordx4 v[150:153], v[98:99], off
	global_load_dwordx4 v[154:157], v[98:99], off offset:528
	global_load_dwordx4 v[158:161], v[98:99], off offset:512
	v_lshlrev_b64 v[98:99], 13, v[202:203]
	v_lshl_add_u64 v[98:99], v[180:181], 0, v[98:99]
	global_load_dwordx4 v[130:133], v[98:99], off offset:16
	global_load_dwordx4 v[138:141], v[98:99], off
	global_load_dwordx4 v[106:109], v[98:99], off offset:528
	global_load_dwordx4 v[114:117], v[98:99], off offset:512
	global_load_dwordx4 v[134:137], v[182:183], off offset:16
	global_load_dwordx4 v[142:145], v[182:183], off
	global_load_dwordx4 v[122:125], v[184:185], off offset:16
	global_load_dwordx4 v[126:129], v[184:185], off
	global_load_dwordx4 v[110:113], v[182:183], off offset:528
	global_load_dwordx4 v[118:121], v[182:183], off offset:512
	global_load_dwordx4 v[98:101], v[184:185], off offset:528
	global_load_dwordx4 v[102:105], v[184:185], off offset:512
	s_waitcnt vmcnt(6)
	v_pk_fma_f32 v[94:95], v[94:95], v[142:143], v[150:151]
	v_lshlrev_b64 v[150:151], 12, v[204:205]
	v_bfe_u32 v151, v150, 12, 4
	v_lshl_add_u32 v150, v151, 6, v150
	v_lshlrev_b32_e32 v151, 12, v151
	v_sub_u32_e32 v150, v150, v151
	v_mov_b32_e32 v151, 0
	v_pk_fma_f32 v[96:97], v[96:97], v[144:145], v[152:153]
	v_pk_fma_f32 v[148:149], v[92:93], v[136:137], v[148:149]
	v_pk_fma_f32 v[146:147], v[90:91], v[134:135], v[146:147]
	v_lshl_add_u64 v[150:151], s[10:11], 0, v[150:151]
	v_cvt_pk_f16_f32 v93, v148, v149
	v_cvt_pk_f16_f32 v91, v96, v97
	v_cvt_pk_f16_f32 v92, v146, v147
	v_cvt_pk_f16_f32 v90, v94, v95
	v_lshl_add_u64 v[150:151], v[198:199], 1, v[150:151]
	v_lshl_add_u64 v[150:151], v[150:151], 0, s[100:101]
	global_store_dwordx4 v[150:151], v[90:93], off
	v_mul_f32_e32 v0, v95, v95
	v_fmac_f32_e32 v0, v94, v94
	v_mul_f32_e32 v90, v97, v97
	v_fmac_f32_e32 v90, v96, v96
	v_add_f32_e32 v0, v0, v90
	v_mul_f32_e32 v90, v147, v147
	v_mul_f32_e32 v91, v149, v149
	v_fmac_f32_e32 v90, v146, v146
	v_fmac_f32_e32 v91, v148, v148
	v_add_f32_e32 v90, v90, v91
	v_add_f32_e32 v0, v0, v90
	s_waitcnt vmcnt(5)
; __device__ __forceinline__ float bperm(float v, int src_lane) { return __int_as_float(__builtin_amdgcn_ds_bpermute(src_lane << 2, __float_as_int(v))); }
; __device__ __forceinline__ u32x4 pack8(const f32x4 a, const f32x4 b) { u32x4 w; w.x = cvt_pk_bf16(a.x, a.y); w.y = cvt_pk_bf16(a.z, a.w); w.z = cvt_pk_bf16(b.x, b.y); w.w = cvt_pk_bf16(b.z, b.w); return w; }
; __host__ __device__ __forceinline__ size_t xs_off(int row, int col) { return (size_t)(row >> 8) * (256 * D) + (size_t)(col >> 6) * (256 * 64) + (size_t)((row & 255) * 64 + (col & 63)); }
;     template <bool INF32, int M0, int M1> __device__ __forceinline__ void half(f32x4 (&acc)[2][2][4][2], int ai, int b, int row0, int col, int pn, int wc, int fr, int fq) const {
;     ...
;         for (int m = M0; m < M1; ++m) { const int row = row0 + ai * 128 + m * 16; float ss = 0.f;
; #pragma unroll
;             for (int bj = 0; bj < 2; ++bj) { const size_t o = (size_t)row * D + col + bj * 128;
;                 const f32x4 x0 = xv[m][bj][0] + gt[bj][0] * acc[ai][bj][m][0], x1 = xv[m][bj][1] + gt[bj][1] * acc[ai][bj][m][1];
;                 if (out_f32) { *(f32x4*)((float*)xout + o) = x0; *(f32x4*)((float*)xout + o + 4) = x1; }
;                 else { const f32x8_t ff = {x0.x, x0.y, x0.z, x0.w, x1.x, x1.y, x1.z, x1.w}; *(f16x8_t*)((bf16_t*)xout + o) = __builtin_convertvector(ff, f16x8_t); }
;                 ss += ((x0.x * x0.x + x0.y * x0.y) + (x0.z * x0.z + x0.w * x0.w)) + ((x1.x * x1.x + x1.y * x1.y) + (x1.z * x1.z + x1.w * x1.w));
;                 if (XS) *(u32x4*)(XS + xs_off(row0, col) + (ai * 128 + m * 16) * 64 + bj * (2 * 256 * 64)) = pack8(x0 * gs[bj][0], x1 * gs[bj][1]); }
;             { const int ln = fr + 16 * fq; ss += bperm(ss, ln ^ 16); ss += bperm(ss, ln ^ 32); }
;             if (fq == 0) RSS[(size_t)row * 32 + pn * 4 + wc] = ss; }
	v_pk_mul_f32 v[90:91], v[128:129], v[96:97]
	v_pk_mul_f32 v[92:93], v[126:127], v[94:95]
	s_movk_i32 s12, 0x1000
	v_pk_mul_f32 v[94:95], v[122:123], v[146:147]
	v_cvt_pk_bf16_f32 v92, v92, v93
	v_cvt_pk_bf16_f32 v93, v90, v91
	v_add_co_u32_e32 v90, vcc, s12, v178
	v_pk_mul_f32 v[96:97], v[124:125], v[148:149]
	v_cvt_pk_bf16_f32 v94, v94, v95
	s_nop 0
	v_addc_co_u32_e32 v91, vcc, 0, v179, vcc
	v_cvt_pk_bf16_f32 v95, v96, v97
	global_store_dwordx4 v[90:91], v[92:95], off
	s_waitcnt vmcnt(4)
	v_pk_fma_f32 v[88:89], v[88:89], v[120:121], v[160:161]
	v_pk_fma_f32 v[86:87], v[86:87], v[118:119], v[158:159]
	v_pk_fma_f32 v[92:93], v[84:85], v[112:113], v[156:157]
	v_pk_fma_f32 v[94:95], v[82:83], v[110:111], v[154:155]
	v_cvt_pk_f16_f32 v85, v92, v93
	v_cvt_pk_f16_f32 v83, v88, v89
	v_cvt_pk_f16_f32 v84, v94, v95
	v_cvt_pk_f16_f32 v82, v86, v87
	global_store_dwordx4 v[150:151], v[82:85], off offset:1024
	s_nop 1
	v_mul_f32_e32 v82, v87, v87
	v_mul_f32_e32 v83, v89, v89
	v_fmac_f32_e32 v82, v86, v86
	v_fmac_f32_e32 v83, v88, v88
	v_add_f32_e32 v82, v82, v83
	v_mul_f32_e32 v83, v95, v95
	v_mul_f32_e32 v84, v93, v93
	v_fmac_f32_e32 v83, v94, v94
	v_fmac_f32_e32 v84, v92, v92
	v_add_f32_e32 v83, v83, v84
	v_add_f32_e32 v82, v82, v83
	v_add_f32_e32 v0, v0, v82
	s_waitcnt vmcnt(3)
	v_pk_mul_f32 v[82:83], v[104:105], v[88:89]
	v_pk_mul_f32 v[84:85], v[102:103], v[86:87]
	v_pk_mul_f32 v[88:89], v[100:101], v[92:93]
	v_cvt_pk_bf16_f32 v84, v84, v85
	v_cvt_pk_bf16_f32 v85, v82, v83
	ds_bpermute_b32 v82, v245, v0
	v_pk_mul_f32 v[86:87], v[98:99], v[94:95]
	s_waitcnt lgkmcnt(0)
	v_add_f32_e32 v0, v0, v82
	ds_bpermute_b32 v82, v244, v0
	v_cvt_pk_bf16_f32 v86, v86, v87
	v_cvt_pk_bf16_f32 v87, v88, v89
	v_add_co_u32_e32 v88, vcc, 0x11000, v178
	s_nop 1
	v_addc_co_u32_e32 v89, vcc, 0, v179, vcc
	global_store_dwordx4 v[88:89], v[84:87], off
	s_and_saveexec_b64 s[30:31], s[28:29]
	s_cbranch_execz .LBB0_1156
	v_lshlrev_b64 v[84:85], 7, v[204:205]
	v_lshl_add_u64 v[84:85], s[42:43], 0, v[84:85]
	v_lshl_add_u64 v[84:85], s[34:35], 2, v[84:85]
	s_lshl_b32 s44, s71, 2
	v_lshl_add_u64 v[84:85], v[84:85], 0, s[44:45]
	s_waitcnt lgkmcnt(0)
	v_add_f32_e32 v0, v0, v82
	global_store_dword v[84:85], v0, off
.LBB0_1156:
	s_or_b64 exec, exec, s[30:31]
	v_lshlrev_b64 v[86:87], 12, v[202:203]
	v_bfe_u32 v87, v86, 12, 4
	v_lshl_add_u32 v86, v87, 6, v86
	v_lshlrev_b32_e32 v87, 12, v87
	v_sub_u32_e32 v86, v86, v87
	v_mov_b32_e32 v87, 0
	v_pk_fma_f32 v[80:81], v[80:81], v[144:145], v[140:141]
	v_pk_fma_f32 v[78:79], v[78:79], v[142:143], v[138:139]
	s_waitcnt lgkmcnt(0)
	v_pk_fma_f32 v[82:83], v[76:77], v[136:137], v[132:133]
	v_pk_fma_f32 v[84:85], v[74:75], v[134:135], v[130:131]
	v_lshl_add_u64 v[86:87], s[10:11], 0, v[86:87]
	v_cvt_pk_f16_f32 v77, v82, v83
	v_cvt_pk_f16_f32 v75, v80, v81
	v_cvt_pk_f16_f32 v74, v78, v79
	v_cvt_pk_f16_f32 v76, v84, v85
	v_lshl_add_u64 v[86:87], v[198:199], 1, v[86:87]
	v_lshl_add_u64 v[86:87], v[86:87], 0, s[100:101]
	global_store_dwordx4 v[86:87], v[74:77], off
	v_mul_f32_e32 v0, v79, v79
	v_fmac_f32_e32 v0, v78, v78
	v_mul_f32_e32 v74, v81, v81
	v_fmac_f32_e32 v74, v80, v80
	v_add_f32_e32 v0, v0, v74
	v_mul_f32_e32 v74, v85, v85
	v_mul_f32_e32 v75, v83, v83
	v_fmac_f32_e32 v74, v84, v84
	v_fmac_f32_e32 v75, v82, v82
	v_add_f32_e32 v74, v74, v75
	v_add_f32_e32 v0, v0, v74
	v_pk_mul_f32 v[76:77], v[128:129], v[80:81]
	v_pk_mul_f32 v[74:75], v[126:127], v[78:79]
	v_pk_mul_f32 v[78:79], v[124:125], v[82:83]
	v_pk_mul_f32 v[80:81], v[122:123], v[84:85]
	v_cvt_pk_bf16_f32 v74, v74, v75
	v_cvt_pk_bf16_f32 v75, v76, v77
	v_pk_fma_f32 v[72:73], v[72:73], v[120:121], v[116:117]
	v_cvt_pk_bf16_f32 v76, v80, v81
	v_cvt_pk_bf16_f32 v77, v78, v79
	global_store_dwordx4 v[90:91], v[74:77], off offset:2048
	v_pk_fma_f32 v[70:71], v[70:71], v[118:119], v[114:115]
	s_nop 0
	v_pk_fma_f32 v[74:75], v[68:69], v[112:113], v[108:109]
	v_pk_fma_f32 v[76:77], v[66:67], v[110:111], v[106:107]
	v_cvt_pk_f16_f32 v69, v74, v75
	v_cvt_pk_f16_f32 v67, v72, v73
	v_cvt_pk_f16_f32 v66, v70, v71
	v_cvt_pk_f16_f32 v68, v76, v77
	global_store_dwordx4 v[86:87], v[66:69], off offset:1024
	s_nop 1
	v_mul_f32_e32 v66, v71, v71
	v_mul_f32_e32 v67, v73, v73
	v_fmac_f32_e32 v66, v70, v70
	v_fmac_f32_e32 v67, v72, v72
	v_add_f32_e32 v66, v66, v67
	v_mul_f32_e32 v67, v77, v77
	v_mul_f32_e32 v68, v75, v75
	v_fmac_f32_e32 v67, v76, v76
	v_fmac_f32_e32 v68, v74, v74
	v_add_f32_e32 v67, v67, v68
	v_add_f32_e32 v66, v66, v67
	v_add_f32_e32 v0, v0, v66
	v_pk_mul_f32 v[66:67], v[104:105], v[72:73]
	v_pk_mul_f32 v[68:69], v[102:103], v[70:71]
	v_pk_mul_f32 v[72:73], v[100:101], v[74:75]
	v_cvt_pk_bf16_f32 v68, v68, v69
	v_cvt_pk_bf16_f32 v69, v66, v67
	ds_bpermute_b32 v66, v245, v0
	v_pk_mul_f32 v[70:71], v[98:99], v[76:77]
	s_waitcnt lgkmcnt(0)
	v_add_f32_e32 v0, v0, v66
	ds_bpermute_b32 v66, v244, v0
	v_cvt_pk_bf16_f32 v70, v70, v71
	v_cvt_pk_bf16_f32 v71, v72, v73
	v_add_co_u32_e32 v72, vcc, 0x11000, v178
	s_nop 1
	v_addc_co_u32_e32 v73, vcc, 0, v179, vcc
	global_store_dwordx4 v[72:73], v[68:71], off offset:2048
	s_and_saveexec_b64 s[30:31], s[28:29]
	s_cbranch_execz .LBB0_1158
	v_lshlrev_b64 v[68:69], 7, v[202:203]
	v_lshl_add_u64 v[68:69], s[42:43], 0, v[68:69]
	v_lshl_add_u64 v[68:69], s[34:35], 2, v[68:69]
	s_lshl_b32 s44, s71, 2
	v_lshl_add_u64 v[68:69], v[68:69], 0, s[44:45]
	s_waitcnt lgkmcnt(0)
	v_add_f32_e32 v0, v0, v66
	global_store_dword v[68:69], v0, off
;     template <bool INF32, int M0, int M1> __device__ __forceinline__ void half(f32x4 (&acc)[2][2][4][2], int ai, int b, int row0, int col, int pn, int wc, int fr, int fq) const {
;     ...
;         if (INF32) {
; #pragma unroll
;             for (int m = M0; m < M1; ++m)
; #pragma unroll
;                 for (int bj = 0; bj < 2; ++bj) { const float* p = (const float*)xin + (size_t)(row0 + ai * 128 + m * 16) * D + col + bj * 128; xv[m][bj][0] = *(const f32x4*)p; xv[m][bj][1] = *(const f32x4*)(p + 4); }
;         } else {
;             f16x8_t hh[4][2];
; #pragma unroll
;             for (int m = M0; m < M1; ++m)
; #pragma unroll
;                 for (int bj = 0; bj < 2; ++bj) hh[m][bj] = *(const f16x8_t*)((const bf16_t*)xin + (size_t)(row0 + ai * 128 + m * 16) * D + col + bj * 128);
; #pragma unroll
;             for (int m = M0; m < M1; ++m)
; #pragma unroll
;                 for (int bj = 0; bj < 2; ++bj) { const f32x8_t ff = __builtin_convertvector(hh[m][bj], f32x8_t); xv[m][bj][0] = (f32x4){ff[0], ff[1], ff[2], ff[3]}; xv[m][bj][1] = (f32x4){ff[4], ff[5], ff[6], ff[7]}; }
;         }
;         f32x4 gt[2][2], gs[2][2];
; #pragma unroll
;         for (int bj = 0; bj < 2; ++bj)
; #pragma unroll
;             for (int n = 0; n < 2; ++n) { gt[bj][n] = *(const f32x4*)(gate + (size_t)b * 6 * D + col + bj * 128 + n * 4); gs[bj][n] = XS ? *(const f32x4*)(GS + (size_t)b * D + col + bj * 128 + n * 4) : (f32x4){0.f, 0.f, 0.f, 0.f}; }
;         __builtin_amdgcn_sched_barrier(0);
; #pragma unroll
;         for (int m = M0; m < M1; ++m) { const int row = row0 + ai * 128 + m * 16; float ss = 0.f;
; #pragma unroll
;             for (int bj = 0; bj < 2; ++bj) { const size_t o = (size_t)row * D + col + bj * 128;
;                 const f32x4 x0 = xv[m][bj][0] + gt[bj][0] * acc[ai][bj][m][0], x1 = xv[m][bj][1] + gt[bj][1] * acc[ai][bj][m][1];
;                 if (out_f32) { *(f32x4*)((float*)xout + o) = x0; *(f32x4*)((float*)xout + o + 4) = x1; }
;                 else { const f32x8_t ff = {x0.x, x0.y, x0.z, x0.w, x1.x, x1.y, x1.z, x1.w}; *(f16x8_t*)((bf16_t*)xout + o) = __builtin_convertvector(ff, f16x8_t); }
;                 ss += ((x0.x * x0.x + x0.y * x0.y) + (x0.z * x0.z + x0.w * x0.w)) + ((x1.x * x1.x + x1.y * x1.y) + (x1.z * x1.z + x1.w * x1.w));
.LBB0_1158:
	s_or_b64 exec, exec, s[30:31]
	v_add_u32_e32 v114, 0x80, v200
	v_ashrrev_i32_e32 v115, 31, v114
	s_waitcnt lgkmcnt(0)
	v_lshlrev_b64 v[66:67], 13, v[114:115]
	v_add_u32_e32 v116, 0x90, v200
	v_lshl_add_u64 v[66:67], v[180:181], 0, v[66:67]
	v_ashrrev_i32_e32 v117, 31, v116
	global_load_dwordx4 v[118:121], v[66:67], off offset:16
	global_load_dwordx4 v[122:125], v[66:67], off
	global_load_dwordx4 v[126:129], v[66:67], off offset:528
	global_load_dwordx4 v[130:133], v[66:67], off offset:512
	v_lshlrev_b64 v[66:67], 13, v[116:117]
	v_lshl_add_u64 v[66:67], v[180:181], 0, v[66:67]
	global_load_dwordx4 v[98:101], v[66:67], off offset:16
	global_load_dwordx4 v[106:109], v[66:67], off
	global_load_dwordx4 v[74:77], v[66:67], off offset:528
	global_load_dwordx4 v[82:85], v[66:67], off offset:512
	global_load_dwordx4 v[102:105], v[182:183], off offset:16
	global_load_dwordx4 v[110:113], v[182:183], off
	global_load_dwordx4 v[90:93], v[184:185], off offset:16
	global_load_dwordx4 v[94:97], v[184:185], off
	global_load_dwordx4 v[78:81], v[182:183], off offset:528
	global_load_dwordx4 v[86:89], v[182:183], off offset:512
	global_load_dwordx4 v[66:69], v[184:185], off offset:528
	global_load_dwordx4 v[70:73], v[184:185], off offset:512
	s_waitcnt vmcnt(6)
	v_pk_fma_f32 v[62:63], v[62:63], v[110:111], v[122:123]
	v_lshlrev_b64 v[122:123], 12, v[114:115]
	v_bfe_u32 v123, v122, 12, 4
	v_lshl_add_u32 v122, v123, 6, v122
	v_lshlrev_b32_e32 v123, 12, v123
	v_sub_u32_e32 v122, v122, v123
	v_mov_b32_e32 v123, 0
	v_pk_fma_f32 v[64:65], v[64:65], v[112:113], v[124:125]
	v_pk_fma_f32 v[120:121], v[60:61], v[104:105], v[120:121]
	v_pk_fma_f32 v[118:119], v[58:59], v[102:103], v[118:119]
	v_lshl_add_u64 v[122:123], s[10:11], 0, v[122:123]
	v_cvt_pk_f16_f32 v61, v120, v121
	v_cvt_pk_f16_f32 v59, v64, v65
	v_cvt_pk_f16_f32 v60, v118, v119
	v_cvt_pk_f16_f32 v58, v62, v63
	v_lshl_add_u64 v[122:123], v[198:199], 1, v[122:123]
	v_lshl_add_u64 v[122:123], v[122:123], 0, s[100:101]
	global_store_dwordx4 v[122:123], v[58:61], off
	v_mul_f32_e32 v0, v63, v63
	v_fmac_f32_e32 v0, v62, v62
	v_mul_f32_e32 v58, v65, v65
	v_fmac_f32_e32 v58, v64, v64
	v_add_f32_e32 v0, v0, v58
	v_mul_f32_e32 v58, v119, v119
	v_mul_f32_e32 v59, v121, v121
	v_fmac_f32_e32 v58, v118, v118
	v_fmac_f32_e32 v59, v120, v120
	v_add_f32_e32 v58, v58, v59
	v_add_f32_e32 v0, v0, v58
	s_waitcnt vmcnt(5)
	v_pk_mul_f32 v[58:59], v[96:97], v[64:65]
	v_pk_mul_f32 v[60:61], v[94:95], v[62:63]
	v_pk_mul_f32 v[62:63], v[90:91], v[118:119]
	v_cvt_pk_bf16_f32 v60, v60, v61
	v_cvt_pk_bf16_f32 v61, v58, v59
	v_add_co_u32_e32 v58, vcc, s60, v178
	v_pk_mul_f32 v[64:65], v[92:93], v[120:121]
	v_cvt_pk_bf16_f32 v62, v62, v63
	s_nop 0
	v_addc_co_u32_e32 v59, vcc, 0, v179, vcc
	v_cvt_pk_bf16_f32 v63, v64, v65
	global_store_dwordx4 v[58:59], v[60:63], off
	s_waitcnt vmcnt(4)
	v_pk_fma_f32 v[56:57], v[56:57], v[88:89], v[132:133]
	v_pk_fma_f32 v[54:55], v[54:55], v[86:87], v[130:131]
	v_pk_fma_f32 v[60:61], v[52:53], v[80:81], v[128:129]
	v_pk_fma_f32 v[62:63], v[50:51], v[78:79], v[126:127]
	v_cvt_pk_f16_f32 v53, v60, v61
	v_cvt_pk_f16_f32 v51, v56, v57
	v_cvt_pk_f16_f32 v52, v62, v63
	v_cvt_pk_f16_f32 v50, v54, v55
	global_store_dwordx4 v[122:123], v[50:53], off offset:1024
	s_nop 1
	v_mul_f32_e32 v50, v55, v55
	v_mul_f32_e32 v51, v57, v57
	v_fmac_f32_e32 v50, v54, v54
	v_fmac_f32_e32 v51, v56, v56
	v_add_f32_e32 v50, v50, v51
	v_mul_f32_e32 v51, v63, v63
	v_mul_f32_e32 v52, v61, v61
	v_fmac_f32_e32 v51, v62, v62
	v_fmac_f32_e32 v52, v60, v60
	v_add_f32_e32 v51, v51, v52
	v_add_f32_e32 v50, v50, v51
	v_add_f32_e32 v0, v0, v50
	s_waitcnt vmcnt(3)
	v_pk_mul_f32 v[50:51], v[72:73], v[56:57]
	v_pk_mul_f32 v[52:53], v[70:71], v[54:55]
	v_pk_mul_f32 v[56:57], v[68:69], v[60:61]
	v_cvt_pk_bf16_f32 v52, v52, v53
	v_cvt_pk_bf16_f32 v53, v50, v51
	ds_bpermute_b32 v50, v245, v0
	v_pk_mul_f32 v[54:55], v[66:67], v[62:63]
	s_waitcnt lgkmcnt(0)
	v_add_f32_e32 v0, v0, v50
	ds_bpermute_b32 v50, v244, v0
	v_cvt_pk_bf16_f32 v54, v54, v55
	v_cvt_pk_bf16_f32 v55, v56, v57
	v_add_co_u32_e32 v56, vcc, 0x14000, v178
	s_nop 1
	v_addc_co_u32_e32 v57, vcc, 0, v179, vcc
	global_store_dwordx4 v[56:57], v[52:55], off
	s_and_saveexec_b64 s[30:31], s[28:29]
	s_cbranch_execz .LBB0_1160
	v_lshlrev_b64 v[52:53], 7, v[114:115]
	v_lshl_add_u64 v[52:53], s[42:43], 0, v[52:53]
	v_lshl_add_u64 v[52:53], s[34:35], 2, v[52:53]
	s_lshl_b32 s44, s71, 2
	v_lshl_add_u64 v[52:53], v[52:53], 0, s[44:45]
	s_waitcnt lgkmcnt(0)
	v_add_f32_e32 v0, v0, v50
	global_store_dword v[52:53], v0, off
;     template <bool INF32, int M0, int M1> __device__ __forceinline__ void half(f32x4 (&acc)[2][2][4][2], int ai, int b, int row0, int col, int pn, int wc, int fr, int fq) const {
;     ...
;         if (INF32) {
; #pragma unroll
;             for (int m = M0; m < M1; ++m)
; #pragma unroll
;                 for (int bj = 0; bj < 2; ++bj) { const float* p = (const float*)xin + (size_t)(row0 + ai * 128 + m * 16) * D + col + bj * 128; xv[m][bj][0] = *(const f32x4*)p; xv[m][bj][1] = *(const f32x4*)(p + 4); }
;         } else {
;             f16x8_t hh[4][2];
; #pragma unroll
;             for (int m = M0; m < M1; ++m)
; #pragma unroll
;                 for (int bj = 0; bj < 2; ++bj) hh[m][bj] = *(const f16x8_t*)((const bf16_t*)xin + (size_t)(row0 + ai * 128 + m * 16) * D + col + bj * 128);
; #pragma unroll
;             for (int m = M0; m < M1; ++m)
; #pragma unroll
;                 for (int bj = 0; bj < 2; ++bj) { const f32x8_t ff = __builtin_convertvector(hh[m][bj], f32x8_t); xv[m][bj][0] = (f32x4){ff[0], ff[1], ff[2], ff[3]}; xv[m][bj][1] = (f32x4){ff[4], ff[5], ff[6], ff[7]}; }
;         }
;         f32x4 gt[2][2], gs[2][2];
; #pragma unroll
;         for (int bj = 0; bj < 2; ++bj)
; #pragma unroll
;             for (int n = 0; n < 2; ++n) { gt[bj][n] = *(const f32x4*)(gate + (size_t)b * 6 * D + col + bj * 128 + n * 4); gs[bj][n] = XS ? *(const f32x4*)(GS + (size_t)b * D + col + bj * 128 + n * 4) : (f32x4){0.f, 0.f, 0.f, 0.f}; }
;         __builtin_amdgcn_sched_barrier(0);
; #pragma unroll
;         for (int m = M0; m < M1; ++m) { const int row = row0 + ai * 128 + m * 16; float ss = 0.f;
; #pragma unroll
;             for (int bj = 0; bj < 2; ++bj) { const size_t o = (size_t)row * D + col + bj * 128;
;                 const f32x4 x0 = xv[m][bj][0] + gt[bj][0] * acc[ai][bj][m][0], x1 = xv[m][bj][1] + gt[bj][1] * acc[ai][bj][m][1];
;                 if (out_f32) { *(f32x4*)((float*)xout + o) = x0; *(f32x4*)((float*)xout + o + 4) = x1; }
;                 else { const f32x8_t ff = {x0.x, x0.y, x0.z, x0.w, x1.x, x1.y, x1.z, x1.w}; *(f16x8_t*)((bf16_t*)xout + o) = __builtin_convertvector(ff, f16x8_t); }
;                 ss += ((x0.x * x0.x + x0.y * x0.y) + (x0.z * x0.z + x0.w * x0.w)) + ((x1.x * x1.x + x1.y * x1.y) + (x1.z * x1.z + x1.w * x1.w));
.LBB0_1160:
	s_or_b64 exec, exec, s[30:31]
	v_lshlrev_b64 v[54:55], 12, v[116:117]
	v_bfe_u32 v55, v54, 12, 4
	v_lshl_add_u32 v54, v55, 6, v54
	v_lshlrev_b32_e32 v55, 12, v55
	v_sub_u32_e32 v54, v54, v55
	v_mov_b32_e32 v55, 0
	v_pk_fma_f32 v[48:49], v[48:49], v[112:113], v[108:109]
	v_pk_fma_f32 v[46:47], v[46:47], v[110:111], v[106:107]
	s_waitcnt lgkmcnt(0)
	v_pk_fma_f32 v[50:51], v[44:45], v[104:105], v[100:101]
	v_pk_fma_f32 v[52:53], v[42:43], v[102:103], v[98:99]
	v_lshl_add_u64 v[54:55], s[10:11], 0, v[54:55]
	v_cvt_pk_f16_f32 v45, v50, v51
	v_cvt_pk_f16_f32 v43, v48, v49
	v_cvt_pk_f16_f32 v42, v46, v47
	v_cvt_pk_f16_f32 v44, v52, v53
	v_lshl_add_u64 v[54:55], v[198:199], 1, v[54:55]
	v_lshl_add_u64 v[54:55], v[54:55], 0, s[100:101]
	global_store_dwordx4 v[54:55], v[42:45], off
	v_mul_f32_e32 v0, v47, v47
	v_fmac_f32_e32 v0, v46, v46
	v_mul_f32_e32 v42, v49, v49
	v_fmac_f32_e32 v42, v48, v48
	v_add_f32_e32 v0, v0, v42
	v_mul_f32_e32 v42, v53, v53
	v_mul_f32_e32 v43, v51, v51
	v_fmac_f32_e32 v42, v52, v52
	v_fmac_f32_e32 v43, v50, v50
	v_add_f32_e32 v42, v42, v43
	v_add_f32_e32 v0, v0, v42
	v_pk_mul_f32 v[44:45], v[96:97], v[48:49]
	v_pk_mul_f32 v[42:43], v[94:95], v[46:47]
	v_pk_mul_f32 v[46:47], v[92:93], v[50:51]
	v_pk_mul_f32 v[48:49], v[90:91], v[52:53]
	v_cvt_pk_bf16_f32 v42, v42, v43
	v_cvt_pk_bf16_f32 v43, v44, v45
	v_pk_fma_f32 v[40:41], v[40:41], v[88:89], v[84:85]
	v_cvt_pk_bf16_f32 v44, v48, v49
	v_cvt_pk_bf16_f32 v45, v46, v47
	global_store_dwordx4 v[58:59], v[42:45], off offset:2048
	v_pk_fma_f32 v[38:39], v[38:39], v[86:87], v[82:83]
	s_nop 0
	v_pk_fma_f32 v[42:43], v[36:37], v[80:81], v[76:77]
	v_pk_fma_f32 v[44:45], v[34:35], v[78:79], v[74:75]
	v_cvt_pk_f16_f32 v37, v42, v43
	v_cvt_pk_f16_f32 v35, v40, v41
	v_cvt_pk_f16_f32 v34, v38, v39
	v_cvt_pk_f16_f32 v36, v44, v45
	global_store_dwordx4 v[54:55], v[34:37], off offset:1024
	s_nop 1
	v_mul_f32_e32 v34, v39, v39
	v_mul_f32_e32 v35, v41, v41
	v_fmac_f32_e32 v34, v38, v38
	v_fmac_f32_e32 v35, v40, v40
	v_add_f32_e32 v34, v34, v35
	v_mul_f32_e32 v35, v45, v45
	v_mul_f32_e32 v36, v43, v43
	v_fmac_f32_e32 v35, v44, v44
	v_fmac_f32_e32 v36, v42, v42
	v_add_f32_e32 v35, v35, v36
	v_add_f32_e32 v34, v34, v35
	v_add_f32_e32 v0, v0, v34
	v_pk_mul_f32 v[34:35], v[72:73], v[40:41]
	v_pk_mul_f32 v[36:37], v[70:71], v[38:39]
	v_pk_mul_f32 v[40:41], v[68:69], v[42:43]
	v_cvt_pk_bf16_f32 v36, v36, v37
	v_cvt_pk_bf16_f32 v37, v34, v35
	ds_bpermute_b32 v34, v245, v0
	v_pk_mul_f32 v[38:39], v[66:67], v[44:45]
	s_waitcnt lgkmcnt(0)
	v_add_f32_e32 v0, v0, v34
	ds_bpermute_b32 v34, v244, v0
	v_cvt_pk_bf16_f32 v38, v38, v39
	v_cvt_pk_bf16_f32 v39, v40, v41
	v_add_co_u32_e32 v40, vcc, 0x14000, v178
	s_nop 1
	v_addc_co_u32_e32 v41, vcc, 0, v179, vcc
	global_store_dwordx4 v[40:41], v[36:39], off offset:2048
	s_and_saveexec_b64 s[30:31], s[28:29]
	s_cbranch_execz .LBB0_1162
	v_lshlrev_b64 v[36:37], 7, v[116:117]
	v_lshl_add_u64 v[36:37], s[42:43], 0, v[36:37]
	v_lshl_add_u64 v[36:37], s[34:35], 2, v[36:37]
	s_lshl_b32 s44, s71, 2
	v_lshl_add_u64 v[36:37], v[36:37], 0, s[44:45]
	s_waitcnt lgkmcnt(0)
	v_add_f32_e32 v0, v0, v34
	global_store_dword v[36:37], v0, off
.LBB0_1162:
	s_or_b64 exec, exec, s[30:31]
	v_or_b32_e32 v82, 32, v114
	v_ashrrev_i32_e32 v83, 31, v82
	s_waitcnt lgkmcnt(0)
	v_lshlrev_b64 v[34:35], 13, v[82:83]
	v_or_b32_e32 v218, 48, v114
	v_lshl_add_u64 v[34:35], v[180:181], 0, v[34:35]
	v_ashrrev_i32_e32 v219, 31, v218
	global_load_dwordx4 v[84:87], v[34:35], off offset:16
	global_load_dwordx4 v[88:91], v[34:35], off
	global_load_dwordx4 v[92:95], v[34:35], off offset:528
	global_load_dwordx4 v[96:99], v[34:35], off offset:512
	v_lshlrev_b64 v[34:35], 13, v[218:219]
	v_lshl_add_u64 v[34:35], v[180:181], 0, v[34:35]
	global_load_dwordx4 v[66:69], v[34:35], off offset:16
	global_load_dwordx4 v[74:77], v[34:35], off
	global_load_dwordx4 v[42:45], v[34:35], off offset:528
	global_load_dwordx4 v[50:53], v[34:35], off offset:512
	global_load_dwordx4 v[70:73], v[182:183], off offset:16
	global_load_dwordx4 v[78:81], v[182:183], off
	global_load_dwordx4 v[58:61], v[184:185], off offset:16
	global_load_dwordx4 v[62:65], v[184:185], off
	global_load_dwordx4 v[46:49], v[182:183], off offset:528
	global_load_dwordx4 v[54:57], v[182:183], off offset:512
	global_load_dwordx4 v[34:37], v[184:185], off offset:528
	global_load_dwordx4 v[38:41], v[184:185], off offset:512
	s_waitcnt vmcnt(6)
	v_pk_fma_f32 v[30:31], v[30:31], v[78:79], v[88:89]
	v_lshlrev_b64 v[88:89], 12, v[82:83]
	v_bfe_u32 v89, v88, 12, 4
	v_lshl_add_u32 v88, v89, 6, v88
	v_lshlrev_b32_e32 v89, 12, v89
	v_sub_u32_e32 v88, v88, v89
	v_mov_b32_e32 v89, 0
	v_pk_fma_f32 v[32:33], v[32:33], v[80:81], v[90:91]
	v_pk_fma_f32 v[86:87], v[28:29], v[72:73], v[86:87]
	v_pk_fma_f32 v[84:85], v[26:27], v[70:71], v[84:85]
	v_lshl_add_u64 v[88:89], s[10:11], 0, v[88:89]
	v_cvt_pk_f16_f32 v29, v86, v87
	v_cvt_pk_f16_f32 v27, v32, v33
	v_cvt_pk_f16_f32 v28, v84, v85
	v_cvt_pk_f16_f32 v26, v30, v31
	v_lshl_add_u64 v[88:89], v[198:199], 1, v[88:89]
	v_lshl_add_u64 v[88:89], v[88:89], 0, s[100:101]
	global_store_dwordx4 v[88:89], v[26:29], off
	v_mul_f32_e32 v0, v31, v31
	v_fmac_f32_e32 v0, v30, v30
	v_mul_f32_e32 v26, v33, v33
	v_fmac_f32_e32 v26, v32, v32
	v_add_f32_e32 v0, v0, v26
	v_mul_f32_e32 v26, v85, v85
	v_mul_f32_e32 v27, v87, v87
	v_fmac_f32_e32 v26, v84, v84
	v_fmac_f32_e32 v27, v86, v86
	v_add_f32_e32 v26, v26, v27
	v_add_f32_e32 v0, v0, v26
	s_waitcnt vmcnt(5)
; __device__ __forceinline__ float bperm(float v, int src_lane) { return __int_as_float(__builtin_amdgcn_ds_bpermute(src_lane << 2, __float_as_int(v))); }
; __device__ __forceinline__ u32x4 pack8(const f32x4 a, const f32x4 b) { u32x4 w; w.x = cvt_pk_bf16(a.x, a.y); w.y = cvt_pk_bf16(a.z, a.w); w.z = cvt_pk_bf16(b.x, b.y); w.w = cvt_pk_bf16(b.z, b.w); return w; }
; __host__ __device__ __forceinline__ size_t xs_off(int row, int col) { return (size_t)(row >> 8) * (256 * D) + (size_t)(col >> 6) * (256 * 64) + (size_t)((row & 255) * 64 + (col & 63)); }
;     template <bool INF32, int M0, int M1> __device__ __forceinline__ void half(f32x4 (&acc)[2][2][4][2], int ai, int b, int row0, int col, int pn, int wc, int fr, int fq) const {
;     ...
;         for (int m = M0; m < M1; ++m) { const int row = row0 + ai * 128 + m * 16; float ss = 0.f;
; #pragma unroll
;             for (int bj = 0; bj < 2; ++bj) { const size_t o = (size_t)row * D + col + bj * 128;
;                 const f32x4 x0 = xv[m][bj][0] + gt[bj][0] * acc[ai][bj][m][0], x1 = xv[m][bj][1] + gt[bj][1] * acc[ai][bj][m][1];
;                 if (out_f32) { *(f32x4*)((float*)xout + o) = x0; *(f32x4*)((float*)xout + o + 4) = x1; }
;                 else { const f32x8_t ff = {x0.x, x0.y, x0.z, x0.w, x1.x, x1.y, x1.z, x1.w}; *(f16x8_t*)((bf16_t*)xout + o) = __builtin_convertvector(ff, f16x8_t); }
;                 ss += ((x0.x * x0.x + x0.y * x0.y) + (x0.z * x0.z + x0.w * x0.w)) + ((x1.x * x1.x + x1.y * x1.y) + (x1.z * x1.z + x1.w * x1.w));
;                 if (XS) *(u32x4*)(XS + xs_off(row0, col) + (ai * 128 + m * 16) * 64 + bj * (2 * 256 * 64)) = pack8(x0 * gs[bj][0], x1 * gs[bj][1]); }
;             { const int ln = fr + 16 * fq; ss += bperm(ss, ln ^ 16); ss += bperm(ss, ln ^ 32); }
;             if (fq == 0) RSS[(size_t)row * 32 + pn * 4 + wc] = ss; }
	v_pk_mul_f32 v[26:27], v[64:65], v[32:33]
	v_pk_mul_f32 v[28:29], v[62:63], v[30:31]
	v_pk_mul_f32 v[30:31], v[58:59], v[84:85]
	v_cvt_pk_bf16_f32 v28, v28, v29
	v_cvt_pk_bf16_f32 v29, v26, v27
	v_add_co_u32_e32 v26, vcc, s82, v178
	v_pk_mul_f32 v[32:33], v[60:61], v[86:87]
	v_cvt_pk_bf16_f32 v30, v30, v31
	s_nop 0
	v_addc_co_u32_e32 v27, vcc, 0, v179, vcc
	v_cvt_pk_bf16_f32 v31, v32, v33
	global_store_dwordx4 v[26:27], v[28:31], off
	s_waitcnt vmcnt(4)
	v_pk_fma_f32 v[24:25], v[24:25], v[56:57], v[98:99]
	v_pk_fma_f32 v[22:23], v[22:23], v[54:55], v[96:97]
	v_pk_fma_f32 v[28:29], v[20:21], v[48:49], v[94:95]
	v_pk_fma_f32 v[30:31], v[18:19], v[46:47], v[92:93]
	v_cvt_pk_f16_f32 v21, v28, v29
	v_cvt_pk_f16_f32 v19, v24, v25
	v_cvt_pk_f16_f32 v20, v30, v31
	v_cvt_pk_f16_f32 v18, v22, v23
	global_store_dwordx4 v[88:89], v[18:21], off offset:1024
	s_nop 1
	v_mul_f32_e32 v18, v23, v23
	v_mul_f32_e32 v19, v25, v25
	v_fmac_f32_e32 v18, v22, v22
	v_fmac_f32_e32 v19, v24, v24
	v_add_f32_e32 v18, v18, v19
	v_mul_f32_e32 v19, v31, v31
	v_mul_f32_e32 v20, v29, v29
	v_fmac_f32_e32 v19, v30, v30
	v_fmac_f32_e32 v20, v28, v28
	v_add_f32_e32 v19, v19, v20
	v_add_f32_e32 v18, v18, v19
	v_add_f32_e32 v0, v0, v18
	s_waitcnt vmcnt(3)
	v_pk_mul_f32 v[18:19], v[40:41], v[24:25]
	v_pk_mul_f32 v[20:21], v[38:39], v[22:23]
	v_pk_mul_f32 v[24:25], v[36:37], v[28:29]
	v_cvt_pk_bf16_f32 v20, v20, v21
	v_cvt_pk_bf16_f32 v21, v18, v19
	ds_bpermute_b32 v18, v245, v0
	v_pk_mul_f32 v[22:23], v[34:35], v[30:31]
	s_waitcnt lgkmcnt(0)
	v_add_f32_e32 v0, v0, v18
	ds_bpermute_b32 v18, v244, v0
	v_cvt_pk_bf16_f32 v22, v22, v23
	v_cvt_pk_bf16_f32 v23, v24, v25
	v_add_co_u32_e32 v24, vcc, 0x15000, v178
	s_nop 1
	v_addc_co_u32_e32 v25, vcc, 0, v179, vcc
	global_store_dwordx4 v[24:25], v[20:23], off
	s_and_saveexec_b64 s[30:31], s[28:29]
	s_cbranch_execz .LBB0_1164
	v_lshlrev_b64 v[20:21], 7, v[82:83]
	v_lshl_add_u64 v[20:21], s[42:43], 0, v[20:21]
	v_lshl_add_u64 v[20:21], s[34:35], 2, v[20:21]
	s_lshl_b32 s44, s71, 2
	v_lshl_add_u64 v[20:21], v[20:21], 0, s[44:45]
	s_waitcnt lgkmcnt(0)
	v_add_f32_e32 v0, v0, v18
	global_store_dword v[20:21], v0, off
.LBB0_1164:
	s_or_b64 exec, exec, s[30:31]
	v_lshlrev_b64 v[22:23], 12, v[218:219]
	v_bfe_u32 v23, v22, 12, 4
	v_lshl_add_u32 v22, v23, 6, v22
	v_lshlrev_b32_e32 v23, 12, v23
	v_sub_u32_e32 v22, v22, v23
	v_mov_b32_e32 v23, 0
	v_pk_fma_f32 v[16:17], v[16:17], v[80:81], v[76:77]
	v_pk_fma_f32 v[14:15], v[14:15], v[78:79], v[74:75]
	s_waitcnt lgkmcnt(0)
	v_pk_fma_f32 v[18:19], v[12:13], v[72:73], v[68:69]
	v_pk_fma_f32 v[20:21], v[10:11], v[70:71], v[66:67]
	v_lshl_add_u64 v[22:23], s[10:11], 0, v[22:23]
	v_cvt_pk_f16_f32 v13, v18, v19
	v_cvt_pk_f16_f32 v11, v16, v17
	v_cvt_pk_f16_f32 v10, v14, v15
	v_cvt_pk_f16_f32 v12, v20, v21
	v_lshl_add_u64 v[22:23], v[198:199], 1, v[22:23]
	v_lshl_add_u64 v[22:23], v[22:23], 0, s[100:101]
	global_store_dwordx4 v[22:23], v[10:13], off
	v_pk_mul_f32 v[24:25], v[60:61], v[18:19]
	v_pk_mul_f32 v[28:29], v[58:59], v[20:21]
	v_pk_mul_f32 v[12:13], v[64:65], v[16:17]
	v_pk_mul_f32 v[10:11], v[62:63], v[14:15]
	v_pk_fma_f32 v[8:9], v[8:9], v[56:57], v[52:53]
	v_cvt_pk_bf16_f32 v10, v10, v11
	v_cvt_pk_bf16_f32 v11, v12, v13
	v_cvt_pk_bf16_f32 v12, v28, v29
	v_cvt_pk_bf16_f32 v13, v24, v25
	global_store_dwordx4 v[26:27], v[10:13], off offset:2048
	v_pk_fma_f32 v[6:7], v[6:7], v[54:55], v[50:51]
	s_nop 0
	v_pk_fma_f32 v[10:11], v[4:5], v[48:49], v[44:45]
	v_pk_fma_f32 v[12:13], v[2:3], v[46:47], v[42:43]
	v_cvt_pk_f16_f32 v5, v10, v11
	v_cvt_pk_f16_f32 v3, v8, v9
	v_cvt_pk_f16_f32 v2, v6, v7
	v_cvt_pk_f16_f32 v4, v12, v13
	global_store_dwordx4 v[22:23], v[2:5], off offset:1024
	s_nop 1
	v_mov_b32_e32 v4, v15
	v_mov_b32_e32 v5, v7
	v_mov_b32_e32 v2, v14
	v_mov_b32_e32 v3, v6
	v_pk_mul_f32 v[4:5], v[4:5], v[4:5]
	v_mov_b32_e32 v14, v17
	v_mov_b32_e32 v15, v9
	v_pk_fma_f32 v[2:3], v[2:3], v[2:3], v[4:5]
	v_mov_b32_e32 v4, v16
	v_mov_b32_e32 v5, v8
	v_pk_mul_f32 v[14:15], v[14:15], v[14:15]
	v_mov_b32_e32 v16, v19
	v_pk_fma_f32 v[4:5], v[4:5], v[4:5], v[14:15]
	v_mov_b32_e32 v14, v21
	v_mov_b32_e32 v15, v13
	v_pk_add_f32 v[2:3], v[2:3], v[4:5]
	v_mov_b32_e32 v4, v20
	v_mov_b32_e32 v5, v12
	v_pk_mul_f32 v[14:15], v[14:15], v[14:15]
	v_mov_b32_e32 v17, v11
	v_pk_fma_f32 v[4:5], v[4:5], v[4:5], v[14:15]
	v_mov_b32_e32 v14, v18
	v_mov_b32_e32 v15, v10
	v_pk_mul_f32 v[16:17], v[16:17], v[16:17]
	s_nop 0
	v_pk_fma_f32 v[14:15], v[14:15], v[14:15], v[16:17]
	s_nop 0
	v_pk_add_f32 v[4:5], v[4:5], v[14:15]
	s_nop 0
	v_pk_add_f32 v[2:3], v[2:3], v[4:5]
	v_pk_mul_f32 v[4:5], v[40:41], v[8:9]
	v_add_f32_e32 v0, v2, v3
	v_pk_mul_f32 v[2:3], v[38:39], v[6:7]
	v_pk_mul_f32 v[6:7], v[36:37], v[10:11]
	ds_bpermute_b32 v10, v245, v0
	v_pk_mul_f32 v[8:9], v[34:35], v[12:13]
	v_cvt_pk_bf16_f32 v2, v2, v3
	v_cvt_pk_bf16_f32 v3, v4, v5
	s_waitcnt lgkmcnt(0)
	v_add_f32_e32 v0, v0, v10
	ds_bpermute_b32 v130, v244, v0
	v_cvt_pk_bf16_f32 v4, v8, v9
	v_cvt_pk_bf16_f32 v5, v6, v7
	v_add_co_u32_e32 v6, vcc, 0x15000, v178
	s_nop 1
	v_addc_co_u32_e32 v7, vcc, 0, v179, vcc
	global_store_dwordx4 v[6:7], v[2:5], off offset:2048
	s_and_saveexec_b64 s[30:31], s[28:29]
	s_cbranch_execz .LBB0_1148

;     template <bool INF32, int M0, int M1> __device__ __forceinline__ void half(f32x4 (&acc)[2][2][4][2], int ai, int b, int row0, int col, int pn, int wc, int fr, int fq) const {
;     ...
;             for (int m = M0; m < M1; ++m)
; #pragma unroll
;                 for (int bj = 0; bj < 2; ++bj) hh[m][bj] = *(const f16x8_t*)((const bf16_t*)xin + (size_t)(row0 + ai * 128 + m * 16) * D + col + bj * 128);
; #pragma unroll
;             for (int m = M0; m < M1; ++m)
; #pragma unroll
;                 for (int bj = 0; bj < 2; ++bj) { const f32x8_t ff = __builtin_convertvector(hh[m][bj], f32x8_t); xv[m][bj][0] = (f32x4){ff[0], ff[1], ff[2], ff[3]}; xv[m][bj][1] = (f32x4){ff[4], ff[5], ff[6], ff[7]}; }
;         }
;         f32x4 gt[2][2], gs[2][2];
; #pragma unroll
;         for (int bj = 0; bj < 2; ++bj)
; #pragma unroll
;             for (int n = 0; n < 2; ++n) { gt[bj][n] = *(const f32x4*)(gate + (size_t)b * 6 * D + col + bj * 128 + n * 4); gs[bj][n] = XS ? *(const f32x4*)(GS + (size_t)b * D + col + bj * 128 + n * 4) : (f32x4){0.f, 0.f, 0.f, 0.f}; }
;         __builtin_amdgcn_sched_barrier(0);
; #pragma unroll
;         for (int m = M0; m < M1; ++m) { const int row = row0 + ai * 128 + m * 16; float ss = 0.f;
; #pragma unroll
;             for (int bj = 0; bj < 2; ++bj) { const size_t o = (size_t)row * D + col + bj * 128;
;                 const f32x4 x0 = xv[m][bj][0] + gt[bj][0] * acc[ai][bj][m][0], x1 = xv[m][bj][1] + gt[bj][1] * acc[ai][bj][m][1];
;                 if (out_f32) { *(f32x4*)((float*)xout + o) = x0; *(f32x4*)((float*)xout + o + 4) = x1; }
;                 else { const f32x8_t ff = {x0.x, x0.y, x0.z, x0.w, x1.x, x1.y, x1.z, x1.w}; *(f16x8_t*)((bf16_t*)xout + o) = __builtin_convertvector(ff, f16x8_t); }
;                 ss += ((x0.x * x0.x + x0.y * x0.y) + (x0.z * x0.z + x0.w * x0.w)) + ((x1.x * x1.x + x1.y * x1.y) + (x1.z * x1.z + x1.w * x1.w));
;                 if (XS) *(u32x4*)(XS + xs_off(row0, col) + (ai * 128 + m * 16) * 64 + bj * (2 * 256 * 64)) = pack8(x0 * gs[bj][0], x1 * gs[bj][1]); }
;             { const int ln = fr + 16 * fq; ss += bperm(ss, ln ^ 16); ss += bperm(ss, ln ^ 32); }
;             if (fq == 0) RSS[(size_t)row * 32 + pn * 4 + wc] = ss; }
;     }
;     __device__ __forceinline__ void operator()(f32x4 (&acc)[2][2][4][2], const pg8::Unit& u, int ui, int wr, int wc, int fr, int fq) const {
.LBB0_1451:
	s_mul_i32 s100, s86, 0x1e00
	s_mul_i32 s101, s70, 62
	s_add_u32 s100, s100, s101
	s_mov_b32 s101, 0
	s_lshl_b32 s10, s87, 8
	v_mbcnt_lo_u32_b32 v232, -1, 0
	v_mbcnt_hi_u32_b32 v232, -1, v232
	s_add_i32 s10, s10, s68
	v_and_b32_e32 v233, 15, v232
	v_ashrrev_i32_e32 v234, 4, v232
	v_or_b32_e32 v208, s10, v233
	v_lshl_add_u32 v0, v234, 3, s70
	v_lshl_add_u32 v202, s86, 8, v0
	v_or_b32_e32 v224, 16, v208
	v_ashrrev_i32_e32 v203, 31, v202
	v_ashrrev_i32_e32 v209, 31, v208
	v_ashrrev_i32_e32 v225, 31, v224
	v_or_b32_e32 v220, 32, v208
	v_or_b32_e32 v216, 48, v208
	s_ashr_i32 s8, s87, 4
	v_lshl_add_u64 v[210:211], v[202:203], 1, s[14:15]
	v_lshl_add_u64 v[210:211], v[210:211], 0, s[100:101]
	v_lshlrev_b64 v[228:229], 12, v[208:209]
	v_bfe_u32 v229, v228, 12, 4
	v_lshl_add_u32 v228, v229, 6, v228
	v_lshlrev_b32_e32 v229, 12, v229
	v_sub_u32_e32 v228, v228, v229
	v_mov_b32_e32 v229, 0
	v_lshlrev_b64 v[226:227], 12, v[224:225]
	v_bfe_u32 v227, v226, 12, 4
	v_lshl_add_u32 v226, v227, 6, v226
	v_lshlrev_b32_e32 v227, 12, v227
	v_sub_u32_e32 v226, v226, v227
	v_mov_b32_e32 v227, 0
	v_ashrrev_i32_e32 v221, 31, v220
	v_ashrrev_i32_e32 v217, 31, v216
	v_lshl_add_u64 v[134:135], v[210:211], 0, v[228:229]
	v_lshl_add_u64 v[130:131], v[210:211], 0, v[226:227]
	v_lshlrev_b64 v[222:223], 12, v[220:221]
	v_bfe_u32 v223, v222, 12, 4
	v_lshl_add_u32 v222, v223, 6, v222
	v_lshlrev_b32_e32 v223, 12, v223
	v_sub_u32_e32 v222, v222, v223
	v_mov_b32_e32 v223, 0
	v_lshlrev_b64 v[218:219], 12, v[216:217]
	v_bfe_u32 v219, v218, 12, 4
	v_lshl_add_u32 v218, v219, 6, v218
	v_lshlrev_b32_e32 v219, 12, v219
	v_sub_u32_e32 v218, v218, v219
	v_mov_b32_e32 v219, 0
	s_ashr_i32 s9, s8, 31
	s_mul_i32 s28, s8, 0xc000
	global_load_dwordx4 v[186:189], v[134:135], off offset:1024
	global_load_dwordx4 v[182:185], v[130:131], off
	v_lshl_add_u64 v[132:133], v[210:211], 0, v[222:223]
	global_load_dwordx4 v[178:181], v[130:131], off offset:1024
	global_load_dwordx4 v[174:177], v[132:133], off
	v_lshl_add_u64 v[130:131], v[210:211], 0, v[218:219]
	s_mul_hi_i32 s11, s8, 0xc000
	s_add_u32 s28, s51, s28
	global_load_dwordx4 v[170:173], v[132:133], off offset:1024
	global_load_dwordx4 v[158:161], v[130:131], off
	s_nop 0
	global_load_dwordx4 v[130:133], v[130:131], off offset:1024
	s_addc_u32 s29, s54, s11
	v_lshlrev_b64 v[136:137], 2, v[202:203]
	v_lshl_add_u64 v[204:205], s[28:29], 0, v[136:137]
	global_load_dwordx4 v[190:193], v[134:135], off
	global_load_dwordx4 v[162:165], v[204:205], off
	s_lshl_b64 s[8:9], s[8:9], 13
	s_add_u32 s8, s61, s8
	s_addc_u32 s9, s63, s9
	v_cndmask_b32_e64 v134, 0, 1, s[16:17]
	v_lshl_add_u64 v[206:207], s[8:9], 0, v[136:137]
	v_mov_b32_e32 v146, 0
	v_cmp_ne_u32_e64 s[8:9], 1, v134
	s_andn2_b64 vcc, exec, s[16:17]
	v_mov_b32_e32 v150, 0
	v_mov_b32_e32 v151, 0
	v_mov_b32_e32 v152, 0
	v_mov_b32_e32 v153, 0
	s_cbranch_vccnz .LBB0_1453
	global_load_dwordx4 v[150:153], v[206:207], off

; __device__ __forceinline__ float bperm(float v, int src_lane) { return __int_as_float(__builtin_amdgcn_ds_bpermute(src_lane << 2, __float_as_int(v))); }
; __device__ __forceinline__ u32x4 pack8(const f32x4 a, const f32x4 b) { u32x4 w; w.x = cvt_pk_bf16(a.x, a.y); w.y = cvt_pk_bf16(a.z, a.w); w.z = cvt_pk_bf16(b.x, b.y); w.w = cvt_pk_bf16(b.z, b.w); return w; }
; __host__ __device__ __forceinline__ size_t xs_off(int row, int col) { return (size_t)(row >> 8) * (256 * D) + (size_t)(col >> 6) * (256 * 64) + (size_t)((row & 255) * 64 + (col & 63)); }
;     template <bool INF32, int M0, int M1> __device__ __forceinline__ void half(f32x4 (&acc)[2][2][4][2], int ai, int b, int row0, int col, int pn, int wc, int fr, int fq) const {
;     ...
;         for (int m = M0; m < M1; ++m) { const int row = row0 + ai * 128 + m * 16; float ss = 0.f;
; #pragma unroll
;             for (int bj = 0; bj < 2; ++bj) { const size_t o = (size_t)row * D + col + bj * 128;
;                 const f32x4 x0 = xv[m][bj][0] + gt[bj][0] * acc[ai][bj][m][0], x1 = xv[m][bj][1] + gt[bj][1] * acc[ai][bj][m][1];
;                 if (out_f32) { *(f32x4*)((float*)xout + o) = x0; *(f32x4*)((float*)xout + o + 4) = x1; }
;                 else { const f32x8_t ff = {x0.x, x0.y, x0.z, x0.w, x1.x, x1.y, x1.z, x1.w}; *(f16x8_t*)((bf16_t*)xout + o) = __builtin_convertvector(ff, f16x8_t); }
;                 ss += ((x0.x * x0.x + x0.y * x0.y) + (x0.z * x0.z + x0.w * x0.w)) + ((x1.x * x1.x + x1.y * x1.y) + (x1.z * x1.z + x1.w * x1.w));
;                 if (XS) *(u32x4*)(XS + xs_off(row0, col) + (ai * 128 + m * 16) * 64 + bj * (2 * 256 * 64)) = pack8(x0 * gs[bj][0], x1 * gs[bj][1]); }
;             { const int ln = fr + 16 * fq; ss += bperm(ss, ln ^ 16); ss += bperm(ss, ln ^ 32); }
;             if (fq == 0) RSS[(size_t)row * 32 + pn * 4 + wc] = ss; }
.LBB0_1459:
	s_waitcnt vmcnt(0)
	v_cvt_f32_f16_sdwa v213, v192 dst_sel:DWORD dst_unused:UNUSED_PAD src0_sel:WORD_1
	v_cvt_f32_f16_sdwa v215, v193 dst_sel:DWORD dst_unused:UNUSED_PAD src0_sel:WORD_1
	v_cvt_f32_f16_sdwa v237, v190 dst_sel:DWORD dst_unused:UNUSED_PAD src0_sel:WORD_1
	v_cvt_f32_f16_sdwa v239, v191 dst_sel:DWORD dst_unused:UNUSED_PAD src0_sel:WORD_1
	v_cvt_f32_f16_e32 v212, v192
	v_cvt_f32_f16_e32 v214, v193
	v_cvt_f32_f16_e32 v236, v190
	v_cvt_f32_f16_e32 v238, v191
	v_ashrrev_i32_e32 v190, 6, v202
	s_ashr_i32 s10, s10, 8
	v_ashrrev_i32_e32 v191, 31, v190
	s_ashr_i32 s11, s10, 31
	v_lshlrev_b32_e32 v192, 6, v208
	v_and_b32_e32 v0, 56, v0
	s_movk_i32 s28, 0x33c0
	v_lshlrev_b64 v[190:191], 15, v[190:191]
	v_and_or_b32 v0, v192, s28, v0
	s_lshl_b64 s[10:11], s[10:11], 20
	v_pk_fma_f32 v[128:129], v[128:129], v[164:165], v[238:239]
	v_pk_fma_f32 v[126:127], v[126:127], v[162:163], v[236:237]
	v_pk_fma_f32 v[124:125], v[124:125], v[168:169], v[214:215]
	v_pk_fma_f32 v[122:123], v[122:123], v[166:167], v[212:213]
	v_lshl_add_u64 v[192:193], s[14:15], 0, v[228:229]
	v_lshl_add_u64 v[190:191], s[18:19], 0, v[190:191]
	v_cvt_pk_f16_f32 v215, v124, v125
	v_cvt_pk_f16_f32 v213, v128, v129
	v_cvt_pk_f16_f32 v214, v122, v123
	v_cvt_pk_f16_f32 v212, v126, v127
	v_lshl_add_u64 v[192:193], v[202:203], 1, v[192:193]
	v_lshl_add_u64 v[192:193], v[192:193], 0, s[100:101]
	s_and_b64 vcc, exec, s[8:9]
	v_lshl_add_u64 v[190:191], v[190:191], 0, s[10:11]
	v_lshlrev_b32_e32 v0, 1, v0
	global_store_dwordx4 v[192:193], v[212:215], off
	s_cbranch_vccnz .LBB0_1461
	s_nop 0
	v_pk_mul_f32 v[214:215], v[128:129], v[152:153]
	v_pk_mul_f32 v[212:213], v[126:127], v[150:151]
	v_pk_mul_f32 v[228:229], v[124:125], v[148:149]
	v_pk_mul_f32 v[236:237], v[122:123], v[146:147]
	v_cvt_pk_bf16_f32 v212, v212, v213
	v_cvt_pk_bf16_f32 v213, v214, v215
	s_nop 0
	v_cvt_pk_bf16_f32 v214, v236, v237
	v_cvt_pk_bf16_f32 v215, v228, v229
	v_lshl_add_u64 v[228:229], v[190:191], 0, v[0:1]
	global_store_dwordx4 v[228:229], v[212:215], off
.LBB0_1461:
	s_nop 1
	v_cvt_f32_f16_sdwa v213, v188 dst_sel:DWORD dst_unused:UNUSED_PAD src0_sel:WORD_1
	v_cvt_f32_f16_sdwa v215, v189 dst_sel:DWORD dst_unused:UNUSED_PAD src0_sel:WORD_1
	v_cvt_f32_f16_sdwa v229, v186 dst_sel:DWORD dst_unused:UNUSED_PAD src0_sel:WORD_1
	v_cvt_f32_f16_sdwa v237, v187 dst_sel:DWORD dst_unused:UNUSED_PAD src0_sel:WORD_1
	v_cvt_f32_f16_e32 v236, v187
	v_cvt_f32_f16_e32 v228, v186
	v_cvt_f32_f16_e32 v214, v189
	v_cvt_f32_f16_e32 v212, v188
	v_pk_fma_f32 v[120:121], v[120:121], v[144:145], v[236:237]
	v_pk_fma_f32 v[118:119], v[118:119], v[142:143], v[228:229]
	v_pk_fma_f32 v[116:117], v[116:117], v[156:157], v[214:215]
	v_pk_fma_f32 v[114:115], v[114:115], v[154:155], v[212:213]
	v_cvt_pk_f16_f32 v189, v116, v117
	v_cvt_pk_f16_f32 v187, v120, v121
	v_cvt_pk_f16_f32 v188, v114, v115
	v_cvt_pk_f16_f32 v186, v118, v119
	s_and_b64 vcc, exec, s[8:9]
	global_store_dwordx4 v[192:193], v[186:189], off offset:1024
	s_cbranch_vccnz .LBB0_1463
	s_nop 0
	v_pk_mul_f32 v[188:189], v[120:121], v[140:141]
	v_pk_mul_f32 v[186:187], v[118:119], v[138:139]
	v_pk_mul_f32 v[192:193], v[116:117], v[136:137]
	v_pk_mul_f32 v[212:213], v[114:115], v[134:135]
	v_cvt_pk_bf16_f32 v186, v186, v187
	v_cvt_pk_bf16_f32 v187, v188, v189
	s_nop 0
	v_cvt_pk_bf16_f32 v188, v212, v213
	v_cvt_pk_bf16_f32 v189, v192, v193
	v_lshl_add_u64 v[192:193], v[190:191], 0, v[0:1]
	v_add_co_u32_e32 v192, vcc, 0x10000, v192
	s_nop 1
	v_addc_co_u32_e32 v193, vcc, 0, v193, vcc
	global_store_dwordx4 v[192:193], v[186:189], off

; __device__ __forceinline__ float bperm(float v, int src_lane) { return __int_as_float(__builtin_amdgcn_ds_bpermute(src_lane << 2, __float_as_int(v))); }
; __device__ __forceinline__ u32x4 pack8(const f32x4 a, const f32x4 b) { u32x4 w; w.x = cvt_pk_bf16(a.x, a.y); w.y = cvt_pk_bf16(a.z, a.w); w.z = cvt_pk_bf16(b.x, b.y); w.w = cvt_pk_bf16(b.z, b.w); return w; }
; __host__ __device__ __forceinline__ size_t xs_off(int row, int col) { return (size_t)(row >> 8) * (256 * D) + (size_t)(col >> 6) * (256 * 64) + (size_t)((row & 255) * 64 + (col & 63)); }
;     template <bool INF32, int M0, int M1> __device__ __forceinline__ void half(f32x4 (&acc)[2][2][4][2], int ai, int b, int row0, int col, int pn, int wc, int fr, int fq) const {
;     ...
;         for (int m = M0; m < M1; ++m) { const int row = row0 + ai * 128 + m * 16; float ss = 0.f;
; #pragma unroll
;             for (int bj = 0; bj < 2; ++bj) { const size_t o = (size_t)row * D + col + bj * 128;
;                 const f32x4 x0 = xv[m][bj][0] + gt[bj][0] * acc[ai][bj][m][0], x1 = xv[m][bj][1] + gt[bj][1] * acc[ai][bj][m][1];
;                 if (out_f32) { *(f32x4*)((float*)xout + o) = x0; *(f32x4*)((float*)xout + o + 4) = x1; }
;                 else { const f32x8_t ff = {x0.x, x0.y, x0.z, x0.w, x1.x, x1.y, x1.z, x1.w}; *(f16x8_t*)((bf16_t*)xout + o) = __builtin_convertvector(ff, f16x8_t); }
;                 ss += ((x0.x * x0.x + x0.y * x0.y) + (x0.z * x0.z + x0.w * x0.w)) + ((x1.x * x1.x + x1.y * x1.y) + (x1.z * x1.z + x1.w * x1.w));
;                 if (XS) *(u32x4*)(XS + xs_off(row0, col) + (ai * 128 + m * 16) * 64 + bj * (2 * 256 * 64)) = pack8(x0 * gs[bj][0], x1 * gs[bj][1]); }
;             { const int ln = fr + 16 * fq; ss += bperm(ss, ln ^ 16); ss += bperm(ss, ln ^ 32); }
;             if (fq == 0) RSS[(size_t)row * 32 + pn * 4 + wc] = ss; }
.LBB0_1465:
	s_or_b64 exec, exec, s[30:31]
	s_waitcnt lgkmcnt(0)
	v_cvt_f32_f16_sdwa v115, v184 dst_sel:DWORD dst_unused:UNUSED_PAD src0_sel:WORD_1
	v_cvt_f32_f16_sdwa v117, v185 dst_sel:DWORD dst_unused:UNUSED_PAD src0_sel:WORD_1
	v_cvt_f32_f16_sdwa v119, v182 dst_sel:DWORD dst_unused:UNUSED_PAD src0_sel:WORD_1
	v_cvt_f32_f16_sdwa v121, v183 dst_sel:DWORD dst_unused:UNUSED_PAD src0_sel:WORD_1
	v_cvt_f32_f16_e32 v120, v183
	v_cvt_f32_f16_e32 v118, v182
	v_cvt_f32_f16_e32 v116, v185
	v_cvt_f32_f16_e32 v114, v184
	v_pk_fma_f32 v[112:113], v[112:113], v[164:165], v[120:121]
	v_pk_fma_f32 v[110:111], v[110:111], v[162:163], v[118:119]
	v_pk_fma_f32 v[108:109], v[108:109], v[168:169], v[116:117]
	v_pk_fma_f32 v[106:107], v[106:107], v[166:167], v[114:115]
	v_lshl_add_u64 v[114:115], s[14:15], 0, v[226:227]
	v_cvt_pk_f16_f32 v119, v108, v109
	v_cvt_pk_f16_f32 v117, v112, v113
	v_cvt_pk_f16_f32 v118, v106, v107
	v_cvt_pk_f16_f32 v116, v110, v111
	v_lshl_add_u64 v[114:115], v[202:203], 1, v[114:115]
	v_lshl_add_u64 v[114:115], v[114:115], 0, s[100:101]
	s_and_b64 vcc, exec, s[8:9]
	global_store_dwordx4 v[114:115], v[116:119], off
	s_cbranch_vccnz .LBB0_1467
	s_nop 0
	v_pk_mul_f32 v[118:119], v[112:113], v[152:153]
	v_pk_mul_f32 v[116:117], v[110:111], v[150:151]
	v_pk_mul_f32 v[120:121], v[108:109], v[148:149]
	v_pk_mul_f32 v[122:123], v[106:107], v[146:147]
	v_cvt_pk_bf16_f32 v116, v116, v117
	v_cvt_pk_bf16_f32 v117, v118, v119
	s_nop 0
	v_cvt_pk_bf16_f32 v118, v122, v123
	v_cvt_pk_bf16_f32 v119, v120, v121
	v_lshl_add_u64 v[120:121], v[190:191], 0, v[0:1]
	global_store_dwordx4 v[120:121], v[116:119], off offset:2048
.LBB0_1467:
	s_nop 1
	v_cvt_f32_f16_sdwa v117, v180 dst_sel:DWORD dst_unused:UNUSED_PAD src0_sel:WORD_1
	v_cvt_f32_f16_sdwa v119, v181 dst_sel:DWORD dst_unused:UNUSED_PAD src0_sel:WORD_1
	v_cvt_f32_f16_sdwa v121, v178 dst_sel:DWORD dst_unused:UNUSED_PAD src0_sel:WORD_1
	v_cvt_f32_f16_sdwa v123, v179 dst_sel:DWORD dst_unused:UNUSED_PAD src0_sel:WORD_1
	v_cvt_f32_f16_e32 v122, v179
	v_cvt_f32_f16_e32 v120, v178
	v_cvt_f32_f16_e32 v118, v181
	v_cvt_f32_f16_e32 v116, v180
	v_pk_fma_f32 v[104:105], v[104:105], v[144:145], v[122:123]
	v_pk_fma_f32 v[102:103], v[102:103], v[142:143], v[120:121]
	v_pk_fma_f32 v[100:101], v[100:101], v[156:157], v[118:119]
	v_pk_fma_f32 v[98:99], v[98:99], v[154:155], v[116:117]
	v_cvt_pk_f16_f32 v119, v100, v101
	v_cvt_pk_f16_f32 v117, v104, v105
	v_cvt_pk_f16_f32 v118, v98, v99
	v_cvt_pk_f16_f32 v116, v102, v103
	s_and_b64 vcc, exec, s[8:9]
	global_store_dwordx4 v[114:115], v[116:119], off offset:1024
	s_cbranch_vccnz .LBB0_1469
	s_nop 0
	v_pk_mul_f32 v[116:117], v[104:105], v[140:141]
	v_pk_mul_f32 v[114:115], v[102:103], v[138:139]
	v_pk_mul_f32 v[118:119], v[100:101], v[136:137]
	v_pk_mul_f32 v[120:121], v[98:99], v[134:135]
	v_cvt_pk_bf16_f32 v114, v114, v115
	v_cvt_pk_bf16_f32 v115, v116, v117
	s_nop 0
	v_cvt_pk_bf16_f32 v116, v120, v121
	v_cvt_pk_bf16_f32 v117, v118, v119
	v_lshl_add_u64 v[118:119], v[190:191], 0, v[0:1]
	v_add_co_u32_e32 v118, vcc, 0x10000, v118
	s_nop 1
	v_addc_co_u32_e32 v119, vcc, 0, v119, vcc
	global_store_dwordx4 v[118:119], v[114:117], off offset:2048

; __device__ __forceinline__ float bperm(float v, int src_lane) { return __int_as_float(__builtin_amdgcn_ds_bpermute(src_lane << 2, __float_as_int(v))); }
; __device__ __forceinline__ u32x4 pack8(const f32x4 a, const f32x4 b) { u32x4 w; w.x = cvt_pk_bf16(a.x, a.y); w.y = cvt_pk_bf16(a.z, a.w); w.z = cvt_pk_bf16(b.x, b.y); w.w = cvt_pk_bf16(b.z, b.w); return w; }
; __host__ __device__ __forceinline__ size_t xs_off(int row, int col) { return (size_t)(row >> 8) * (256 * D) + (size_t)(col >> 6) * (256 * 64) + (size_t)((row & 255) * 64 + (col & 63)); }
;     template <bool INF32, int M0, int M1> __device__ __forceinline__ void half(f32x4 (&acc)[2][2][4][2], int ai, int b, int row0, int col, int pn, int wc, int fr, int fq) const {
;     ...
;         for (int m = M0; m < M1; ++m) { const int row = row0 + ai * 128 + m * 16; float ss = 0.f;
; #pragma unroll
;             for (int bj = 0; bj < 2; ++bj) { const size_t o = (size_t)row * D + col + bj * 128;
;                 const f32x4 x0 = xv[m][bj][0] + gt[bj][0] * acc[ai][bj][m][0], x1 = xv[m][bj][1] + gt[bj][1] * acc[ai][bj][m][1];
;                 if (out_f32) { *(f32x4*)((float*)xout + o) = x0; *(f32x4*)((float*)xout + o + 4) = x1; }
;                 else { const f32x8_t ff = {x0.x, x0.y, x0.z, x0.w, x1.x, x1.y, x1.z, x1.w}; *(f16x8_t*)((bf16_t*)xout + o) = __builtin_convertvector(ff, f16x8_t); }
;                 ss += ((x0.x * x0.x + x0.y * x0.y) + (x0.z * x0.z + x0.w * x0.w)) + ((x1.x * x1.x + x1.y * x1.y) + (x1.z * x1.z + x1.w * x1.w));
;                 if (XS) *(u32x4*)(XS + xs_off(row0, col) + (ai * 128 + m * 16) * 64 + bj * (2 * 256 * 64)) = pack8(x0 * gs[bj][0], x1 * gs[bj][1]); }
;             { const int ln = fr + 16 * fq; ss += bperm(ss, ln ^ 16); ss += bperm(ss, ln ^ 32); }
;             if (fq == 0) RSS[(size_t)row * 32 + pn * 4 + wc] = ss; }
.LBB0_1471:
	s_or_b64 exec, exec, s[30:31]
	s_waitcnt lgkmcnt(0)
	v_cvt_f32_f16_sdwa v99, v176 dst_sel:DWORD dst_unused:UNUSED_PAD src0_sel:WORD_1
	v_cvt_f32_f16_sdwa v101, v177 dst_sel:DWORD dst_unused:UNUSED_PAD src0_sel:WORD_1
	v_cvt_f32_f16_sdwa v103, v174 dst_sel:DWORD dst_unused:UNUSED_PAD src0_sel:WORD_1
	v_cvt_f32_f16_sdwa v105, v175 dst_sel:DWORD dst_unused:UNUSED_PAD src0_sel:WORD_1
	v_cvt_f32_f16_e32 v104, v175
	v_cvt_f32_f16_e32 v102, v174
	v_cvt_f32_f16_e32 v100, v177
	v_cvt_f32_f16_e32 v98, v176
	v_pk_fma_f32 v[96:97], v[96:97], v[164:165], v[104:105]
	v_pk_fma_f32 v[94:95], v[94:95], v[162:163], v[102:103]
	v_pk_fma_f32 v[92:93], v[92:93], v[168:169], v[100:101]
	v_pk_fma_f32 v[90:91], v[90:91], v[166:167], v[98:99]
	v_lshl_add_u64 v[98:99], s[14:15], 0, v[222:223]
	v_cvt_pk_f16_f32 v103, v92, v93
	v_cvt_pk_f16_f32 v101, v96, v97
	v_cvt_pk_f16_f32 v102, v90, v91
	v_cvt_pk_f16_f32 v100, v94, v95
	v_lshl_add_u64 v[98:99], v[202:203], 1, v[98:99]
	v_lshl_add_u64 v[98:99], v[98:99], 0, s[100:101]
	s_and_b64 vcc, exec, s[8:9]
	global_store_dwordx4 v[98:99], v[100:103], off
	s_cbranch_vccnz .LBB0_1473
	s_nop 0
	v_pk_mul_f32 v[102:103], v[96:97], v[152:153]
	v_pk_mul_f32 v[100:101], v[94:95], v[150:151]
	v_pk_mul_f32 v[104:105], v[92:93], v[148:149]
	v_pk_mul_f32 v[106:107], v[90:91], v[146:147]
	v_cvt_pk_bf16_f32 v100, v100, v101
	v_cvt_pk_bf16_f32 v101, v102, v103
	s_nop 0
	v_cvt_pk_bf16_f32 v102, v106, v107
	v_cvt_pk_bf16_f32 v103, v104, v105
	v_lshl_add_u64 v[104:105], v[190:191], 0, v[0:1]
	v_add_co_u32_e32 v104, vcc, 0x1000, v104
	s_nop 1
	v_addc_co_u32_e32 v105, vcc, 0, v105, vcc
	global_store_dwordx4 v[104:105], v[100:103], off
.LBB0_1473:
	s_nop 1
	v_cvt_f32_f16_sdwa v101, v172 dst_sel:DWORD dst_unused:UNUSED_PAD src0_sel:WORD_1
	v_cvt_f32_f16_sdwa v103, v173 dst_sel:DWORD dst_unused:UNUSED_PAD src0_sel:WORD_1
	v_cvt_f32_f16_sdwa v105, v170 dst_sel:DWORD dst_unused:UNUSED_PAD src0_sel:WORD_1
	v_cvt_f32_f16_sdwa v107, v171 dst_sel:DWORD dst_unused:UNUSED_PAD src0_sel:WORD_1
	v_cvt_f32_f16_e32 v106, v171
	v_cvt_f32_f16_e32 v104, v170
	v_cvt_f32_f16_e32 v102, v173
	v_cvt_f32_f16_e32 v100, v172
	v_pk_fma_f32 v[88:89], v[88:89], v[144:145], v[106:107]
	v_pk_fma_f32 v[86:87], v[86:87], v[142:143], v[104:105]
	v_pk_fma_f32 v[84:85], v[84:85], v[156:157], v[102:103]
	v_pk_fma_f32 v[82:83], v[82:83], v[154:155], v[100:101]
	v_cvt_pk_f16_f32 v103, v84, v85
	v_cvt_pk_f16_f32 v101, v88, v89
	v_cvt_pk_f16_f32 v102, v82, v83
	v_cvt_pk_f16_f32 v100, v86, v87
	s_and_b64 vcc, exec, s[8:9]
	global_store_dwordx4 v[98:99], v[100:103], off offset:1024
	s_cbranch_vccnz .LBB0_1475
	s_nop 0
	v_pk_mul_f32 v[100:101], v[88:89], v[140:141]
	v_pk_mul_f32 v[98:99], v[86:87], v[138:139]
	v_pk_mul_f32 v[102:103], v[84:85], v[136:137]
	v_pk_mul_f32 v[104:105], v[82:83], v[134:135]
	v_cvt_pk_bf16_f32 v98, v98, v99
	v_cvt_pk_bf16_f32 v99, v100, v101
	s_nop 0
	v_cvt_pk_bf16_f32 v100, v104, v105
	v_cvt_pk_bf16_f32 v101, v102, v103
	v_lshl_add_u64 v[102:103], v[190:191], 0, v[0:1]
	v_add_co_u32_e32 v102, vcc, 0x11000, v102
	s_nop 1
	v_addc_co_u32_e32 v103, vcc, 0, v103, vcc
	global_store_dwordx4 v[102:103], v[98:101], off

; __device__ __forceinline__ float bperm(float v, int src_lane) { return __int_as_float(__builtin_amdgcn_ds_bpermute(src_lane << 2, __float_as_int(v))); }
; __device__ __forceinline__ u32x4 pack8(const f32x4 a, const f32x4 b) { u32x4 w; w.x = cvt_pk_bf16(a.x, a.y); w.y = cvt_pk_bf16(a.z, a.w); w.z = cvt_pk_bf16(b.x, b.y); w.w = cvt_pk_bf16(b.z, b.w); return w; }
; __host__ __device__ __forceinline__ size_t xs_off(int row, int col) { return (size_t)(row >> 8) * (256 * D) + (size_t)(col >> 6) * (256 * 64) + (size_t)((row & 255) * 64 + (col & 63)); }
;     template <bool INF32, int M0, int M1> __device__ __forceinline__ void half(f32x4 (&acc)[2][2][4][2], int ai, int b, int row0, int col, int pn, int wc, int fr, int fq) const {
;     ...
;         for (int m = M0; m < M1; ++m) { const int row = row0 + ai * 128 + m * 16; float ss = 0.f;
; #pragma unroll
;             for (int bj = 0; bj < 2; ++bj) { const size_t o = (size_t)row * D + col + bj * 128;
;                 const f32x4 x0 = xv[m][bj][0] + gt[bj][0] * acc[ai][bj][m][0], x1 = xv[m][bj][1] + gt[bj][1] * acc[ai][bj][m][1];
;                 if (out_f32) { *(f32x4*)((float*)xout + o) = x0; *(f32x4*)((float*)xout + o + 4) = x1; }
;                 else { const f32x8_t ff = {x0.x, x0.y, x0.z, x0.w, x1.x, x1.y, x1.z, x1.w}; *(f16x8_t*)((bf16_t*)xout + o) = __builtin_convertvector(ff, f16x8_t); }
;                 ss += ((x0.x * x0.x + x0.y * x0.y) + (x0.z * x0.z + x0.w * x0.w)) + ((x1.x * x1.x + x1.y * x1.y) + (x1.z * x1.z + x1.w * x1.w));
;                 if (XS) *(u32x4*)(XS + xs_off(row0, col) + (ai * 128 + m * 16) * 64 + bj * (2 * 256 * 64)) = pack8(x0 * gs[bj][0], x1 * gs[bj][1]); }
;             { const int ln = fr + 16 * fq; ss += bperm(ss, ln ^ 16); ss += bperm(ss, ln ^ 32); }
;             if (fq == 0) RSS[(size_t)row * 32 + pn * 4 + wc] = ss; }
.LBB0_1477:
	s_or_b64 exec, exec, s[30:31]
	s_waitcnt lgkmcnt(0)
	v_cvt_f32_f16_sdwa v83, v160 dst_sel:DWORD dst_unused:UNUSED_PAD src0_sel:WORD_1
	v_cvt_f32_f16_sdwa v85, v161 dst_sel:DWORD dst_unused:UNUSED_PAD src0_sel:WORD_1
	v_cvt_f32_f16_sdwa v87, v158 dst_sel:DWORD dst_unused:UNUSED_PAD src0_sel:WORD_1
	v_cvt_f32_f16_sdwa v89, v159 dst_sel:DWORD dst_unused:UNUSED_PAD src0_sel:WORD_1
	v_cvt_f32_f16_e32 v88, v159
	v_cvt_f32_f16_e32 v86, v158
	v_cvt_f32_f16_e32 v84, v161
	v_cvt_f32_f16_e32 v82, v160
	v_pk_fma_f32 v[80:81], v[80:81], v[164:165], v[88:89]
	v_pk_fma_f32 v[78:79], v[78:79], v[162:163], v[86:87]
	v_pk_fma_f32 v[76:77], v[76:77], v[168:169], v[84:85]
	v_pk_fma_f32 v[74:75], v[74:75], v[166:167], v[82:83]
	v_lshl_add_u64 v[82:83], s[14:15], 0, v[218:219]
	v_cvt_pk_f16_f32 v87, v76, v77
	v_cvt_pk_f16_f32 v85, v80, v81
	v_cvt_pk_f16_f32 v86, v74, v75
	v_cvt_pk_f16_f32 v84, v78, v79
	v_lshl_add_u64 v[82:83], v[202:203], 1, v[82:83]
	v_lshl_add_u64 v[82:83], v[82:83], 0, s[100:101]
	s_and_b64 vcc, exec, s[8:9]
	global_store_dwordx4 v[82:83], v[84:87], off
	s_cbranch_vccnz .LBB0_1479
	s_nop 0
	v_pk_mul_f32 v[86:87], v[80:81], v[152:153]
	v_pk_mul_f32 v[84:85], v[78:79], v[150:151]
	v_pk_mul_f32 v[88:89], v[76:77], v[148:149]
	v_pk_mul_f32 v[90:91], v[74:75], v[146:147]
	v_cvt_pk_bf16_f32 v84, v84, v85
	v_cvt_pk_bf16_f32 v85, v86, v87
	s_nop 0
	v_cvt_pk_bf16_f32 v86, v90, v91
	v_cvt_pk_bf16_f32 v87, v88, v89
	v_lshl_add_u64 v[88:89], v[190:191], 0, v[0:1]
	v_add_co_u32_e32 v88, vcc, 0x1000, v88
	s_nop 1
	v_addc_co_u32_e32 v89, vcc, 0, v89, vcc
	global_store_dwordx4 v[88:89], v[84:87], off offset:2048
.LBB0_1479:
	s_nop 1
	v_cvt_f32_f16_sdwa v85, v132 dst_sel:DWORD dst_unused:UNUSED_PAD src0_sel:WORD_1
	v_cvt_f32_f16_sdwa v87, v133 dst_sel:DWORD dst_unused:UNUSED_PAD src0_sel:WORD_1
	v_cvt_f32_f16_sdwa v89, v130 dst_sel:DWORD dst_unused:UNUSED_PAD src0_sel:WORD_1
	v_cvt_f32_f16_sdwa v91, v131 dst_sel:DWORD dst_unused:UNUSED_PAD src0_sel:WORD_1
	v_cvt_f32_f16_e32 v90, v131
	v_cvt_f32_f16_e32 v88, v130
	v_cvt_f32_f16_e32 v86, v133
	v_cvt_f32_f16_e32 v84, v132
	v_pk_fma_f32 v[72:73], v[72:73], v[144:145], v[90:91]
	v_pk_fma_f32 v[70:71], v[70:71], v[142:143], v[88:89]
	v_pk_fma_f32 v[68:69], v[68:69], v[156:157], v[86:87]
	v_pk_fma_f32 v[66:67], v[66:67], v[154:155], v[84:85]
	v_cvt_pk_f16_f32 v87, v68, v69
	v_cvt_pk_f16_f32 v85, v72, v73
	v_cvt_pk_f16_f32 v86, v66, v67
	v_cvt_pk_f16_f32 v84, v70, v71
	s_and_b64 vcc, exec, s[8:9]
	global_store_dwordx4 v[82:83], v[84:87], off offset:1024
	s_cbranch_vccnz .LBB0_1481
	s_nop 0
	v_pk_mul_f32 v[84:85], v[72:73], v[140:141]
	v_pk_mul_f32 v[82:83], v[70:71], v[138:139]
	v_pk_mul_f32 v[86:87], v[68:69], v[136:137]
	v_pk_mul_f32 v[88:89], v[66:67], v[134:135]
	v_cvt_pk_bf16_f32 v82, v82, v83
	v_cvt_pk_bf16_f32 v83, v84, v85
	s_nop 0
	v_cvt_pk_bf16_f32 v84, v88, v89
	v_cvt_pk_bf16_f32 v85, v86, v87
	v_lshl_add_u64 v[86:87], v[190:191], 0, v[0:1]
	v_add_co_u32_e32 v86, vcc, 0x11000, v86
	s_nop 1
	v_addc_co_u32_e32 v87, vcc, 0, v87, vcc
	global_store_dwordx4 v[86:87], v[82:85], off offset:2048

;     template <bool INF32, int M0, int M1> __device__ __forceinline__ void half(f32x4 (&acc)[2][2][4][2], int ai, int b, int row0, int col, int pn, int wc, int fr, int fq) const {
;     ...
;             for (int m = M0; m < M1; ++m)
; #pragma unroll
;                 for (int bj = 0; bj < 2; ++bj) hh[m][bj] = *(const f16x8_t*)((const bf16_t*)xin + (size_t)(row0 + ai * 128 + m * 16) * D + col + bj * 128);
; #pragma unroll
;             for (int m = M0; m < M1; ++m)
; #pragma unroll
;                 for (int bj = 0; bj < 2; ++bj) { const f32x8_t ff = __builtin_convertvector(hh[m][bj], f32x8_t); xv[m][bj][0] = (f32x4){ff[0], ff[1], ff[2], ff[3]}; xv[m][bj][1] = (f32x4){ff[4], ff[5], ff[6], ff[7]}; }
;         }
;         f32x4 gt[2][2], gs[2][2];
; #pragma unroll
;         for (int bj = 0; bj < 2; ++bj)
; #pragma unroll
;             for (int n = 0; n < 2; ++n) { gt[bj][n] = *(const f32x4*)(gate + (size_t)b * 6 * D + col + bj * 128 + n * 4); gs[bj][n] = XS ? *(const f32x4*)(GS + (size_t)b * D + col + bj * 128 + n * 4) : (f32x4){0.f, 0.f, 0.f, 0.f}; }
.LBB0_1483:
	s_or_b64 exec, exec, s[30:31]
	v_add_u32_e32 v142, 0x80, v208
	v_add_u32_e32 v138, 0x90, v208
	v_ashrrev_i32_e32 v143, 31, v142
	v_ashrrev_i32_e32 v139, 31, v138
	v_add_u32_e32 v134, 0xa0, v208
	v_add_u32_e32 v130, 0xb0, v208
	v_lshlrev_b64 v[144:145], 12, v[142:143]
	v_bfe_u32 v145, v144, 12, 4
	v_lshl_add_u32 v144, v145, 6, v144
	v_lshlrev_b32_e32 v145, 12, v145
	v_sub_u32_e32 v144, v144, v145
	v_mov_b32_e32 v145, 0
	v_lshlrev_b64 v[140:141], 12, v[138:139]
	v_bfe_u32 v141, v140, 12, 4
	v_lshl_add_u32 v140, v141, 6, v140
	v_lshlrev_b32_e32 v141, 12, v141
	v_sub_u32_e32 v140, v140, v141
	v_mov_b32_e32 v141, 0
	v_ashrrev_i32_e32 v135, 31, v134
	v_ashrrev_i32_e32 v131, 31, v130
	v_lshl_add_u64 v[70:71], v[210:211], 0, v[144:145]
	s_waitcnt lgkmcnt(0)
	v_lshl_add_u64 v[66:67], v[210:211], 0, v[140:141]
	v_lshlrev_b64 v[136:137], 12, v[134:135]
	v_bfe_u32 v137, v136, 12, 4
	v_lshl_add_u32 v136, v137, 6, v136
	v_lshlrev_b32_e32 v137, 12, v137
	v_sub_u32_e32 v136, v136, v137
	v_mov_b32_e32 v137, 0
	v_lshlrev_b64 v[132:133], 12, v[130:131]
	v_bfe_u32 v133, v132, 12, 4
	v_lshl_add_u32 v132, v133, 6, v132
	v_lshlrev_b32_e32 v133, 12, v133
	v_sub_u32_e32 v132, v132, v133
	v_mov_b32_e32 v133, 0
	global_load_dwordx4 v[122:125], v[70:71], off offset:1024
	global_load_dwordx4 v[118:121], v[66:67], off
	v_lshl_add_u64 v[68:69], v[210:211], 0, v[136:137]
	global_load_dwordx4 v[114:117], v[66:67], off offset:1024
	global_load_dwordx4 v[110:113], v[68:69], off
	v_lshl_add_u64 v[66:67], v[210:211], 0, v[132:133]
	global_load_dwordx4 v[106:109], v[68:69], off offset:1024
	global_load_dwordx4 v[98:101], v[66:67], off
	s_nop 0
	global_load_dwordx4 v[66:69], v[66:67], off offset:1024
	s_nop 0
	global_load_dwordx4 v[126:129], v[70:71], off
	global_load_dwordx4 v[94:97], v[204:205], off
	v_mov_b32_e32 v82, 0
	s_and_b64 vcc, exec, s[8:9]
	v_mov_b32_e32 v86, 0
	v_mov_b32_e32 v87, 0
	v_mov_b32_e32 v88, 0
	v_mov_b32_e32 v89, 0
	s_cbranch_vccnz .LBB0_1485
	global_load_dwordx4 v[86:89], v[206:207], off

; __device__ __forceinline__ float bperm(float v, int src_lane) { return __int_as_float(__builtin_amdgcn_ds_bpermute(src_lane << 2, __float_as_int(v))); }
; __device__ __forceinline__ u32x4 pack8(const f32x4 a, const f32x4 b) { u32x4 w; w.x = cvt_pk_bf16(a.x, a.y); w.y = cvt_pk_bf16(a.z, a.w); w.z = cvt_pk_bf16(b.x, b.y); w.w = cvt_pk_bf16(b.z, b.w); return w; }
; __host__ __device__ __forceinline__ size_t xs_off(int row, int col) { return (size_t)(row >> 8) * (256 * D) + (size_t)(col >> 6) * (256 * 64) + (size_t)((row & 255) * 64 + (col & 63)); }
;     template <bool INF32, int M0, int M1> __device__ __forceinline__ void half(f32x4 (&acc)[2][2][4][2], int ai, int b, int row0, int col, int pn, int wc, int fr, int fq) const {
;     ...
;         for (int m = M0; m < M1; ++m) { const int row = row0 + ai * 128 + m * 16; float ss = 0.f;
; #pragma unroll
;             for (int bj = 0; bj < 2; ++bj) { const size_t o = (size_t)row * D + col + bj * 128;
;                 const f32x4 x0 = xv[m][bj][0] + gt[bj][0] * acc[ai][bj][m][0], x1 = xv[m][bj][1] + gt[bj][1] * acc[ai][bj][m][1];
;                 if (out_f32) { *(f32x4*)((float*)xout + o) = x0; *(f32x4*)((float*)xout + o + 4) = x1; }
;                 else { const f32x8_t ff = {x0.x, x0.y, x0.z, x0.w, x1.x, x1.y, x1.z, x1.w}; *(f16x8_t*)((bf16_t*)xout + o) = __builtin_convertvector(ff, f16x8_t); }
;                 ss += ((x0.x * x0.x + x0.y * x0.y) + (x0.z * x0.z + x0.w * x0.w)) + ((x1.x * x1.x + x1.y * x1.y) + (x1.z * x1.z + x1.w * x1.w));
;                 if (XS) *(u32x4*)(XS + xs_off(row0, col) + (ai * 128 + m * 16) * 64 + bj * (2 * 256 * 64)) = pack8(x0 * gs[bj][0], x1 * gs[bj][1]); }
;             { const int ln = fr + 16 * fq; ss += bperm(ss, ln ^ 16); ss += bperm(ss, ln ^ 32); }
;             if (fq == 0) RSS[(size_t)row * 32 + pn * 4 + wc] = ss; }
.LBB0_1491:
	s_waitcnt vmcnt(4)
	v_cvt_f32_f16_sdwa v147, v128 dst_sel:DWORD dst_unused:UNUSED_PAD src0_sel:WORD_1
	v_cvt_f32_f16_sdwa v149, v129 dst_sel:DWORD dst_unused:UNUSED_PAD src0_sel:WORD_1
	v_cvt_f32_f16_sdwa v151, v126 dst_sel:DWORD dst_unused:UNUSED_PAD src0_sel:WORD_1
	v_cvt_f32_f16_sdwa v153, v127 dst_sel:DWORD dst_unused:UNUSED_PAD src0_sel:WORD_1
	v_cvt_f32_f16_e32 v146, v128
	v_cvt_f32_f16_e32 v148, v129
	v_cvt_f32_f16_e32 v150, v126
	v_cvt_f32_f16_e32 v152, v127
	s_waitcnt vmcnt(3)
	v_pk_fma_f32 v[64:65], v[64:65], v[96:97], v[152:153]
	v_pk_fma_f32 v[62:63], v[62:63], v[94:95], v[150:151]
	s_waitcnt vmcnt(2)
	v_pk_fma_f32 v[60:61], v[60:61], v[104:105], v[148:149]
	v_pk_fma_f32 v[58:59], v[58:59], v[102:103], v[146:147]
	v_lshl_add_u64 v[126:127], s[14:15], 0, v[144:145]
	v_cvt_pk_f16_f32 v149, v60, v61
	v_cvt_pk_f16_f32 v147, v64, v65
	v_cvt_pk_f16_f32 v148, v58, v59
	v_cvt_pk_f16_f32 v146, v62, v63
	v_lshl_add_u64 v[126:127], v[202:203], 1, v[126:127]
	v_lshl_add_u64 v[126:127], v[126:127], 0, s[100:101]
	s_and_b64 vcc, exec, s[8:9]
	global_store_dwordx4 v[126:127], v[146:149], off
	s_cbranch_vccnz .LBB0_1493
	v_pk_mul_f32 v[128:129], v[64:65], v[88:89]
	v_pk_mul_f32 v[144:145], v[62:63], v[86:87]
	v_pk_mul_f32 v[146:147], v[58:59], v[82:83]
	v_cvt_pk_bf16_f32 v144, v144, v145
	v_cvt_pk_bf16_f32 v145, v128, v129
	v_lshl_add_u64 v[128:129], v[190:191], 0, v[0:1]
	v_add_co_u32_e32 v128, vcc, 0x4000, v128
	v_pk_mul_f32 v[148:149], v[60:61], v[84:85]
	s_nop 0
	v_addc_co_u32_e32 v129, vcc, 0, v129, vcc
	v_cvt_pk_bf16_f32 v146, v146, v147
	v_cvt_pk_bf16_f32 v147, v148, v149
	global_store_dwordx4 v[128:129], v[144:147], off
.LBB0_1493:
	v_cvt_f32_f16_sdwa v129, v124 dst_sel:DWORD dst_unused:UNUSED_PAD src0_sel:WORD_1
	s_nop 0
	v_cvt_f32_f16_sdwa v145, v125 dst_sel:DWORD dst_unused:UNUSED_PAD src0_sel:WORD_1
	v_cvt_f32_f16_sdwa v147, v122 dst_sel:DWORD dst_unused:UNUSED_PAD src0_sel:WORD_1
	v_cvt_f32_f16_sdwa v149, v123 dst_sel:DWORD dst_unused:UNUSED_PAD src0_sel:WORD_1
	v_cvt_f32_f16_e32 v148, v123
	v_cvt_f32_f16_e32 v146, v122
	v_cvt_f32_f16_e32 v144, v125
	v_cvt_f32_f16_e32 v128, v124
	s_waitcnt vmcnt(2)
	v_pk_fma_f32 v[56:57], v[56:57], v[80:81], v[148:149]
	v_pk_fma_f32 v[54:55], v[54:55], v[78:79], v[146:147]
	s_waitcnt vmcnt(1)
	v_pk_fma_f32 v[52:53], v[52:53], v[92:93], v[144:145]
	v_pk_fma_f32 v[50:51], v[50:51], v[90:91], v[128:129]
	v_cvt_pk_f16_f32 v125, v52, v53
	v_cvt_pk_f16_f32 v123, v56, v57
	v_cvt_pk_f16_f32 v124, v50, v51
	v_cvt_pk_f16_f32 v122, v54, v55
	s_and_b64 vcc, exec, s[8:9]
	global_store_dwordx4 v[126:127], v[122:125], off offset:1024
	s_cbranch_vccnz .LBB0_1495
	s_nop 0
	v_pk_mul_f32 v[124:125], v[56:57], v[76:77]
	v_pk_mul_f32 v[122:123], v[54:55], v[74:75]
	v_pk_mul_f32 v[126:127], v[52:53], v[72:73]
	v_pk_mul_f32 v[128:129], v[50:51], v[70:71]
	v_cvt_pk_bf16_f32 v122, v122, v123
	v_cvt_pk_bf16_f32 v123, v124, v125
	s_nop 0
	v_cvt_pk_bf16_f32 v124, v128, v129
	v_cvt_pk_bf16_f32 v125, v126, v127
	v_lshl_add_u64 v[126:127], v[190:191], 0, v[0:1]
	v_add_co_u32_e32 v126, vcc, 0x14000, v126
	s_nop 1
	v_addc_co_u32_e32 v127, vcc, 0, v127, vcc
	global_store_dwordx4 v[126:127], v[122:125], off

; __device__ __forceinline__ float bperm(float v, int src_lane) { return __int_as_float(__builtin_amdgcn_ds_bpermute(src_lane << 2, __float_as_int(v))); }
; __device__ __forceinline__ u32x4 pack8(const f32x4 a, const f32x4 b) { u32x4 w; w.x = cvt_pk_bf16(a.x, a.y); w.y = cvt_pk_bf16(a.z, a.w); w.z = cvt_pk_bf16(b.x, b.y); w.w = cvt_pk_bf16(b.z, b.w); return w; }
; __host__ __device__ __forceinline__ size_t xs_off(int row, int col) { return (size_t)(row >> 8) * (256 * D) + (size_t)(col >> 6) * (256 * 64) + (size_t)((row & 255) * 64 + (col & 63)); }
;     template <bool INF32, int M0, int M1> __device__ __forceinline__ void half(f32x4 (&acc)[2][2][4][2], int ai, int b, int row0, int col, int pn, int wc, int fr, int fq) const {
;     ...
;         for (int m = M0; m < M1; ++m) { const int row = row0 + ai * 128 + m * 16; float ss = 0.f;
; #pragma unroll
;             for (int bj = 0; bj < 2; ++bj) { const size_t o = (size_t)row * D + col + bj * 128;
;                 const f32x4 x0 = xv[m][bj][0] + gt[bj][0] * acc[ai][bj][m][0], x1 = xv[m][bj][1] + gt[bj][1] * acc[ai][bj][m][1];
;                 if (out_f32) { *(f32x4*)((float*)xout + o) = x0; *(f32x4*)((float*)xout + o + 4) = x1; }
;                 else { const f32x8_t ff = {x0.x, x0.y, x0.z, x0.w, x1.x, x1.y, x1.z, x1.w}; *(f16x8_t*)((bf16_t*)xout + o) = __builtin_convertvector(ff, f16x8_t); }
;                 ss += ((x0.x * x0.x + x0.y * x0.y) + (x0.z * x0.z + x0.w * x0.w)) + ((x1.x * x1.x + x1.y * x1.y) + (x1.z * x1.z + x1.w * x1.w));
;                 if (XS) *(u32x4*)(XS + xs_off(row0, col) + (ai * 128 + m * 16) * 64 + bj * (2 * 256 * 64)) = pack8(x0 * gs[bj][0], x1 * gs[bj][1]); }
;             { const int ln = fr + 16 * fq; ss += bperm(ss, ln ^ 16); ss += bperm(ss, ln ^ 32); }
;             if (fq == 0) RSS[(size_t)row * 32 + pn * 4 + wc] = ss; }
.LBB0_1497:
	s_or_b64 exec, exec, s[30:31]
	s_waitcnt lgkmcnt(0)
	v_cvt_f32_f16_sdwa v51, v120 dst_sel:DWORD dst_unused:UNUSED_PAD src0_sel:WORD_1
	v_cvt_f32_f16_sdwa v53, v121 dst_sel:DWORD dst_unused:UNUSED_PAD src0_sel:WORD_1
	v_cvt_f32_f16_sdwa v55, v118 dst_sel:DWORD dst_unused:UNUSED_PAD src0_sel:WORD_1
	v_cvt_f32_f16_sdwa v57, v119 dst_sel:DWORD dst_unused:UNUSED_PAD src0_sel:WORD_1
	v_cvt_f32_f16_e32 v56, v119
	v_cvt_f32_f16_e32 v54, v118
	v_cvt_f32_f16_e32 v52, v121
	v_cvt_f32_f16_e32 v50, v120
	v_pk_fma_f32 v[48:49], v[48:49], v[96:97], v[56:57]
	v_pk_fma_f32 v[46:47], v[46:47], v[94:95], v[54:55]
	v_pk_fma_f32 v[44:45], v[44:45], v[104:105], v[52:53]
	v_pk_fma_f32 v[42:43], v[42:43], v[102:103], v[50:51]
	v_lshl_add_u64 v[50:51], s[14:15], 0, v[140:141]
	v_cvt_pk_f16_f32 v55, v44, v45
	v_cvt_pk_f16_f32 v53, v48, v49
	v_cvt_pk_f16_f32 v54, v42, v43
	v_cvt_pk_f16_f32 v52, v46, v47
	v_lshl_add_u64 v[50:51], v[202:203], 1, v[50:51]
	v_lshl_add_u64 v[50:51], v[50:51], 0, s[100:101]
	s_and_b64 vcc, exec, s[8:9]
	global_store_dwordx4 v[50:51], v[52:55], off
	s_cbranch_vccnz .LBB0_1499
	s_nop 0
	v_pk_mul_f32 v[54:55], v[48:49], v[88:89]
	v_pk_mul_f32 v[52:53], v[46:47], v[86:87]
	v_pk_mul_f32 v[56:57], v[44:45], v[84:85]
	v_pk_mul_f32 v[58:59], v[42:43], v[82:83]
	v_cvt_pk_bf16_f32 v52, v52, v53
	v_cvt_pk_bf16_f32 v53, v54, v55
	s_nop 0
	v_cvt_pk_bf16_f32 v54, v58, v59
	v_cvt_pk_bf16_f32 v55, v56, v57
	v_lshl_add_u64 v[56:57], v[190:191], 0, v[0:1]
	v_add_co_u32_e32 v56, vcc, 0x4000, v56
	s_nop 1
	v_addc_co_u32_e32 v57, vcc, 0, v57, vcc
	global_store_dwordx4 v[56:57], v[52:55], off offset:2048
.LBB0_1499:
	s_nop 1
	v_cvt_f32_f16_sdwa v53, v116 dst_sel:DWORD dst_unused:UNUSED_PAD src0_sel:WORD_1
	v_cvt_f32_f16_sdwa v55, v117 dst_sel:DWORD dst_unused:UNUSED_PAD src0_sel:WORD_1
	v_cvt_f32_f16_sdwa v57, v114 dst_sel:DWORD dst_unused:UNUSED_PAD src0_sel:WORD_1
	v_cvt_f32_f16_sdwa v59, v115 dst_sel:DWORD dst_unused:UNUSED_PAD src0_sel:WORD_1
	v_cvt_f32_f16_e32 v58, v115
	v_cvt_f32_f16_e32 v56, v114
	v_cvt_f32_f16_e32 v54, v117
	v_cvt_f32_f16_e32 v52, v116
	v_pk_fma_f32 v[40:41], v[40:41], v[80:81], v[58:59]
	v_pk_fma_f32 v[38:39], v[38:39], v[78:79], v[56:57]
	v_pk_fma_f32 v[36:37], v[36:37], v[92:93], v[54:55]
	v_pk_fma_f32 v[34:35], v[34:35], v[90:91], v[52:53]
	v_cvt_pk_f16_f32 v55, v36, v37
	v_cvt_pk_f16_f32 v53, v40, v41
	v_cvt_pk_f16_f32 v54, v34, v35
	v_cvt_pk_f16_f32 v52, v38, v39
	s_and_b64 vcc, exec, s[8:9]
	global_store_dwordx4 v[50:51], v[52:55], off offset:1024
	s_cbranch_vccnz .LBB0_1501
	s_nop 0
	v_pk_mul_f32 v[52:53], v[40:41], v[76:77]
	v_pk_mul_f32 v[50:51], v[38:39], v[74:75]
	v_pk_mul_f32 v[54:55], v[36:37], v[72:73]
	v_pk_mul_f32 v[56:57], v[34:35], v[70:71]
	v_cvt_pk_bf16_f32 v50, v50, v51
	v_cvt_pk_bf16_f32 v51, v52, v53
	s_nop 0
	v_cvt_pk_bf16_f32 v52, v56, v57
	v_cvt_pk_bf16_f32 v53, v54, v55
	v_lshl_add_u64 v[54:55], v[190:191], 0, v[0:1]
	v_add_co_u32_e32 v54, vcc, 0x14000, v54
	s_nop 1
	v_addc_co_u32_e32 v55, vcc, 0, v55, vcc
	global_store_dwordx4 v[54:55], v[50:53], off offset:2048

; __device__ __forceinline__ float bperm(float v, int src_lane) { return __int_as_float(__builtin_amdgcn_ds_bpermute(src_lane << 2, __float_as_int(v))); }
; __device__ __forceinline__ u32x4 pack8(const f32x4 a, const f32x4 b) { u32x4 w; w.x = cvt_pk_bf16(a.x, a.y); w.y = cvt_pk_bf16(a.z, a.w); w.z = cvt_pk_bf16(b.x, b.y); w.w = cvt_pk_bf16(b.z, b.w); return w; }
; __host__ __device__ __forceinline__ size_t xs_off(int row, int col) { return (size_t)(row >> 8) * (256 * D) + (size_t)(col >> 6) * (256 * 64) + (size_t)((row & 255) * 64 + (col & 63)); }
;     template <bool INF32, int M0, int M1> __device__ __forceinline__ void half(f32x4 (&acc)[2][2][4][2], int ai, int b, int row0, int col, int pn, int wc, int fr, int fq) const {
;     ...
;         for (int m = M0; m < M1; ++m) { const int row = row0 + ai * 128 + m * 16; float ss = 0.f;
; #pragma unroll
;             for (int bj = 0; bj < 2; ++bj) { const size_t o = (size_t)row * D + col + bj * 128;
;                 const f32x4 x0 = xv[m][bj][0] + gt[bj][0] * acc[ai][bj][m][0], x1 = xv[m][bj][1] + gt[bj][1] * acc[ai][bj][m][1];
;                 if (out_f32) { *(f32x4*)((float*)xout + o) = x0; *(f32x4*)((float*)xout + o + 4) = x1; }
;                 else { const f32x8_t ff = {x0.x, x0.y, x0.z, x0.w, x1.x, x1.y, x1.z, x1.w}; *(f16x8_t*)((bf16_t*)xout + o) = __builtin_convertvector(ff, f16x8_t); }
;                 ss += ((x0.x * x0.x + x0.y * x0.y) + (x0.z * x0.z + x0.w * x0.w)) + ((x1.x * x1.x + x1.y * x1.y) + (x1.z * x1.z + x1.w * x1.w));
;                 if (XS) *(u32x4*)(XS + xs_off(row0, col) + (ai * 128 + m * 16) * 64 + bj * (2 * 256 * 64)) = pack8(x0 * gs[bj][0], x1 * gs[bj][1]); }
;             { const int ln = fr + 16 * fq; ss += bperm(ss, ln ^ 16); ss += bperm(ss, ln ^ 32); }
;             if (fq == 0) RSS[(size_t)row * 32 + pn * 4 + wc] = ss; }
.LBB0_1503:
	s_or_b64 exec, exec, s[30:31]
	s_waitcnt lgkmcnt(0)
	v_cvt_f32_f16_sdwa v35, v112 dst_sel:DWORD dst_unused:UNUSED_PAD src0_sel:WORD_1
	v_cvt_f32_f16_sdwa v37, v113 dst_sel:DWORD dst_unused:UNUSED_PAD src0_sel:WORD_1
	v_cvt_f32_f16_sdwa v39, v110 dst_sel:DWORD dst_unused:UNUSED_PAD src0_sel:WORD_1
	v_cvt_f32_f16_sdwa v41, v111 dst_sel:DWORD dst_unused:UNUSED_PAD src0_sel:WORD_1
	v_cvt_f32_f16_e32 v40, v111
	v_cvt_f32_f16_e32 v38, v110
	v_cvt_f32_f16_e32 v36, v113
	v_cvt_f32_f16_e32 v34, v112
	v_pk_fma_f32 v[32:33], v[32:33], v[96:97], v[40:41]
	v_pk_fma_f32 v[30:31], v[30:31], v[94:95], v[38:39]
	v_pk_fma_f32 v[28:29], v[28:29], v[104:105], v[36:37]
	v_pk_fma_f32 v[26:27], v[26:27], v[102:103], v[34:35]
	v_lshl_add_u64 v[34:35], s[14:15], 0, v[136:137]
	v_cvt_pk_f16_f32 v39, v28, v29
	v_cvt_pk_f16_f32 v37, v32, v33
	v_cvt_pk_f16_f32 v38, v26, v27
	v_cvt_pk_f16_f32 v36, v30, v31
	v_lshl_add_u64 v[34:35], v[202:203], 1, v[34:35]
	v_lshl_add_u64 v[34:35], v[34:35], 0, s[100:101]
	s_and_b64 vcc, exec, s[8:9]
	global_store_dwordx4 v[34:35], v[36:39], off
	s_cbranch_vccnz .LBB0_1505
	s_nop 0
	v_pk_mul_f32 v[38:39], v[32:33], v[88:89]
	v_pk_mul_f32 v[36:37], v[30:31], v[86:87]
	v_pk_mul_f32 v[40:41], v[28:29], v[84:85]
	v_pk_mul_f32 v[42:43], v[26:27], v[82:83]
	v_cvt_pk_bf16_f32 v36, v36, v37
	v_cvt_pk_bf16_f32 v37, v38, v39
	s_nop 0
	v_cvt_pk_bf16_f32 v38, v42, v43
	v_cvt_pk_bf16_f32 v39, v40, v41
	v_lshl_add_u64 v[40:41], v[190:191], 0, v[0:1]
	v_add_co_u32_e32 v40, vcc, 0x5000, v40
	s_nop 1
	v_addc_co_u32_e32 v41, vcc, 0, v41, vcc
	global_store_dwordx4 v[40:41], v[36:39], off
.LBB0_1505:
	s_nop 1
	v_cvt_f32_f16_sdwa v37, v108 dst_sel:DWORD dst_unused:UNUSED_PAD src0_sel:WORD_1
	v_cvt_f32_f16_sdwa v39, v109 dst_sel:DWORD dst_unused:UNUSED_PAD src0_sel:WORD_1
	v_cvt_f32_f16_sdwa v41, v106 dst_sel:DWORD dst_unused:UNUSED_PAD src0_sel:WORD_1
	v_cvt_f32_f16_sdwa v43, v107 dst_sel:DWORD dst_unused:UNUSED_PAD src0_sel:WORD_1
	v_cvt_f32_f16_e32 v42, v107
	v_cvt_f32_f16_e32 v40, v106
	v_cvt_f32_f16_e32 v38, v109
	v_cvt_f32_f16_e32 v36, v108
	v_pk_fma_f32 v[24:25], v[24:25], v[80:81], v[42:43]
	v_pk_fma_f32 v[22:23], v[22:23], v[78:79], v[40:41]
	v_pk_fma_f32 v[20:21], v[20:21], v[92:93], v[38:39]
	v_pk_fma_f32 v[18:19], v[18:19], v[90:91], v[36:37]
	v_cvt_pk_f16_f32 v39, v20, v21
	v_cvt_pk_f16_f32 v37, v24, v25
	v_cvt_pk_f16_f32 v38, v18, v19
	v_cvt_pk_f16_f32 v36, v22, v23
	s_and_b64 vcc, exec, s[8:9]
	global_store_dwordx4 v[34:35], v[36:39], off offset:1024
	s_cbranch_vccnz .LBB0_1507
	s_nop 0
	v_pk_mul_f32 v[36:37], v[24:25], v[76:77]
	v_pk_mul_f32 v[34:35], v[22:23], v[74:75]
	v_pk_mul_f32 v[38:39], v[20:21], v[72:73]
	v_pk_mul_f32 v[40:41], v[18:19], v[70:71]
	v_cvt_pk_bf16_f32 v34, v34, v35
	v_cvt_pk_bf16_f32 v35, v36, v37
	s_nop 0
	v_cvt_pk_bf16_f32 v36, v40, v41
	v_cvt_pk_bf16_f32 v37, v38, v39
	v_lshl_add_u64 v[38:39], v[190:191], 0, v[0:1]
	v_add_co_u32_e32 v38, vcc, 0x15000, v38
	s_nop 1
	v_addc_co_u32_e32 v39, vcc, 0, v39, vcc
	global_store_dwordx4 v[38:39], v[34:37], off

; __device__ __forceinline__ float bperm(float v, int src_lane) { return __int_as_float(__builtin_amdgcn_ds_bpermute(src_lane << 2, __float_as_int(v))); }
; __device__ __forceinline__ u32x4 pack8(const f32x4 a, const f32x4 b) { u32x4 w; w.x = cvt_pk_bf16(a.x, a.y); w.y = cvt_pk_bf16(a.z, a.w); w.z = cvt_pk_bf16(b.x, b.y); w.w = cvt_pk_bf16(b.z, b.w); return w; }
; __host__ __device__ __forceinline__ size_t xs_off(int row, int col) { return (size_t)(row >> 8) * (256 * D) + (size_t)(col >> 6) * (256 * 64) + (size_t)((row & 255) * 64 + (col & 63)); }
;     template <bool INF32, int M0, int M1> __device__ __forceinline__ void half(f32x4 (&acc)[2][2][4][2], int ai, int b, int row0, int col, int pn, int wc, int fr, int fq) const {
;     ...
;         for (int m = M0; m < M1; ++m) { const int row = row0 + ai * 128 + m * 16; float ss = 0.f;
; #pragma unroll
;             for (int bj = 0; bj < 2; ++bj) { const size_t o = (size_t)row * D + col + bj * 128;
;                 const f32x4 x0 = xv[m][bj][0] + gt[bj][0] * acc[ai][bj][m][0], x1 = xv[m][bj][1] + gt[bj][1] * acc[ai][bj][m][1];
;                 if (out_f32) { *(f32x4*)((float*)xout + o) = x0; *(f32x4*)((float*)xout + o + 4) = x1; }
;                 else { const f32x8_t ff = {x0.x, x0.y, x0.z, x0.w, x1.x, x1.y, x1.z, x1.w}; *(f16x8_t*)((bf16_t*)xout + o) = __builtin_convertvector(ff, f16x8_t); }
;                 ss += ((x0.x * x0.x + x0.y * x0.y) + (x0.z * x0.z + x0.w * x0.w)) + ((x1.x * x1.x + x1.y * x1.y) + (x1.z * x1.z + x1.w * x1.w));
;                 if (XS) *(u32x4*)(XS + xs_off(row0, col) + (ai * 128 + m * 16) * 64 + bj * (2 * 256 * 64)) = pack8(x0 * gs[bj][0], x1 * gs[bj][1]); }
;             { const int ln = fr + 16 * fq; ss += bperm(ss, ln ^ 16); ss += bperm(ss, ln ^ 32); }
;             if (fq == 0) RSS[(size_t)row * 32 + pn * 4 + wc] = ss; }
.LBB0_1509:
	s_or_b64 exec, exec, s[30:31]
	s_waitcnt lgkmcnt(0)
	v_cvt_f32_f16_sdwa v19, v100 dst_sel:DWORD dst_unused:UNUSED_PAD src0_sel:WORD_1
	v_cvt_f32_f16_sdwa v21, v101 dst_sel:DWORD dst_unused:UNUSED_PAD src0_sel:WORD_1
	v_cvt_f32_f16_sdwa v23, v98 dst_sel:DWORD dst_unused:UNUSED_PAD src0_sel:WORD_1
	v_cvt_f32_f16_sdwa v25, v99 dst_sel:DWORD dst_unused:UNUSED_PAD src0_sel:WORD_1
	v_cvt_f32_f16_e32 v24, v99
	v_cvt_f32_f16_e32 v22, v98
	v_cvt_f32_f16_e32 v20, v101
	v_cvt_f32_f16_e32 v18, v100
	v_pk_fma_f32 v[16:17], v[16:17], v[96:97], v[24:25]
	v_pk_fma_f32 v[14:15], v[14:15], v[94:95], v[22:23]
	v_pk_fma_f32 v[12:13], v[12:13], v[104:105], v[20:21]
	v_pk_fma_f32 v[10:11], v[10:11], v[102:103], v[18:19]
	v_lshl_add_u64 v[18:19], s[14:15], 0, v[132:133]
	v_cvt_pk_f16_f32 v23, v12, v13
	v_cvt_pk_f16_f32 v21, v16, v17
	v_cvt_pk_f16_f32 v22, v10, v11
	v_cvt_pk_f16_f32 v20, v14, v15
	v_lshl_add_u64 v[18:19], v[202:203], 1, v[18:19]
	v_lshl_add_u64 v[18:19], v[18:19], 0, s[100:101]
	s_and_b64 vcc, exec, s[8:9]
	global_store_dwordx4 v[18:19], v[20:23], off
	s_cbranch_vccnz .LBB0_1511
	s_nop 0
	v_pk_mul_f32 v[22:23], v[16:17], v[88:89]
	v_pk_mul_f32 v[20:21], v[14:15], v[86:87]
	v_pk_mul_f32 v[24:25], v[12:13], v[84:85]
	v_pk_mul_f32 v[26:27], v[10:11], v[82:83]
	v_cvt_pk_bf16_f32 v20, v20, v21
	v_cvt_pk_bf16_f32 v21, v22, v23
	s_nop 0
	v_cvt_pk_bf16_f32 v22, v26, v27
	v_cvt_pk_bf16_f32 v23, v24, v25
	v_lshl_add_u64 v[24:25], v[190:191], 0, v[0:1]
	v_add_co_u32_e32 v24, vcc, 0x5000, v24
	s_nop 1
	v_addc_co_u32_e32 v25, vcc, 0, v25, vcc
	global_store_dwordx4 v[24:25], v[20:23], off offset:2048
.LBB0_1511:
	s_nop 1
	v_cvt_f32_f16_sdwa v21, v68 dst_sel:DWORD dst_unused:UNUSED_PAD src0_sel:WORD_1
	v_cvt_f32_f16_sdwa v23, v69 dst_sel:DWORD dst_unused:UNUSED_PAD src0_sel:WORD_1
	v_cvt_f32_f16_sdwa v25, v66 dst_sel:DWORD dst_unused:UNUSED_PAD src0_sel:WORD_1
	v_cvt_f32_f16_sdwa v27, v67 dst_sel:DWORD dst_unused:UNUSED_PAD src0_sel:WORD_1
	v_cvt_f32_f16_e32 v26, v67
	v_cvt_f32_f16_e32 v24, v66
	v_cvt_f32_f16_e32 v22, v69
	v_cvt_f32_f16_e32 v20, v68
	v_pk_fma_f32 v[8:9], v[8:9], v[80:81], v[26:27]
	v_pk_fma_f32 v[6:7], v[6:7], v[78:79], v[24:25]
	v_pk_fma_f32 v[4:5], v[4:5], v[92:93], v[22:23]
	v_pk_fma_f32 v[2:3], v[2:3], v[90:91], v[20:21]
	v_cvt_pk_f16_f32 v23, v4, v5
	v_cvt_pk_f16_f32 v21, v8, v9
	v_cvt_pk_f16_f32 v22, v2, v3
	v_cvt_pk_f16_f32 v20, v6, v7
	s_and_b64 vcc, exec, s[8:9]
	global_store_dwordx4 v[18:19], v[20:23], off offset:1024
	s_cbranch_vccnz .LBB0_1513
	s_nop 0
	v_pk_mul_f32 v[20:21], v[8:9], v[76:77]
	v_pk_mul_f32 v[18:19], v[6:7], v[74:75]
	v_pk_mul_f32 v[22:23], v[4:5], v[72:73]
	v_pk_mul_f32 v[24:25], v[2:3], v[70:71]
	v_cvt_pk_bf16_f32 v18, v18, v19
	v_cvt_pk_bf16_f32 v19, v20, v21
	s_nop 0
	v_cvt_pk_bf16_f32 v20, v24, v25
	v_cvt_pk_bf16_f32 v21, v22, v23
	v_lshl_add_u64 v[22:23], v[190:191], 0, v[0:1]
	v_add_co_u32_e32 v22, vcc, 0x15000, v22
	s_nop 1
	v_addc_co_u32_e32 v23, vcc, 0, v23, vcc
	global_store_dwordx4 v[22:23], v[18:21], off offset:2048

; __device__ __forceinline__ float bperm(float v, int src_lane) { return __int_as_float(__builtin_amdgcn_ds_bpermute(src_lane << 2, __float_as_int(v))); }
; __global__ void __launch_bounds__(NTHR, 2) mk_fwd(MKArgs args) {
;     ...
;         const float* RSS1 = (const float*)(wsl + O_RSS1); const float* fin_g = args.in[16]; const bf16_t* X = (const bf16_t*)(wsl + O_X);
;         const int lane = tid & 63, wv = wid_s;
;         const bool byg = (G == 256);
;         for (int row = byg ? 2048 * (cid & 7) + (cid >> 3) * NWAVES + wv : cid * NWAVES + wv; row < (byg ? 2048 * (cid & 7) + 2048 : M); row += (byg ? 32 : G) * NWAVES) {
;             float s = (lane < 32) ? RSS1[(size_t)row * 32 + lane] : 0.f;
; #pragma unroll
;             for (int o = 32; o >= 1; o >>= 1) s += bperm(s, lane ^ o);
;             const float r = rsqrtf(s * (1.f / D) + EPS);
;             float* orow = args.out + (size_t)row * D; const bf16_t* xrow = X + (size_t)row * D;
; #pragma unroll
;             for (int j = 0; j < 4; ++j) { const int c = j * 512 + lane * 8; const f16x8_t hh = *(const f16x8_t*)(xrow + c); const f32x8_t ff = __builtin_convertvector(hh, f32x8_t);
.LBB0_1596:
	s_add_i32 s10, s3, s6
	s_addk_i32 s2, 0x800
	s_and_b64 s[4:5], s[0:1], exec
	s_cselect_b32 s11, s2, 0x4000
	s_cmp_ge_i32 s10, s11
	s_cbranch_scc1 .LBB0_1601
	s_lshl_b32 s2, s38, 3
	s_and_b64 s[0:1], s[0:1], exec
	s_cselect_b32 s2, 0x100, s2
	s_ashr_i32 s1, s3, 31
	s_add_u32 s0, s6, s3
	s_addc_u32 s1, 0, s1
	s_lshl_b64 s[4:5], s[0:1], 7
	s_add_u32 s3, s8, s4
	s_addc_u32 s5, s9, s5
	s_waitcnt vmcnt(0)
	v_and_b32_e32 v18, 63, v0
	v_mov_b32_e32 v11, 0
	s_add_u32 s4, s76, s3
	v_lshlrev_b32_e32 v6, 2, v18
	v_mov_b32_e32 v7, v11
	s_addc_u32 s5, s77, s5
	v_xor_b32_e32 v12, 0x80, v6
	v_xor_b32_e32 v13, 64, v6
	v_xor_b32_e32 v14, 32, v6
	v_xor_b32_e32 v15, 16, v6
	v_xor_b32_e32 v16, 8, v6
	v_xor_b32_e32 v17, 4, v6
	v_lshl_add_u64 v[6:7], s[4:5], 0, v[6:7]
	s_mov_b64 s[4:5], 0x304000
	s_ashr_i32 s3, s2, 31
	v_lshl_add_u64 v[6:7], v[6:7], 0, s[4:5]
	s_lshl_b64 s[4:5], s[2:3], 7
	s_lshl_b64 s[6:7], s[0:1], 13
	s_add_u32 s6, s74, s6
	v_lshlrev_b32_e32 v10, 5, v18
	s_addc_u32 s7, s75, s7
	v_lshl_add_u64 v[8:9], s[6:7], 0, v[10:11]
	s_mov_b64 s[6:7], 0x1000
	v_lshl_add_u64 v[8:9], v[8:9], 0, s[6:7]
	s_lshl_b64 s[6:7], s[2:3], 13
	s_and_b32 s100, s0, 15
	s_andn2_b32 s0, s0, 15
	s_lshl_b64 s[0:1], s[0:1], 12
	s_lshl_b32 s100, s100, 6
	s_add_u32 s0, s0, s100
	s_addc_u32 s1, s1, 0
	s_add_u32 s0, s8, s0
	s_addc_u32 s1, s9, s1
	s_add_u32 s0, s76, s0
	v_lshl_add_u64 v[0:1], s[72:73], 0, v[10:11]
	s_waitcnt lgkmcnt(0)
	v_or_b32_e32 v2, 0x1000, v10
	v_or_b32_e32 v4, 0x1800, v10
	v_and_b32_e32 v10, 3, v18
	v_lshlrev_b32_e32 v10, 4, v10
	v_bfe_u32 v44, v18, 2, 2
	v_lshl_or_b32 v10, v44, 11, v10
	v_bfe_u32 v44, v18, 4, 1
	v_lshl_or_b32 v10, v44, 10, v10
	v_bfe_u32 v44, v18, 5, 1
	v_lshl_or_b32 v10, v44, 13, v10
	s_addc_u32 s1, s77, s1
	v_mov_b32_e32 v3, v11
	v_mov_b32_e32 v5, v11
	v_lshl_add_u64 v[10:11], s[0:1], 0, v[10:11]
	s_mov_b64 s[0:1], 0x18104000
	v_cmp_gt_u32_e32 vcc, 32, v18
	v_lshl_add_u64 v[2:3], s[72:73], 0, v[2:3]
	v_lshl_add_u64 v[4:5], s[72:73], 0, v[4:5]
	v_lshl_add_u64 v[10:11], v[10:11], 0, s[0:1]
	s_lshl_b64 s[8:9], s[2:3], 12
	v_mov_b32_e32 v18, 0x358637bd
	s_mov_b32 s3, 0x800000
	s_branch .LBB0_1599
; __device__ __forceinline__ float bperm(float v, int src_lane) { return __int_as_float(__builtin_amdgcn_ds_bpermute(src_lane << 2, __float_as_int(v))); }
; __global__ void __launch_bounds__(NTHR, 2) mk_fwd(MKArgs args) {
;     ...
;         for (int row = byg ? 2048 * (cid & 7) + (cid >> 3) * NWAVES + wv : cid * NWAVES + wv; row < (byg ? 2048 * (cid & 7) + 2048 : M); row += (byg ? 32 : G) * NWAVES) {
;             float s = (lane < 32) ? RSS1[(size_t)row * 32 + lane] : 0.f;
; #pragma unroll
;             for (int o = 32; o >= 1; o >>= 1) s += bperm(s, lane ^ o);
;             const float r = rsqrtf(s * (1.f / D) + EPS);
;             float* orow = args.out + (size_t)row * D; const bf16_t* xrow = X + (size_t)row * D;
; #pragma unroll
;             for (int j = 0; j < 4; ++j) { const int c = j * 512 + lane * 8; const f16x8_t hh = *(const f16x8_t*)(xrow + c); const f32x8_t ff = __builtin_convertvector(hh, f32x8_t);
;                 const f32x4 g0 = *(const f32x4*)(fin_g + c), g1 = *(const f32x4*)(fin_g + c + 4);
;                 *(f32x4*)(orow + c) = (f32x4){ff[0], ff[1], ff[2], ff[3]} * r * g0; *(f32x4*)(orow + c + 4) = (f32x4){ff[4], ff[5], ff[6], ff[7]} * r * g1; }
;         }
.LBB0_1598:
	s_or_b64 exec, exec, s[0:1]
	global_load_dwordx4 v[20:23], v[10:11], off
	global_load_dwordx4 v[24:27], v[0:1], off
	global_load_dwordx4 v[28:31], v[0:1], off offset:16
	s_waitcnt vmcnt(3)
	ds_bpermute_b32 v32, v12, v19
	s_add_i32 s10, s10, s2
	v_lshl_add_u64 v[6:7], v[6:7], 0, s[4:5]
	s_cmp_lt_i32 s10, s11
	s_waitcnt lgkmcnt(0)
	v_add_f32_e32 v19, v19, v32
	ds_bpermute_b32 v32, v13, v19
	s_waitcnt lgkmcnt(0)
	v_add_f32_e32 v19, v19, v32
	ds_bpermute_b32 v32, v14, v19
	s_waitcnt lgkmcnt(0)
	v_add_f32_e32 v19, v19, v32
	ds_bpermute_b32 v32, v15, v19
	s_waitcnt lgkmcnt(0)
	v_add_f32_e32 v19, v19, v32
	ds_bpermute_b32 v32, v16, v19
	s_waitcnt lgkmcnt(0)
	v_add_f32_e32 v19, v19, v32
	ds_bpermute_b32 v32, v17, v19
	s_waitcnt lgkmcnt(0)
	v_add_f32_e32 v19, v19, v32
	v_fmamk_f32 v19, v19, 0x3a000000, v18
	v_mul_f32_e32 v32, 0x4b800000, v19
	v_cmp_gt_f32_e64 s[0:1], s3, v19
	s_waitcnt vmcnt(2)
	v_cvt_f32_f16_sdwa v39, v21 dst_sel:DWORD dst_unused:UNUSED_PAD src0_sel:WORD_1
	v_cndmask_b32_e64 v19, v19, v32, s[0:1]
	v_rsq_f32_e32 v19, v19
	v_cvt_f32_f16_sdwa v41, v20 dst_sel:DWORD dst_unused:UNUSED_PAD src0_sel:WORD_1
	v_cvt_f32_f16_e32 v40, v20
	v_cvt_f32_f16_e32 v38, v21
	v_cvt_f32_f16_sdwa v35, v23 dst_sel:DWORD dst_unused:UNUSED_PAD src0_sel:WORD_1
	v_cvt_f32_f16_sdwa v37, v22 dst_sel:DWORD dst_unused:UNUSED_PAD src0_sel:WORD_1
	v_cvt_f32_f16_e32 v36, v22
	v_cvt_f32_f16_e32 v34, v23
	v_mul_f32_e32 v32, 0x45800000, v19
	v_cndmask_b32_e64 v32, v19, v32, s[0:1]
	v_pk_mul_f32 v[20:21], v[32:33], v[40:41] op_sel_hi:[0,1]
	v_pk_mul_f32 v[22:23], v[32:33], v[38:39] op_sel_hi:[0,1]
	v_pk_mul_f32 v[36:37], v[32:33], v[36:37] op_sel_hi:[0,1]
	v_pk_mul_f32 v[34:35], v[32:33], v[34:35] op_sel_hi:[0,1]
	s_waitcnt vmcnt(1)
	v_pk_mul_f32 v[22:23], v[26:27], v[22:23]
	v_pk_mul_f32 v[20:21], v[24:25], v[20:21]
	s_waitcnt vmcnt(0)
	v_pk_mul_f32 v[26:27], v[30:31], v[34:35]
	v_pk_mul_f32 v[24:25], v[28:29], v[36:37]
	global_store_dwordx4 v[8:9], v[20:23], off offset:-4096
	global_store_dwordx4 v[8:9], v[24:27], off offset:-4080
	s_mov_b64 s[100:101], 0x4000
	v_lshl_add_u64 v[46:47], v[10:11], 0, s[100:101]
	global_load_dwordx4 v[20:23], v[46:47], off
	s_nop 0
	global_load_dwordx4 v[24:27], v[0:1], off offset:2048
	global_load_dwordx4 v[28:31], v[0:1], off offset:2064
	s_waitcnt vmcnt(2)
	v_cvt_f32_f16_sdwa v39, v21 dst_sel:DWORD dst_unused:UNUSED_PAD src0_sel:WORD_1
	v_cvt_f32_f16_sdwa v41, v20 dst_sel:DWORD dst_unused:UNUSED_PAD src0_sel:WORD_1
	v_cvt_f32_f16_e32 v40, v20
	v_cvt_f32_f16_e32 v38, v21
	v_cvt_f32_f16_sdwa v35, v23 dst_sel:DWORD dst_unused:UNUSED_PAD src0_sel:WORD_1
	v_cvt_f32_f16_sdwa v37, v22 dst_sel:DWORD dst_unused:UNUSED_PAD src0_sel:WORD_1
	v_cvt_f32_f16_e32 v36, v22
	v_cvt_f32_f16_e32 v34, v23
	v_pk_mul_f32 v[20:21], v[32:33], v[40:41] op_sel_hi:[0,1]
	v_pk_mul_f32 v[22:23], v[32:33], v[38:39] op_sel_hi:[0,1]
	v_pk_mul_f32 v[36:37], v[32:33], v[36:37] op_sel_hi:[0,1]
	v_pk_mul_f32 v[34:35], v[32:33], v[34:35] op_sel_hi:[0,1]
	s_waitcnt vmcnt(1)
	v_pk_mul_f32 v[22:23], v[26:27], v[22:23]
	v_pk_mul_f32 v[20:21], v[24:25], v[20:21]
	s_waitcnt vmcnt(0)
	v_pk_mul_f32 v[26:27], v[30:31], v[34:35]
	v_pk_mul_f32 v[24:25], v[28:29], v[36:37]
	global_store_dwordx4 v[8:9], v[20:23], off offset:-2048
	global_store_dwordx4 v[8:9], v[24:27], off offset:-2032
	s_mov_b64 s[100:101], 0x8000
	v_lshl_add_u64 v[46:47], v[10:11], 0, s[100:101]
	global_load_dwordx4 v[20:23], v[46:47], off
	s_nop 0
	global_load_dwordx4 v[24:27], v[2:3], off
	global_load_dwordx4 v[28:31], v[2:3], off offset:16
	s_waitcnt vmcnt(2)
	v_cvt_f32_f16_sdwa v39, v21 dst_sel:DWORD dst_unused:UNUSED_PAD src0_sel:WORD_1
	v_cvt_f32_f16_sdwa v41, v20 dst_sel:DWORD dst_unused:UNUSED_PAD src0_sel:WORD_1
	v_cvt_f32_f16_e32 v40, v20
	v_cvt_f32_f16_e32 v38, v21
	v_cvt_f32_f16_sdwa v35, v23 dst_sel:DWORD dst_unused:UNUSED_PAD src0_sel:WORD_1
	v_cvt_f32_f16_sdwa v37, v22 dst_sel:DWORD dst_unused:UNUSED_PAD src0_sel:WORD_1
	v_cvt_f32_f16_e32 v36, v22
	v_cvt_f32_f16_e32 v34, v23
	v_pk_mul_f32 v[20:21], v[32:33], v[40:41] op_sel_hi:[0,1]
	v_pk_mul_f32 v[22:23], v[32:33], v[38:39] op_sel_hi:[0,1]
	v_pk_mul_f32 v[36:37], v[32:33], v[36:37] op_sel_hi:[0,1]
	v_pk_mul_f32 v[34:35], v[32:33], v[34:35] op_sel_hi:[0,1]
	s_waitcnt vmcnt(1)
	v_pk_mul_f32 v[22:23], v[26:27], v[22:23]
	v_pk_mul_f32 v[20:21], v[24:25], v[20:21]
	s_waitcnt vmcnt(0)
	v_pk_mul_f32 v[26:27], v[30:31], v[34:35]
	v_pk_mul_f32 v[24:25], v[28:29], v[36:37]
	global_store_dwordx4 v[8:9], v[20:23], off
	global_store_dwordx4 v[8:9], v[24:27], off offset:16
	s_mov_b64 s[100:101], 0xc000
	v_lshl_add_u64 v[46:47], v[10:11], 0, s[100:101]
	global_load_dwordx4 v[20:23], v[46:47], off
	s_nop 0
	global_load_dwordx4 v[24:27], v[4:5], off
	global_load_dwordx4 v[28:31], v[4:5], off offset:16
	v_lshl_add_u64 v[10:11], v[10:11], 0, s[8:9]
	s_waitcnt vmcnt(2)
	v_cvt_f32_f16_sdwa v39, v21 dst_sel:DWORD dst_unused:UNUSED_PAD src0_sel:WORD_1
	v_cvt_f32_f16_sdwa v41, v20 dst_sel:DWORD dst_unused:UNUSED_PAD src0_sel:WORD_1
	v_cvt_f32_f16_e32 v40, v20
	v_cvt_f32_f16_e32 v38, v21
	v_cvt_f32_f16_sdwa v35, v23 dst_sel:DWORD dst_unused:UNUSED_PAD src0_sel:WORD_1
	v_cvt_f32_f16_sdwa v37, v22 dst_sel:DWORD dst_unused:UNUSED_PAD src0_sel:WORD_1
	v_cvt_f32_f16_e32 v36, v22
	v_cvt_f32_f16_e32 v34, v23
	v_pk_mul_f32 v[20:21], v[32:33], v[40:41] op_sel_hi:[0,1]
	v_pk_mul_f32 v[22:23], v[32:33], v[38:39] op_sel_hi:[0,1]
	v_pk_mul_f32 v[36:37], v[32:33], v[36:37] op_sel_hi:[0,1]
	v_pk_mul_f32 v[32:33], v[32:33], v[34:35] op_sel_hi:[0,1]
	s_waitcnt vmcnt(1)
	v_pk_mul_f32 v[22:23], v[26:27], v[22:23]
	v_pk_mul_f32 v[20:21], v[24:25], v[20:21]
	s_waitcnt vmcnt(0)
	v_pk_mul_f32 v[26:27], v[30:31], v[32:33]
	v_pk_mul_f32 v[24:25], v[28:29], v[36:37]
	global_store_dwordx4 v[8:9], v[20:23], off offset:2048
	global_store_dwordx4 v[8:9], v[24:27], off offset:2064
	v_lshl_add_u64 v[8:9], v[8:9], 0, s[6:7]
	s_cbranch_scc0 .LBB0_1601

; #define LAS __attribute__((address_space(3)))
; __global__ void __launch_bounds__(NTHR, 2) mk_fwd(MKArgs args) {
;     extern __shared__ __attribute__((aligned(16))) unsigned char lds_raw[];
;     LAS unsigned char* lds = (LAS unsigned char*)lds_raw;
;     volatile LAS unsigned* MISC = (volatile LAS unsigned*)(lds + MISC_OFF);
;     const int wid_s = __builtin_amdgcn_readfirstlane((int)threadIdx.x >> 6), G = gridDim.x;
	.amdhsa_kernel _Z6mk_fwd6MKArgs
		.amdhsa_group_segment_fixed_size 0
		.amdhsa_private_segment_fixed_size 0
		.amdhsa_kernarg_size 416
		.amdhsa_user_sgpr_count 2
		.amdhsa_user_sgpr_dispatch_ptr 0
		.amdhsa_user_sgpr_queue_ptr 0
		.amdhsa_user_sgpr_kernarg_segment_ptr 1
		.amdhsa_user_sgpr_dispatch_id 0
		.amdhsa_user_sgpr_kernarg_preload_length 0
		.amdhsa_user_sgpr_kernarg_preload_offset 0
		.amdhsa_user_sgpr_private_segment_size 0
		.amdhsa_uses_dynamic_stack 0
		.amdhsa_enable_private_segment 0
		.amdhsa_system_sgpr_workgroup_id_x 1
		.amdhsa_system_sgpr_workgroup_id_y 0
		.amdhsa_system_sgpr_workgroup_id_z 0
		.amdhsa_system_sgpr_workgroup_info 0
		.amdhsa_system_vgpr_workitem_id 0
		.amdhsa_next_free_vgpr 256
		.amdhsa_next_free_sgpr 102
		.amdhsa_accum_offset 256
		.amdhsa_reserve_vcc 1
		.amdhsa_float_round_mode_32 0
		.amdhsa_float_round_mode_16_64 0
		.amdhsa_float_denorm_mode_32 3
		.amdhsa_float_denorm_mode_16_64 3
		.amdhsa_dx10_clamp 1
		.amdhsa_ieee_mode 1
		.amdhsa_fp16_overflow 0
		.amdhsa_tg_split 0
		.amdhsa_exception_fp_ieee_invalid_op 0
		.amdhsa_exception_fp_denorm_src 0
		.amdhsa_exception_fp_ieee_div_zero 0
		.amdhsa_exception_fp_ieee_overflow 0
		.amdhsa_exception_fp_ieee_underflow 0
		.amdhsa_exception_fp_ieee_inexact 0
		.amdhsa_exception_int_div_zero 0
	.end_amdhsa_kernel

; __global__ void __launch_bounds__(NTHR, 2) mk_fwd(MKArgs args) {
amdhsa.kernels:
  - .agpr_count:     0
    .args:
      - .offset:         0
        .size:           160
        .value_kind:     by_value
      - .offset:         160
        .size:           4
        .value_kind:     hidden_block_count_x
      - .offset:         164
        .size:           4
        .value_kind:     hidden_block_count_y
      - .offset:         168
        .size:           4
        .value_kind:     hidden_block_count_z
      - .offset:         172
        .size:           2
        .value_kind:     hidden_group_size_x
      - .offset:         174
        .size:           2
        .value_kind:     hidden_group_size_y
      - .offset:         176
        .size:           2
        .value_kind:     hidden_group_size_z
      - .offset:         178
        .size:           2
        .value_kind:     hidden_remainder_x
      - .offset:         180
        .size:           2
        .value_kind:     hidden_remainder_y
      - .offset:         182
        .size:           2
        .value_kind:     hidden_remainder_z
      - .offset:         200
        .size:           8
        .value_kind:     hidden_global_offset_x
      - .offset:         208
        .size:           8
        .value_kind:     hidden_global_offset_y
      - .offset:         216
        .size:           8
        .value_kind:     hidden_global_offset_z
      - .offset:         224
        .size:           2
        .value_kind:     hidden_grid_dims
      - .offset:         280
        .size:           4
        .value_kind:     hidden_dynamic_lds_size
    .group_segment_fixed_size: 0
    .kernarg_segment_align: 8
    .kernarg_segment_size: 416
    .language:       OpenCL C
    .language_version:
      - 2
      - 0
    .max_flat_workgroup_size: 512
    .name:           _Z6mk_fwd6MKArgs
    .private_segment_fixed_size: 0
    .sgpr_count:     108
    .sgpr_spill_count: 74
    .symbol:         _Z6mk_fwd6MKArgs.kd
    .uniform_work_group_size: 1
    .uses_dynamic_stack: false
    .vgpr_count:     256
    .vgpr_spill_count: 0
    .wavefront_size: 64
